# v29 + GEMM K-loops: the s_waitcnt lgkmcnt(0) that follows each compute segment's opening barrier deleted (it repeats the wait issued before that barrier)
# speedup vs baseline: 1.0138x; 1.0028x over previous
.LBB0_161:
	s_ashr_i32 s23, s22, 31
	s_lshl_b64 s[8:9], s[22:23], 20
	v_readlane_b32 s20, v254, 38
	v_readlane_b32 s21, v254, 39
	s_add_u32 s8, s20, s8
	s_addc_u32 s9, s21, s9
	s_and_b64 s[20:21], s[40:41], exec
	s_cselect_b32 s13, s9, s43
	s_cselect_b32 s20, s8, s42
	s_ashr_i32 s19, s18, 31
	s_lshl_b64 s[28:29], s[18:19], 20
	v_readlane_b32 s30, v254, 22
	v_readlane_b32 s31, v254, 23
	s_add_u32 s28, s30, s28
	s_addc_u32 s29, s31, s29
	s_and_b64 s[30:31], s[40:41], exec
	s_cselect_b32 s19, s29, s45
	s_cselect_b32 s21, s28, s44
	s_add_u32 s42, s42, 0x80080
	s_addc_u32 s43, s43, 0
	s_add_u32 s23, s44, 0x100
	s_addc_u32 s25, s45, 0
	s_mov_b32 s30, -2
	v_readlane_b32 s52, v255, 20
	v_readlane_b32 s53, v255, 21
	v_readlane_b32 s72, v255, 22
	v_readlane_b32 s73, v255, 23
	s_mov_b64 s[74:75], 0x80
	s_add_u32 s31, s42, 0xfff80080
	s_addc_u32 s44, s43, -1
	s_add_i32 s47, 0, 0x10000
	s_cmp_eq_u32 s30, 28
	s_cselect_b32 s49, s13, s44
	s_cselect_b32 s48, s20, s31
	ds_read_b128 v[144:147], v1
	ds_read_b128 v[148:151], v141
	s_cselect_b32 s45, s19, s25
	s_cselect_b32 s44, s21, s23
	s_add_i32 s31, 0, 0x14000
	ds_read_b128 v[152:155], v1 offset:2048
	ds_read_b128 v[156:159], v141 offset:2048
	ds_read_b128 v[160:163], v1 offset:16384
	ds_read_b128 v[164:167], v141 offset:16384
	ds_read_b128 v[168:171], v1 offset:18432
	ds_read_b128 v[172:175], v141 offset:18432
	s_add_i32 m0, s34, 0xc000
	ds_read_b128 v[176:179], v142
	ds_read_b128 v[184:187], v142 offset:2048
	ds_read_b128 v[188:191], v143
	ds_read_b128 v[192:195], v143 offset:2048
	ds_read_b128 v[196:199], v142 offset:4096
	ds_read_b128 v[200:203], v142 offset:6144
	ds_read_b128 v[204:207], v143 offset:4096
	ds_read_b128 v[208:211], v143 offset:6144
	global_load_lds_dwordx4 v138, s[42:43]
	s_add_i32 m0, s34, 0xe000
	s_nop 0
	global_load_lds_dwordx4 v134, s[42:43]
	s_waitcnt vmcnt(8)
	s_waitcnt lgkmcnt(0)
	s_barrier
	s_setprio 1
	v_mfma_f32_16x16x32_bf16 v[128:131], v[144:147], v[176:179], 0
	v_mfma_f32_16x16x32_bf16 v[124:127], v[152:155], v[176:179], 0
	v_mfma_f32_16x16x32_bf16 v[112:115], v[144:147], v[184:187], 0
	v_mfma_f32_16x16x32_bf16 v[108:111], v[152:155], v[184:187], 0
	v_mfma_f32_16x16x32_bf16 v[96:99], v[144:147], v[196:199], 0
	v_mfma_f32_16x16x32_bf16 v[92:95], v[152:155], v[196:199], 0
	v_mfma_f32_16x16x32_bf16 v[80:83], v[144:147], v[200:203], 0
	v_mfma_f32_16x16x32_bf16 v[76:79], v[152:155], v[200:203], 0
	v_mfma_f32_16x16x32_bf16 v[128:131], v[148:151], v[188:191], v[128:131]
	v_mfma_f32_16x16x32_bf16 v[124:127], v[156:159], v[188:191], v[124:127]
	v_mfma_f32_16x16x32_bf16 v[112:115], v[148:151], v[192:195], v[112:115]
	v_mfma_f32_16x16x32_bf16 v[108:111], v[156:159], v[192:195], v[108:111]
	v_mfma_f32_16x16x32_bf16 v[96:99], v[148:151], v[204:207], v[96:99]
	v_mfma_f32_16x16x32_bf16 v[92:95], v[156:159], v[204:207], v[92:95]
	v_mfma_f32_16x16x32_bf16 v[80:83], v[148:151], v[208:211], v[80:83]
	v_mfma_f32_16x16x32_bf16 v[76:79], v[156:159], v[208:211], v[76:79]
	s_setprio 0
	s_setprio 1
	v_mfma_f32_16x16x32_bf16 v[120:123], v[160:163], v[176:179], 0
	v_mfma_f32_16x16x32_bf16 v[116:119], v[168:171], v[176:179], 0
	v_mfma_f32_16x16x32_bf16 v[104:107], v[160:163], v[184:187], 0
	v_mfma_f32_16x16x32_bf16 v[100:103], v[168:171], v[184:187], 0
	v_mfma_f32_16x16x32_bf16 v[88:91], v[160:163], v[196:199], 0
	v_mfma_f32_16x16x32_bf16 v[84:87], v[168:171], v[196:199], 0
	v_mfma_f32_16x16x32_bf16 v[72:75], v[160:163], v[200:203], 0
	v_mfma_f32_16x16x32_bf16 v[68:71], v[168:171], v[200:203], 0
	v_mfma_f32_16x16x32_bf16 v[120:123], v[164:167], v[188:191], v[120:123]
	v_mfma_f32_16x16x32_bf16 v[116:119], v[172:175], v[188:191], v[116:119]
	v_mfma_f32_16x16x32_bf16 v[104:107], v[164:167], v[192:195], v[104:107]
	v_mfma_f32_16x16x32_bf16 v[100:103], v[172:175], v[192:195], v[100:103]
	v_mfma_f32_16x16x32_bf16 v[88:91], v[164:167], v[204:207], v[88:91]
	v_mfma_f32_16x16x32_bf16 v[84:87], v[172:175], v[204:207], v[84:87]
	v_mfma_f32_16x16x32_bf16 v[72:75], v[164:167], v[208:211], v[72:75]
	v_mfma_f32_16x16x32_bf16 v[68:71], v[172:175], v[208:211], v[68:71]
	s_setprio 0
	s_barrier
	s_add_i32 s47, s47, s33
	s_mov_b32 m0, s47
	ds_read_b128 v[176:179], v142 offset:16384
	ds_read_b128 v[184:187], v142 offset:18432
	ds_read_b128 v[188:191], v143 offset:16384
	ds_read_b128 v[192:195], v143 offset:18432
	ds_read_b128 v[196:199], v142 offset:20480
	ds_read_b128 v[200:203], v142 offset:22528
	ds_read_b128 v[204:207], v143 offset:20480
	ds_read_b128 v[208:211], v143 offset:22528
	global_load_lds_dwordx4 v136, s[44:45]
	s_add_i32 m0, s47, 0x2000
	s_add_u32 s50, s44, 0x80000
	s_addc_u32 s51, s45, 0
	s_add_i32 s31, s31, s33
	global_load_lds_dwordx4 v132, s[44:45]
	s_mov_b32 m0, s31
	s_nop 0
	global_load_lds_dwordx4 v136, s[50:51]
	s_add_i32 m0, s31, 0x2000
	s_nop 0
	global_load_lds_dwordx4 v132, s[50:51]
	s_mov_b32 m0, s34
	s_nop 0
	global_load_lds_dwordx4 v138, s[48:49]
	s_mov_b32 m0, s35
	s_nop 0
	global_load_lds_dwordx4 v134, s[48:49]
	s_waitcnt vmcnt(8)
	s_waitcnt lgkmcnt(0)
	s_barrier
	s_setprio 1
	v_mfma_f32_16x16x32_bf16 v[64:67], v[144:147], v[176:179], 0
	v_mfma_f32_16x16x32_bf16 v[60:63], v[152:155], v[176:179], 0
	v_mfma_f32_16x16x32_bf16 v[48:51], v[144:147], v[184:187], 0
	v_mfma_f32_16x16x32_bf16 v[44:47], v[152:155], v[184:187], 0
	v_mfma_f32_16x16x32_bf16 v[30:33], v[144:147], v[196:199], 0
	v_mfma_f32_16x16x32_bf16 v[26:29], v[152:155], v[196:199], 0
	v_mfma_f32_16x16x32_bf16 v[14:17], v[144:147], v[200:203], 0
	v_mfma_f32_16x16x32_bf16 v[10:13], v[152:155], v[200:203], 0
	v_mfma_f32_16x16x32_bf16 v[64:67], v[148:151], v[188:191], v[64:67]
	v_mfma_f32_16x16x32_bf16 v[60:63], v[156:159], v[188:191], v[60:63]
	v_mfma_f32_16x16x32_bf16 v[48:51], v[148:151], v[192:195], v[48:51]
	v_mfma_f32_16x16x32_bf16 v[44:47], v[156:159], v[192:195], v[44:47]
	v_mfma_f32_16x16x32_bf16 v[30:33], v[148:151], v[204:207], v[30:33]
	v_mfma_f32_16x16x32_bf16 v[26:29], v[156:159], v[204:207], v[26:29]
	v_mfma_f32_16x16x32_bf16 v[14:17], v[148:151], v[208:211], v[14:17]
	v_mfma_f32_16x16x32_bf16 v[10:13], v[156:159], v[208:211], v[10:13]
	s_setprio 0
	s_setprio 1
	v_mfma_f32_16x16x32_bf16 v[56:59], v[160:163], v[176:179], 0
	v_mfma_f32_16x16x32_bf16 v[52:55], v[168:171], v[176:179], 0
	v_mfma_f32_16x16x32_bf16 v[40:43], v[160:163], v[184:187], 0
	v_mfma_f32_16x16x32_bf16 v[36:39], v[168:171], v[184:187], 0
	v_mfma_f32_16x16x32_bf16 v[22:25], v[160:163], v[196:199], 0
	v_mfma_f32_16x16x32_bf16 v[18:21], v[168:171], v[196:199], 0
	v_mfma_f32_16x16x32_bf16 v[6:9], v[160:163], v[200:203], 0
	v_mfma_f32_16x16x32_bf16 v[2:5], v[168:171], v[200:203], 0
	v_mfma_f32_16x16x32_bf16 v[56:59], v[164:167], v[188:191], v[56:59]
	v_mfma_f32_16x16x32_bf16 v[52:55], v[172:175], v[188:191], v[52:55]
	v_mfma_f32_16x16x32_bf16 v[40:43], v[164:167], v[192:195], v[40:43]
	v_mfma_f32_16x16x32_bf16 v[36:39], v[172:175], v[192:195], v[36:39]
	v_mfma_f32_16x16x32_bf16 v[22:25], v[164:167], v[204:207], v[22:25]
	v_mfma_f32_16x16x32_bf16 v[18:21], v[172:175], v[204:207], v[18:21]
	v_mfma_f32_16x16x32_bf16 v[6:9], v[164:167], v[208:211], v[6:9]
	v_mfma_f32_16x16x32_bf16 v[2:5], v[172:175], v[208:211], v[2:5]
	s_setprio 0
	s_barrier
	s_add_i32 s31, 0, 0x18000
	ds_read_b128 v[144:147], v1 offset:32768
	ds_read_b128 v[148:151], v141 offset:32768
	s_add_i32 s47, 0, 0x1c000
	ds_read_b128 v[152:155], v1 offset:34816
	ds_read_b128 v[156:159], v141 offset:34816
	ds_read_b128 v[160:163], v1 offset:49152
	ds_read_b128 v[164:167], v141 offset:49152
	ds_read_b128 v[168:171], v1 offset:51200
	ds_read_b128 v[172:175], v141 offset:51200
	s_mov_b64 s[100:101], s[48:49]
	s_add_u32 s48, s48, 0x80000
	s_addc_u32 s49, s49, 0
	s_mov_b32 m0, s54
	ds_read_b128 v[176:179], v142 offset:32768
	ds_read_b128 v[184:187], v142 offset:34816
	ds_read_b128 v[188:191], v143 offset:32768
	ds_read_b128 v[192:195], v143 offset:34816
	ds_read_b128 v[196:199], v142 offset:36864
	ds_read_b128 v[200:203], v142 offset:38912
	ds_read_b128 v[204:207], v143 offset:36864
	ds_read_b128 v[208:211], v143 offset:38912
	global_load_lds_dwordx4 v138, s[48:49]
	s_mov_b32 m0, s55
	s_nop 0
	global_load_lds_dwordx4 v134, s[48:49]
	s_waitcnt vmcnt(8)
	s_waitcnt lgkmcnt(0)
	s_barrier
	s_setprio 1
	v_mfma_f32_16x16x32_bf16 v[128:131], v[144:147], v[176:179], v[128:131]
	v_mfma_f32_16x16x32_bf16 v[124:127], v[152:155], v[176:179], v[124:127]
	v_mfma_f32_16x16x32_bf16 v[112:115], v[144:147], v[184:187], v[112:115]
	v_mfma_f32_16x16x32_bf16 v[108:111], v[152:155], v[184:187], v[108:111]
	v_mfma_f32_16x16x32_bf16 v[96:99], v[144:147], v[196:199], v[96:99]
	v_mfma_f32_16x16x32_bf16 v[92:95], v[152:155], v[196:199], v[92:95]
	v_mfma_f32_16x16x32_bf16 v[80:83], v[144:147], v[200:203], v[80:83]
	v_mfma_f32_16x16x32_bf16 v[76:79], v[152:155], v[200:203], v[76:79]
	v_mfma_f32_16x16x32_bf16 v[128:131], v[148:151], v[188:191], v[128:131]
	v_mfma_f32_16x16x32_bf16 v[124:127], v[156:159], v[188:191], v[124:127]
	v_mfma_f32_16x16x32_bf16 v[112:115], v[148:151], v[192:195], v[112:115]
	v_mfma_f32_16x16x32_bf16 v[108:111], v[156:159], v[192:195], v[108:111]
	v_mfma_f32_16x16x32_bf16 v[96:99], v[148:151], v[204:207], v[96:99]
	v_mfma_f32_16x16x32_bf16 v[92:95], v[156:159], v[204:207], v[92:95]
	v_mfma_f32_16x16x32_bf16 v[80:83], v[148:151], v[208:211], v[80:83]
	v_mfma_f32_16x16x32_bf16 v[76:79], v[156:159], v[208:211], v[76:79]
	s_setprio 0
	s_setprio 1
	v_mfma_f32_16x16x32_bf16 v[120:123], v[160:163], v[176:179], v[120:123]
	v_mfma_f32_16x16x32_bf16 v[116:119], v[168:171], v[176:179], v[116:119]
	v_mfma_f32_16x16x32_bf16 v[104:107], v[160:163], v[184:187], v[104:107]
	v_mfma_f32_16x16x32_bf16 v[100:103], v[168:171], v[184:187], v[100:103]
	v_mfma_f32_16x16x32_bf16 v[88:91], v[160:163], v[196:199], v[88:91]
	v_mfma_f32_16x16x32_bf16 v[84:87], v[168:171], v[196:199], v[84:87]
	v_mfma_f32_16x16x32_bf16 v[72:75], v[160:163], v[200:203], v[72:75]
	v_mfma_f32_16x16x32_bf16 v[68:71], v[168:171], v[200:203], v[68:71]
	v_mfma_f32_16x16x32_bf16 v[120:123], v[164:167], v[188:191], v[120:123]
	v_mfma_f32_16x16x32_bf16 v[116:119], v[172:175], v[188:191], v[116:119]
	v_mfma_f32_16x16x32_bf16 v[104:107], v[164:167], v[192:195], v[104:107]
	v_mfma_f32_16x16x32_bf16 v[100:103], v[172:175], v[192:195], v[100:103]
	v_mfma_f32_16x16x32_bf16 v[88:91], v[164:167], v[204:207], v[88:91]
	v_mfma_f32_16x16x32_bf16 v[84:87], v[172:175], v[204:207], v[84:87]
	v_mfma_f32_16x16x32_bf16 v[72:75], v[164:167], v[208:211], v[72:75]
	v_mfma_f32_16x16x32_bf16 v[68:71], v[172:175], v[208:211], v[68:71]
	s_setprio 0
	s_barrier
	s_add_i32 s31, s31, s33
	s_add_i32 m0, s31, 0xffffff80
	ds_read_b128 v[176:179], v142 offset:49152
	ds_read_b128 v[184:187], v142 offset:51200
	ds_read_b128 v[188:191], v143 offset:49152
	ds_read_b128 v[192:195], v143 offset:51200
	ds_read_b128 v[196:199], v142 offset:53248
	ds_read_b128 v[200:203], v142 offset:55296
	ds_read_b128 v[204:207], v143 offset:53248
	ds_read_b128 v[208:211], v143 offset:55296
	global_load_lds_dwordx4 v136, s[44:45] offset:128
	s_add_i32 m0, s31, 0x1f80
	s_mov_b64 s[98:99], s[44:45]
	s_add_u32 s44, s44, 0x80080
	s_addc_u32 s45, s45, 0
	s_add_i32 s31, s47, s33
	global_load_lds_dwordx4 v132, s[98:99] offset:128
	s_mov_b32 m0, s31
	s_nop 0
	global_load_lds_dwordx4 v136, s[44:45]
	s_add_i32 m0, s31, 0x2000
	s_nop 0
	global_load_lds_dwordx4 v132, s[44:45]
	s_add_i32 m0, s56, 0xffffff80
	s_nop 0
	global_load_lds_dwordx4 v138, s[100:101] offset:128
	s_add_i32 m0, s57, 0xffffff80
	s_nop 0
	global_load_lds_dwordx4 v134, s[100:101] offset:128
	s_waitcnt vmcnt(8)
	s_waitcnt lgkmcnt(0)
	s_barrier
	s_setprio 1
	v_mfma_f32_16x16x32_bf16 v[64:67], v[144:147], v[176:179], v[64:67]
	v_mfma_f32_16x16x32_bf16 v[60:63], v[152:155], v[176:179], v[60:63]
	v_mfma_f32_16x16x32_bf16 v[48:51], v[144:147], v[184:187], v[48:51]
	v_mfma_f32_16x16x32_bf16 v[44:47], v[152:155], v[184:187], v[44:47]
	v_mfma_f32_16x16x32_bf16 v[30:33], v[144:147], v[196:199], v[30:33]
	v_mfma_f32_16x16x32_bf16 v[26:29], v[152:155], v[196:199], v[26:29]
	v_mfma_f32_16x16x32_bf16 v[14:17], v[144:147], v[200:203], v[14:17]
	v_mfma_f32_16x16x32_bf16 v[10:13], v[152:155], v[200:203], v[10:13]
	v_mfma_f32_16x16x32_bf16 v[64:67], v[148:151], v[188:191], v[64:67]
	v_mfma_f32_16x16x32_bf16 v[60:63], v[156:159], v[188:191], v[60:63]
	v_mfma_f32_16x16x32_bf16 v[48:51], v[148:151], v[192:195], v[48:51]
	v_mfma_f32_16x16x32_bf16 v[44:47], v[156:159], v[192:195], v[44:47]
	v_mfma_f32_16x16x32_bf16 v[30:33], v[148:151], v[204:207], v[30:33]
	v_mfma_f32_16x16x32_bf16 v[26:29], v[156:159], v[204:207], v[26:29]
	v_mfma_f32_16x16x32_bf16 v[14:17], v[148:151], v[208:211], v[14:17]
	v_mfma_f32_16x16x32_bf16 v[10:13], v[156:159], v[208:211], v[10:13]
	s_setprio 0
	s_setprio 1
	v_mfma_f32_16x16x32_bf16 v[56:59], v[160:163], v[176:179], v[56:59]
	v_mfma_f32_16x16x32_bf16 v[52:55], v[168:171], v[176:179], v[52:55]
	v_mfma_f32_16x16x32_bf16 v[40:43], v[160:163], v[184:187], v[40:43]
	v_mfma_f32_16x16x32_bf16 v[36:39], v[168:171], v[184:187], v[36:39]
	v_mfma_f32_16x16x32_bf16 v[22:25], v[160:163], v[196:199], v[22:25]
	v_mfma_f32_16x16x32_bf16 v[18:21], v[168:171], v[196:199], v[18:21]
	v_mfma_f32_16x16x32_bf16 v[6:9], v[160:163], v[200:203], v[6:9]
	v_mfma_f32_16x16x32_bf16 v[2:5], v[168:171], v[200:203], v[2:5]
	v_mfma_f32_16x16x32_bf16 v[56:59], v[164:167], v[188:191], v[56:59]
	v_mfma_f32_16x16x32_bf16 v[52:55], v[172:175], v[188:191], v[52:55]
	v_mfma_f32_16x16x32_bf16 v[40:43], v[164:167], v[192:195], v[40:43]
	v_mfma_f32_16x16x32_bf16 v[36:39], v[172:175], v[192:195], v[36:39]
	v_mfma_f32_16x16x32_bf16 v[22:25], v[164:167], v[204:207], v[22:25]
	v_mfma_f32_16x16x32_bf16 v[18:21], v[172:175], v[204:207], v[18:21]
	v_mfma_f32_16x16x32_bf16 v[6:9], v[164:167], v[208:211], v[6:9]
	v_mfma_f32_16x16x32_bf16 v[2:5], v[172:175], v[208:211], v[2:5]
	s_setprio 0
	s_barrier
	s_add_i32 s30, s30, 2
	s_add_u32 s42, s42, 0x100
	s_addc_u32 s43, s43, 0
	s_add_u32 s23, s23, 0x100
	s_addc_u32 s25, s25, 0
	s_cmp_gt_u32 s30, 29
	s_cbranch_scc1 .Lpeel_done_P1
.LBB0_162:
	s_add_u32 s31, s42, 0xfff80080
	s_addc_u32 s44, s43, -1
	s_add_i32 s47, 0, 0x10000
	s_cmp_eq_u32 s30, 28
	s_cselect_b32 s49, s13, s44
	s_cselect_b32 s48, s20, s31
	ds_read_b128 v[144:147], v1
	ds_read_b128 v[148:151], v141
	s_cselect_b32 s45, s19, s25
	s_cselect_b32 s44, s21, s23
	s_add_i32 s31, 0, 0x14000
	ds_read_b128 v[152:155], v1 offset:2048
	ds_read_b128 v[156:159], v141 offset:2048
	ds_read_b128 v[160:163], v1 offset:16384
	ds_read_b128 v[164:167], v141 offset:16384
	ds_read_b128 v[168:171], v1 offset:18432
	ds_read_b128 v[172:175], v141 offset:18432
	s_add_i32 m0, s34, 0xc000
	ds_read_b128 v[176:179], v142
	ds_read_b128 v[184:187], v142 offset:2048
	ds_read_b128 v[188:191], v143
	ds_read_b128 v[192:195], v143 offset:2048
	ds_read_b128 v[196:199], v142 offset:4096
	ds_read_b128 v[200:203], v142 offset:6144
	ds_read_b128 v[204:207], v143 offset:4096
	ds_read_b128 v[208:211], v143 offset:6144
	global_load_lds_dwordx4 v138, s[42:43]
	s_add_i32 m0, s34, 0xe000
	s_nop 0
	global_load_lds_dwordx4 v134, s[42:43]
	s_waitcnt vmcnt(8)
	s_waitcnt lgkmcnt(0)
	s_barrier
	s_setprio 1
	v_mfma_f32_16x16x32_bf16 v[128:131], v[144:147], v[176:179], v[128:131]
	v_mfma_f32_16x16x32_bf16 v[124:127], v[152:155], v[176:179], v[124:127]
	v_mfma_f32_16x16x32_bf16 v[112:115], v[144:147], v[184:187], v[112:115]
	v_mfma_f32_16x16x32_bf16 v[108:111], v[152:155], v[184:187], v[108:111]
	v_mfma_f32_16x16x32_bf16 v[96:99], v[144:147], v[196:199], v[96:99]
	v_mfma_f32_16x16x32_bf16 v[92:95], v[152:155], v[196:199], v[92:95]
	v_mfma_f32_16x16x32_bf16 v[80:83], v[144:147], v[200:203], v[80:83]
	v_mfma_f32_16x16x32_bf16 v[76:79], v[152:155], v[200:203], v[76:79]
	v_mfma_f32_16x16x32_bf16 v[128:131], v[148:151], v[188:191], v[128:131]
	v_mfma_f32_16x16x32_bf16 v[124:127], v[156:159], v[188:191], v[124:127]
	v_mfma_f32_16x16x32_bf16 v[112:115], v[148:151], v[192:195], v[112:115]
	v_mfma_f32_16x16x32_bf16 v[108:111], v[156:159], v[192:195], v[108:111]
	v_mfma_f32_16x16x32_bf16 v[96:99], v[148:151], v[204:207], v[96:99]
	v_mfma_f32_16x16x32_bf16 v[92:95], v[156:159], v[204:207], v[92:95]
	v_mfma_f32_16x16x32_bf16 v[80:83], v[148:151], v[208:211], v[80:83]
	v_mfma_f32_16x16x32_bf16 v[76:79], v[156:159], v[208:211], v[76:79]
	s_setprio 0
	s_setprio 1
	v_mfma_f32_16x16x32_bf16 v[120:123], v[160:163], v[176:179], v[120:123]
	v_mfma_f32_16x16x32_bf16 v[116:119], v[168:171], v[176:179], v[116:119]
	v_mfma_f32_16x16x32_bf16 v[104:107], v[160:163], v[184:187], v[104:107]
	v_mfma_f32_16x16x32_bf16 v[100:103], v[168:171], v[184:187], v[100:103]
	v_mfma_f32_16x16x32_bf16 v[88:91], v[160:163], v[196:199], v[88:91]
	v_mfma_f32_16x16x32_bf16 v[84:87], v[168:171], v[196:199], v[84:87]
	v_mfma_f32_16x16x32_bf16 v[72:75], v[160:163], v[200:203], v[72:75]
	v_mfma_f32_16x16x32_bf16 v[68:71], v[168:171], v[200:203], v[68:71]
	v_mfma_f32_16x16x32_bf16 v[120:123], v[164:167], v[188:191], v[120:123]
	v_mfma_f32_16x16x32_bf16 v[116:119], v[172:175], v[188:191], v[116:119]
	v_mfma_f32_16x16x32_bf16 v[104:107], v[164:167], v[192:195], v[104:107]
	v_mfma_f32_16x16x32_bf16 v[100:103], v[172:175], v[192:195], v[100:103]
	v_mfma_f32_16x16x32_bf16 v[88:91], v[164:167], v[204:207], v[88:91]
	v_mfma_f32_16x16x32_bf16 v[84:87], v[172:175], v[204:207], v[84:87]
	v_mfma_f32_16x16x32_bf16 v[72:75], v[164:167], v[208:211], v[72:75]
	v_mfma_f32_16x16x32_bf16 v[68:71], v[172:175], v[208:211], v[68:71]
	s_setprio 0
	s_barrier
	s_add_i32 s47, s47, s33
	s_mov_b32 m0, s47
	ds_read_b128 v[176:179], v142 offset:16384
	ds_read_b128 v[184:187], v142 offset:18432
	ds_read_b128 v[188:191], v143 offset:16384
	ds_read_b128 v[192:195], v143 offset:18432
	ds_read_b128 v[196:199], v142 offset:20480
	ds_read_b128 v[200:203], v142 offset:22528
	ds_read_b128 v[204:207], v143 offset:20480
	ds_read_b128 v[208:211], v143 offset:22528
	global_load_lds_dwordx4 v136, s[44:45]
	s_add_i32 m0, s47, 0x2000
	s_add_u32 s50, s44, 0x80000
	s_addc_u32 s51, s45, 0
	s_add_i32 s31, s31, s33
	global_load_lds_dwordx4 v132, s[44:45]
	s_mov_b32 m0, s31
	s_nop 0
	global_load_lds_dwordx4 v136, s[50:51]
	s_add_i32 m0, s31, 0x2000
	s_nop 0
	global_load_lds_dwordx4 v132, s[50:51]
	s_mov_b32 m0, s34
	s_nop 0
	global_load_lds_dwordx4 v138, s[48:49]
	s_mov_b32 m0, s35
	s_nop 0
	global_load_lds_dwordx4 v134, s[48:49]
	s_waitcnt vmcnt(8)
	s_waitcnt lgkmcnt(0)
	s_barrier
	s_setprio 1
	v_mfma_f32_16x16x32_bf16 v[64:67], v[144:147], v[176:179], v[64:67]
	v_mfma_f32_16x16x32_bf16 v[60:63], v[152:155], v[176:179], v[60:63]
	v_mfma_f32_16x16x32_bf16 v[48:51], v[144:147], v[184:187], v[48:51]
	v_mfma_f32_16x16x32_bf16 v[44:47], v[152:155], v[184:187], v[44:47]
	v_mfma_f32_16x16x32_bf16 v[30:33], v[144:147], v[196:199], v[30:33]
	v_mfma_f32_16x16x32_bf16 v[26:29], v[152:155], v[196:199], v[26:29]
	v_mfma_f32_16x16x32_bf16 v[14:17], v[144:147], v[200:203], v[14:17]
	v_mfma_f32_16x16x32_bf16 v[10:13], v[152:155], v[200:203], v[10:13]
	v_mfma_f32_16x16x32_bf16 v[64:67], v[148:151], v[188:191], v[64:67]
	v_mfma_f32_16x16x32_bf16 v[60:63], v[156:159], v[188:191], v[60:63]
	v_mfma_f32_16x16x32_bf16 v[48:51], v[148:151], v[192:195], v[48:51]
	v_mfma_f32_16x16x32_bf16 v[44:47], v[156:159], v[192:195], v[44:47]
	v_mfma_f32_16x16x32_bf16 v[30:33], v[148:151], v[204:207], v[30:33]
	v_mfma_f32_16x16x32_bf16 v[26:29], v[156:159], v[204:207], v[26:29]
	v_mfma_f32_16x16x32_bf16 v[14:17], v[148:151], v[208:211], v[14:17]
	v_mfma_f32_16x16x32_bf16 v[10:13], v[156:159], v[208:211], v[10:13]
	s_setprio 0
	s_setprio 1
	v_mfma_f32_16x16x32_bf16 v[56:59], v[160:163], v[176:179], v[56:59]
	v_mfma_f32_16x16x32_bf16 v[52:55], v[168:171], v[176:179], v[52:55]
	v_mfma_f32_16x16x32_bf16 v[40:43], v[160:163], v[184:187], v[40:43]
	v_mfma_f32_16x16x32_bf16 v[36:39], v[168:171], v[184:187], v[36:39]
	v_mfma_f32_16x16x32_bf16 v[22:25], v[160:163], v[196:199], v[22:25]
	v_mfma_f32_16x16x32_bf16 v[18:21], v[168:171], v[196:199], v[18:21]
	v_mfma_f32_16x16x32_bf16 v[6:9], v[160:163], v[200:203], v[6:9]
	v_mfma_f32_16x16x32_bf16 v[2:5], v[168:171], v[200:203], v[2:5]
	v_mfma_f32_16x16x32_bf16 v[56:59], v[164:167], v[188:191], v[56:59]
	v_mfma_f32_16x16x32_bf16 v[52:55], v[172:175], v[188:191], v[52:55]
	v_mfma_f32_16x16x32_bf16 v[40:43], v[164:167], v[192:195], v[40:43]
	v_mfma_f32_16x16x32_bf16 v[36:39], v[172:175], v[192:195], v[36:39]
	v_mfma_f32_16x16x32_bf16 v[22:25], v[164:167], v[204:207], v[22:25]
	v_mfma_f32_16x16x32_bf16 v[18:21], v[172:175], v[204:207], v[18:21]
	v_mfma_f32_16x16x32_bf16 v[6:9], v[164:167], v[208:211], v[6:9]
	v_mfma_f32_16x16x32_bf16 v[2:5], v[172:175], v[208:211], v[2:5]
	s_setprio 0
	s_barrier
	s_add_i32 s31, 0, 0x18000
	ds_read_b128 v[144:147], v1 offset:32768
	ds_read_b128 v[148:151], v141 offset:32768
	s_add_i32 s47, 0, 0x1c000
	ds_read_b128 v[152:155], v1 offset:34816
	ds_read_b128 v[156:159], v141 offset:34816
	ds_read_b128 v[160:163], v1 offset:49152
	ds_read_b128 v[164:167], v141 offset:49152
	ds_read_b128 v[168:171], v1 offset:51200
	ds_read_b128 v[172:175], v141 offset:51200
	s_mov_b64 s[100:101], s[48:49]
	s_add_u32 s48, s48, 0x80000
	s_addc_u32 s49, s49, 0
	s_mov_b32 m0, s54
	ds_read_b128 v[176:179], v142 offset:32768
	ds_read_b128 v[184:187], v142 offset:34816
	ds_read_b128 v[188:191], v143 offset:32768
	ds_read_b128 v[192:195], v143 offset:34816
	ds_read_b128 v[196:199], v142 offset:36864
	ds_read_b128 v[200:203], v142 offset:38912
	ds_read_b128 v[204:207], v143 offset:36864
	ds_read_b128 v[208:211], v143 offset:38912
	global_load_lds_dwordx4 v138, s[48:49]
	s_mov_b32 m0, s55
	s_nop 0
	global_load_lds_dwordx4 v134, s[48:49]
	s_waitcnt vmcnt(8)
	s_waitcnt lgkmcnt(0)
	s_barrier
	s_setprio 1
	v_mfma_f32_16x16x32_bf16 v[128:131], v[144:147], v[176:179], v[128:131]
	v_mfma_f32_16x16x32_bf16 v[124:127], v[152:155], v[176:179], v[124:127]
	v_mfma_f32_16x16x32_bf16 v[112:115], v[144:147], v[184:187], v[112:115]
	v_mfma_f32_16x16x32_bf16 v[108:111], v[152:155], v[184:187], v[108:111]
	v_mfma_f32_16x16x32_bf16 v[96:99], v[144:147], v[196:199], v[96:99]
	v_mfma_f32_16x16x32_bf16 v[92:95], v[152:155], v[196:199], v[92:95]
	v_mfma_f32_16x16x32_bf16 v[80:83], v[144:147], v[200:203], v[80:83]
	v_mfma_f32_16x16x32_bf16 v[76:79], v[152:155], v[200:203], v[76:79]
	v_mfma_f32_16x16x32_bf16 v[128:131], v[148:151], v[188:191], v[128:131]
	v_mfma_f32_16x16x32_bf16 v[124:127], v[156:159], v[188:191], v[124:127]
	v_mfma_f32_16x16x32_bf16 v[112:115], v[148:151], v[192:195], v[112:115]
	v_mfma_f32_16x16x32_bf16 v[108:111], v[156:159], v[192:195], v[108:111]
	v_mfma_f32_16x16x32_bf16 v[96:99], v[148:151], v[204:207], v[96:99]
	v_mfma_f32_16x16x32_bf16 v[92:95], v[156:159], v[204:207], v[92:95]
	v_mfma_f32_16x16x32_bf16 v[80:83], v[148:151], v[208:211], v[80:83]
	v_mfma_f32_16x16x32_bf16 v[76:79], v[156:159], v[208:211], v[76:79]
	s_setprio 0
	s_setprio 1
	v_mfma_f32_16x16x32_bf16 v[120:123], v[160:163], v[176:179], v[120:123]
	v_mfma_f32_16x16x32_bf16 v[116:119], v[168:171], v[176:179], v[116:119]
	v_mfma_f32_16x16x32_bf16 v[104:107], v[160:163], v[184:187], v[104:107]
	v_mfma_f32_16x16x32_bf16 v[100:103], v[168:171], v[184:187], v[100:103]
	v_mfma_f32_16x16x32_bf16 v[88:91], v[160:163], v[196:199], v[88:91]
	v_mfma_f32_16x16x32_bf16 v[84:87], v[168:171], v[196:199], v[84:87]
	v_mfma_f32_16x16x32_bf16 v[72:75], v[160:163], v[200:203], v[72:75]
	v_mfma_f32_16x16x32_bf16 v[68:71], v[168:171], v[200:203], v[68:71]
	v_mfma_f32_16x16x32_bf16 v[120:123], v[164:167], v[188:191], v[120:123]
	v_mfma_f32_16x16x32_bf16 v[116:119], v[172:175], v[188:191], v[116:119]
	v_mfma_f32_16x16x32_bf16 v[104:107], v[164:167], v[192:195], v[104:107]
	v_mfma_f32_16x16x32_bf16 v[100:103], v[172:175], v[192:195], v[100:103]
	v_mfma_f32_16x16x32_bf16 v[88:91], v[164:167], v[204:207], v[88:91]
	v_mfma_f32_16x16x32_bf16 v[84:87], v[172:175], v[204:207], v[84:87]
	v_mfma_f32_16x16x32_bf16 v[72:75], v[164:167], v[208:211], v[72:75]
	v_mfma_f32_16x16x32_bf16 v[68:71], v[172:175], v[208:211], v[68:71]
	s_setprio 0
	s_barrier
	s_add_i32 s31, s31, s33
	s_add_i32 m0, s31, 0xffffff80
	ds_read_b128 v[176:179], v142 offset:49152
	ds_read_b128 v[184:187], v142 offset:51200
	ds_read_b128 v[188:191], v143 offset:49152
	ds_read_b128 v[192:195], v143 offset:51200
	ds_read_b128 v[196:199], v142 offset:53248
	ds_read_b128 v[200:203], v142 offset:55296
	ds_read_b128 v[204:207], v143 offset:53248
	ds_read_b128 v[208:211], v143 offset:55296
	global_load_lds_dwordx4 v136, s[44:45] offset:128
	s_add_i32 m0, s31, 0x1f80
	s_mov_b64 s[98:99], s[44:45]
	s_add_u32 s44, s44, 0x80080
	s_addc_u32 s45, s45, 0
	s_add_i32 s31, s47, s33
	global_load_lds_dwordx4 v132, s[98:99] offset:128
	s_mov_b32 m0, s31
	s_nop 0
	global_load_lds_dwordx4 v136, s[44:45]
	s_add_i32 m0, s31, 0x2000
	s_nop 0
	global_load_lds_dwordx4 v132, s[44:45]
	s_add_i32 m0, s56, 0xffffff80
	s_nop 0
	global_load_lds_dwordx4 v138, s[100:101] offset:128
	s_add_i32 m0, s57, 0xffffff80
	s_nop 0
	global_load_lds_dwordx4 v134, s[100:101] offset:128
	s_waitcnt vmcnt(8)
	s_waitcnt lgkmcnt(0)
	s_barrier
	s_setprio 1
	v_mfma_f32_16x16x32_bf16 v[64:67], v[144:147], v[176:179], v[64:67]
	v_mfma_f32_16x16x32_bf16 v[60:63], v[152:155], v[176:179], v[60:63]
	v_mfma_f32_16x16x32_bf16 v[48:51], v[144:147], v[184:187], v[48:51]
	v_mfma_f32_16x16x32_bf16 v[44:47], v[152:155], v[184:187], v[44:47]
	v_mfma_f32_16x16x32_bf16 v[30:33], v[144:147], v[196:199], v[30:33]
	v_mfma_f32_16x16x32_bf16 v[26:29], v[152:155], v[196:199], v[26:29]
	v_mfma_f32_16x16x32_bf16 v[14:17], v[144:147], v[200:203], v[14:17]
	v_mfma_f32_16x16x32_bf16 v[10:13], v[152:155], v[200:203], v[10:13]
	v_mfma_f32_16x16x32_bf16 v[64:67], v[148:151], v[188:191], v[64:67]
	v_mfma_f32_16x16x32_bf16 v[60:63], v[156:159], v[188:191], v[60:63]
	v_mfma_f32_16x16x32_bf16 v[48:51], v[148:151], v[192:195], v[48:51]
	v_mfma_f32_16x16x32_bf16 v[44:47], v[156:159], v[192:195], v[44:47]
	v_mfma_f32_16x16x32_bf16 v[30:33], v[148:151], v[204:207], v[30:33]
	v_mfma_f32_16x16x32_bf16 v[26:29], v[156:159], v[204:207], v[26:29]
	v_mfma_f32_16x16x32_bf16 v[14:17], v[148:151], v[208:211], v[14:17]
	v_mfma_f32_16x16x32_bf16 v[10:13], v[156:159], v[208:211], v[10:13]
	s_setprio 0
	s_setprio 1
	v_mfma_f32_16x16x32_bf16 v[56:59], v[160:163], v[176:179], v[56:59]
	v_mfma_f32_16x16x32_bf16 v[52:55], v[168:171], v[176:179], v[52:55]
	v_mfma_f32_16x16x32_bf16 v[40:43], v[160:163], v[184:187], v[40:43]
	v_mfma_f32_16x16x32_bf16 v[36:39], v[168:171], v[184:187], v[36:39]
	v_mfma_f32_16x16x32_bf16 v[22:25], v[160:163], v[196:199], v[22:25]
	v_mfma_f32_16x16x32_bf16 v[18:21], v[168:171], v[196:199], v[18:21]
	v_mfma_f32_16x16x32_bf16 v[6:9], v[160:163], v[200:203], v[6:9]
	v_mfma_f32_16x16x32_bf16 v[2:5], v[168:171], v[200:203], v[2:5]
	v_mfma_f32_16x16x32_bf16 v[56:59], v[164:167], v[188:191], v[56:59]
	v_mfma_f32_16x16x32_bf16 v[52:55], v[172:175], v[188:191], v[52:55]
	v_mfma_f32_16x16x32_bf16 v[40:43], v[164:167], v[192:195], v[40:43]
	v_mfma_f32_16x16x32_bf16 v[36:39], v[172:175], v[192:195], v[36:39]
	v_mfma_f32_16x16x32_bf16 v[22:25], v[164:167], v[204:207], v[22:25]
	v_mfma_f32_16x16x32_bf16 v[18:21], v[172:175], v[204:207], v[18:21]
	v_mfma_f32_16x16x32_bf16 v[6:9], v[164:167], v[208:211], v[6:9]
	v_mfma_f32_16x16x32_bf16 v[2:5], v[172:175], v[208:211], v[2:5]
	s_setprio 0
	s_barrier
	s_add_i32 s30, s30, 2
	s_add_u32 s42, s42, 0x100
	s_addc_u32 s43, s43, 0
	s_add_u32 s23, s23, 0x100
	s_addc_u32 s25, s25, 0
	s_cmp_gt_u32 s30, 29
	s_cbranch_scc0 .LBB0_162

.LBB0_907:
	s_and_b32 s9, 1, s12
	s_cmp_gt_i32 s12, 1
	s_cselect_b32 s24, 10, 12
	s_cmp_eq_u32 s9, 1
	s_cselect_b64 s[18:19], -1, 0
	s_and_b64 s[20:21], s[18:19], exec
	s_cselect_b32 s9, s24, 32
	s_add_i32 s20, s9, -2
	s_add_u32 s22, s22, 0x80080
	s_addc_u32 s23, s23, 0
	s_add_u32 s21, s28, 0x100
	s_addc_u32 s24, s29, 0
	s_mov_b32 s25, 0
	s_waitcnt vmcnt(0)
	v_readlane_b32 s43, v255, 20
	v_readlane_b32 s45, v255, 21
	v_readlane_b32 s66, v255, 22
	v_readlane_b32 s67, v255, 23
	s_mov_b64 s[68:69], 0x80
	s_add_i32 s30, s25, 2
	s_add_u32 s28, s22, 0xfff80080
	s_addc_u32 s29, s23, -1
	s_add_i32 s31, 0, 0x10000
	s_cmp_eq_u32 s20, s25
	s_cselect_b32 s41, s47, s29
	s_cselect_b32 s40, s46, s28
	s_cselect_b32 s29, s49, s24
	s_cselect_b32 s28, s48, s21
	s_add_i32 s25, 0, 0x14000
	ds_read_b128 v[132:135], v1
	ds_read_b128 v[136:139], v204
	ds_read_b128 v[140:143], v1 offset:2048
	ds_read_b128 v[144:147], v204 offset:2048
	ds_read_b128 v[148:151], v1 offset:16384
	ds_read_b128 v[152:155], v204 offset:16384
	ds_read_b128 v[156:159], v1 offset:18432
	ds_read_b128 v[160:163], v204 offset:18432
	s_add_i32 m0, s50, 0xc000
	ds_read_b128 v[164:167], v205
	ds_read_b128 v[168:171], v205 offset:2048
	ds_read_b128 v[172:175], v206
	ds_read_b128 v[176:179], v206 offset:2048
	ds_read_b128 v[190:193], v205 offset:4096
	ds_read_b128 v[194:197], v205 offset:6144
	ds_read_b128 v[198:201], v206 offset:4096
	ds_read_b128 v[232:235], v206 offset:6144
	global_load_lds_dwordx4 v188, s[22:23]
	s_add_i32 m0, s50, 0xe000
	s_nop 0
	global_load_lds_dwordx4 v186, s[22:23]
	s_waitcnt vmcnt(8)
	s_waitcnt lgkmcnt(0)
	s_barrier
	s_setprio 1
	v_mfma_f32_16x16x32_bf16 v[68:71], v[132:135], v[164:167], 0
	v_mfma_f32_16x16x32_bf16 v[72:75], v[140:143], v[164:167], 0
	v_mfma_f32_16x16x32_bf16 v[84:87], v[132:135], v[168:171], 0
	v_mfma_f32_16x16x32_bf16 v[88:91], v[140:143], v[168:171], 0
	v_mfma_f32_16x16x32_bf16 v[100:103], v[132:135], v[190:193], 0
	v_mfma_f32_16x16x32_bf16 v[104:107], v[140:143], v[190:193], 0
	v_mfma_f32_16x16x32_bf16 v[116:119], v[132:135], v[194:197], 0
	v_mfma_f32_16x16x32_bf16 v[120:123], v[140:143], v[194:197], 0
	v_mfma_f32_16x16x32_bf16 v[68:71], v[136:139], v[172:175], v[68:71]
	v_mfma_f32_16x16x32_bf16 v[72:75], v[144:147], v[172:175], v[72:75]
	v_mfma_f32_16x16x32_bf16 v[84:87], v[136:139], v[176:179], v[84:87]
	v_mfma_f32_16x16x32_bf16 v[88:91], v[144:147], v[176:179], v[88:91]
	v_mfma_f32_16x16x32_bf16 v[100:103], v[136:139], v[198:201], v[100:103]
	v_mfma_f32_16x16x32_bf16 v[104:107], v[144:147], v[198:201], v[104:107]
	v_mfma_f32_16x16x32_bf16 v[116:119], v[136:139], v[232:235], v[116:119]
	v_mfma_f32_16x16x32_bf16 v[120:123], v[144:147], v[232:235], v[120:123]
	s_setprio 0
	s_setprio 1
	v_mfma_f32_16x16x32_bf16 v[76:79], v[148:151], v[164:167], 0
	v_mfma_f32_16x16x32_bf16 v[80:83], v[156:159], v[164:167], 0
	v_mfma_f32_16x16x32_bf16 v[92:95], v[148:151], v[168:171], 0
	v_mfma_f32_16x16x32_bf16 v[96:99], v[156:159], v[168:171], 0
	v_mfma_f32_16x16x32_bf16 v[108:111], v[148:151], v[190:193], 0
	v_mfma_f32_16x16x32_bf16 v[112:115], v[156:159], v[190:193], 0
	v_mfma_f32_16x16x32_bf16 v[124:127], v[148:151], v[194:197], 0
	v_mfma_f32_16x16x32_bf16 v[128:131], v[156:159], v[194:197], 0
	v_mfma_f32_16x16x32_bf16 v[76:79], v[152:155], v[172:175], v[76:79]
	v_mfma_f32_16x16x32_bf16 v[80:83], v[160:163], v[172:175], v[80:83]
	v_mfma_f32_16x16x32_bf16 v[92:95], v[152:155], v[176:179], v[92:95]
	v_mfma_f32_16x16x32_bf16 v[96:99], v[160:163], v[176:179], v[96:99]
	v_mfma_f32_16x16x32_bf16 v[108:111], v[152:155], v[198:201], v[108:111]
	v_mfma_f32_16x16x32_bf16 v[112:115], v[160:163], v[198:201], v[112:115]
	v_mfma_f32_16x16x32_bf16 v[124:127], v[152:155], v[232:235], v[124:127]
	v_mfma_f32_16x16x32_bf16 v[128:131], v[160:163], v[232:235], v[128:131]
	s_setprio 0
	s_barrier
	s_add_i32 s31, s31, s33
	s_mov_b32 m0, s31
	ds_read_b128 v[164:167], v205 offset:16384
	ds_read_b128 v[168:171], v205 offset:18432
	ds_read_b128 v[172:175], v206 offset:16384
	ds_read_b128 v[176:179], v206 offset:18432
	ds_read_b128 v[190:193], v205 offset:20480
	ds_read_b128 v[194:197], v205 offset:22528
	ds_read_b128 v[198:201], v206 offset:20480
	ds_read_b128 v[232:235], v206 offset:22528
	global_load_lds_dwordx4 v34, s[28:29]
	s_add_i32 m0, s31, 0x2000
	s_add_u32 s34, s28, 0x80000
	s_addc_u32 s35, s29, 0
	s_add_i32 s25, s25, s33
	global_load_lds_dwordx4 v184, s[28:29]
	s_mov_b32 m0, s25
	s_nop 0
	global_load_lds_dwordx4 v34, s[34:35]
	s_add_i32 m0, s25, 0x2000
	s_nop 0
	global_load_lds_dwordx4 v184, s[34:35]
	s_mov_b32 m0, s50
	s_nop 0
	global_load_lds_dwordx4 v188, s[40:41]
	s_mov_b32 m0, s51
	s_nop 0
	global_load_lds_dwordx4 v186, s[40:41]
	s_waitcnt vmcnt(8)
	s_waitcnt lgkmcnt(0)
	s_barrier
	s_setprio 1
	v_mfma_f32_16x16x32_bf16 v[2:5], v[132:135], v[164:167], 0
	v_mfma_f32_16x16x32_bf16 v[6:9], v[140:143], v[164:167], 0
	v_mfma_f32_16x16x32_bf16 v[18:21], v[132:135], v[168:171], 0
	v_mfma_f32_16x16x32_bf16 v[22:25], v[140:143], v[168:171], 0
	v_mfma_f32_16x16x32_bf16 v[36:39], v[132:135], v[190:193], 0
	v_mfma_f32_16x16x32_bf16 v[40:43], v[140:143], v[190:193], 0
	v_mfma_f32_16x16x32_bf16 v[52:55], v[132:135], v[194:197], 0
	v_mfma_f32_16x16x32_bf16 v[56:59], v[140:143], v[194:197], 0
	v_mfma_f32_16x16x32_bf16 v[2:5], v[136:139], v[172:175], v[2:5]
	v_mfma_f32_16x16x32_bf16 v[6:9], v[144:147], v[172:175], v[6:9]
	v_mfma_f32_16x16x32_bf16 v[18:21], v[136:139], v[176:179], v[18:21]
	v_mfma_f32_16x16x32_bf16 v[22:25], v[144:147], v[176:179], v[22:25]
	v_mfma_f32_16x16x32_bf16 v[36:39], v[136:139], v[198:201], v[36:39]
	v_mfma_f32_16x16x32_bf16 v[40:43], v[144:147], v[198:201], v[40:43]
	v_mfma_f32_16x16x32_bf16 v[52:55], v[136:139], v[232:235], v[52:55]
	v_mfma_f32_16x16x32_bf16 v[56:59], v[144:147], v[232:235], v[56:59]
	s_setprio 0
	s_setprio 1
	v_mfma_f32_16x16x32_bf16 v[10:13], v[148:151], v[164:167], 0
	v_mfma_f32_16x16x32_bf16 v[14:17], v[156:159], v[164:167], 0
	v_mfma_f32_16x16x32_bf16 v[26:29], v[148:151], v[168:171], 0
	v_mfma_f32_16x16x32_bf16 v[30:33], v[156:159], v[168:171], 0
	v_mfma_f32_16x16x32_bf16 v[44:47], v[148:151], v[190:193], 0
	v_mfma_f32_16x16x32_bf16 v[48:51], v[156:159], v[190:193], 0
	v_mfma_f32_16x16x32_bf16 v[60:63], v[148:151], v[194:197], 0
	v_mfma_f32_16x16x32_bf16 v[64:67], v[156:159], v[194:197], 0
	v_mfma_f32_16x16x32_bf16 v[10:13], v[152:155], v[172:175], v[10:13]
	v_mfma_f32_16x16x32_bf16 v[14:17], v[160:163], v[172:175], v[14:17]
	v_mfma_f32_16x16x32_bf16 v[26:29], v[152:155], v[176:179], v[26:29]
	v_mfma_f32_16x16x32_bf16 v[30:33], v[160:163], v[176:179], v[30:33]
	v_mfma_f32_16x16x32_bf16 v[44:47], v[152:155], v[198:201], v[44:47]
	v_mfma_f32_16x16x32_bf16 v[48:51], v[160:163], v[198:201], v[48:51]
	v_mfma_f32_16x16x32_bf16 v[60:63], v[152:155], v[232:235], v[60:63]
	v_mfma_f32_16x16x32_bf16 v[64:67], v[160:163], v[232:235], v[64:67]
	s_setprio 0
	s_barrier
	s_add_i32 s25, 0, 0x18000
	s_add_i32 s31, 0, 0x1c000
	ds_read_b128 v[132:135], v1 offset:32768
	ds_read_b128 v[136:139], v204 offset:32768
	ds_read_b128 v[140:143], v1 offset:34816
	ds_read_b128 v[144:147], v204 offset:34816
	ds_read_b128 v[148:151], v1 offset:49152
	ds_read_b128 v[152:155], v204 offset:49152
	ds_read_b128 v[156:159], v1 offset:51200
	ds_read_b128 v[160:163], v204 offset:51200
	s_add_u32 s34, s40, 0x80000
	s_addc_u32 s35, s41, 0
	s_mov_b32 m0, s52
	ds_read_b128 v[164:167], v205 offset:32768
	ds_read_b128 v[168:171], v205 offset:34816
	ds_read_b128 v[172:175], v206 offset:32768
	ds_read_b128 v[176:179], v206 offset:34816
	ds_read_b128 v[190:193], v205 offset:36864
	ds_read_b128 v[194:197], v205 offset:38912
	ds_read_b128 v[198:201], v206 offset:36864
	ds_read_b128 v[232:235], v206 offset:38912
	global_load_lds_dwordx4 v188, s[34:35]
	s_mov_b32 m0, s53
	s_nop 0
	global_load_lds_dwordx4 v186, s[34:35]
	s_waitcnt vmcnt(8)
	s_waitcnt lgkmcnt(0)
	s_barrier
	s_setprio 1
	v_mfma_f32_16x16x32_bf16 v[68:71], v[132:135], v[164:167], v[68:71]
	v_mfma_f32_16x16x32_bf16 v[72:75], v[140:143], v[164:167], v[72:75]
	v_mfma_f32_16x16x32_bf16 v[84:87], v[132:135], v[168:171], v[84:87]
	v_mfma_f32_16x16x32_bf16 v[88:91], v[140:143], v[168:171], v[88:91]
	v_mfma_f32_16x16x32_bf16 v[100:103], v[132:135], v[190:193], v[100:103]
	v_mfma_f32_16x16x32_bf16 v[104:107], v[140:143], v[190:193], v[104:107]
	v_mfma_f32_16x16x32_bf16 v[116:119], v[132:135], v[194:197], v[116:119]
	v_mfma_f32_16x16x32_bf16 v[120:123], v[140:143], v[194:197], v[120:123]
	v_mfma_f32_16x16x32_bf16 v[68:71], v[136:139], v[172:175], v[68:71]
	v_mfma_f32_16x16x32_bf16 v[72:75], v[144:147], v[172:175], v[72:75]
	v_mfma_f32_16x16x32_bf16 v[84:87], v[136:139], v[176:179], v[84:87]
	v_mfma_f32_16x16x32_bf16 v[88:91], v[144:147], v[176:179], v[88:91]
	v_mfma_f32_16x16x32_bf16 v[100:103], v[136:139], v[198:201], v[100:103]
	v_mfma_f32_16x16x32_bf16 v[104:107], v[144:147], v[198:201], v[104:107]
	v_mfma_f32_16x16x32_bf16 v[116:119], v[136:139], v[232:235], v[116:119]
	v_mfma_f32_16x16x32_bf16 v[120:123], v[144:147], v[232:235], v[120:123]
	s_setprio 0
	s_setprio 1
	v_mfma_f32_16x16x32_bf16 v[76:79], v[148:151], v[164:167], v[76:79]
	v_mfma_f32_16x16x32_bf16 v[80:83], v[156:159], v[164:167], v[80:83]
	v_mfma_f32_16x16x32_bf16 v[92:95], v[148:151], v[168:171], v[92:95]
	v_mfma_f32_16x16x32_bf16 v[96:99], v[156:159], v[168:171], v[96:99]
	v_mfma_f32_16x16x32_bf16 v[108:111], v[148:151], v[190:193], v[108:111]
	v_mfma_f32_16x16x32_bf16 v[112:115], v[156:159], v[190:193], v[112:115]
	v_mfma_f32_16x16x32_bf16 v[124:127], v[148:151], v[194:197], v[124:127]
	v_mfma_f32_16x16x32_bf16 v[128:131], v[156:159], v[194:197], v[128:131]
	v_mfma_f32_16x16x32_bf16 v[76:79], v[152:155], v[172:175], v[76:79]
	v_mfma_f32_16x16x32_bf16 v[80:83], v[160:163], v[172:175], v[80:83]
	v_mfma_f32_16x16x32_bf16 v[92:95], v[152:155], v[176:179], v[92:95]
	v_mfma_f32_16x16x32_bf16 v[96:99], v[160:163], v[176:179], v[96:99]
	v_mfma_f32_16x16x32_bf16 v[108:111], v[152:155], v[198:201], v[108:111]
	v_mfma_f32_16x16x32_bf16 v[112:115], v[160:163], v[198:201], v[112:115]
	v_mfma_f32_16x16x32_bf16 v[124:127], v[152:155], v[232:235], v[124:127]
	v_mfma_f32_16x16x32_bf16 v[128:131], v[160:163], v[232:235], v[128:131]
	s_setprio 0
	s_barrier
	s_add_i32 s25, s25, s33
	s_add_i32 m0, s25, 0xffffff80
	ds_read_b128 v[164:167], v205 offset:49152
	ds_read_b128 v[168:171], v205 offset:51200
	ds_read_b128 v[172:175], v206 offset:49152
	ds_read_b128 v[176:179], v206 offset:51200
	ds_read_b128 v[190:193], v205 offset:53248
	ds_read_b128 v[194:197], v205 offset:55296
	ds_read_b128 v[198:201], v206 offset:53248
	ds_read_b128 v[232:235], v206 offset:55296
	global_load_lds_dwordx4 v34, s[28:29] offset:128
	s_add_i32 m0, s25, 0x1f80
	s_mov_b64 s[98:99], s[28:29]
	s_add_u32 s28, s28, 0x80080
	s_addc_u32 s29, s29, 0
	s_add_i32 s25, s31, s33
	global_load_lds_dwordx4 v184, s[98:99] offset:128
	s_mov_b32 m0, s25
	s_nop 0
	global_load_lds_dwordx4 v34, s[28:29]
	s_add_i32 m0, s25, 0x2000
	s_nop 0
	global_load_lds_dwordx4 v184, s[28:29]
	s_add_i32 m0, s54, 0xffffff80
	s_nop 0
	global_load_lds_dwordx4 v188, s[40:41] offset:128
	s_add_i32 m0, s55, 0xffffff80
	s_nop 0
	global_load_lds_dwordx4 v186, s[40:41] offset:128
	s_waitcnt vmcnt(8)
	s_waitcnt lgkmcnt(0)
	s_barrier
	s_setprio 1
	v_mfma_f32_16x16x32_bf16 v[2:5], v[132:135], v[164:167], v[2:5]
	v_mfma_f32_16x16x32_bf16 v[6:9], v[140:143], v[164:167], v[6:9]
	v_mfma_f32_16x16x32_bf16 v[18:21], v[132:135], v[168:171], v[18:21]
	v_mfma_f32_16x16x32_bf16 v[22:25], v[140:143], v[168:171], v[22:25]
	v_mfma_f32_16x16x32_bf16 v[36:39], v[132:135], v[190:193], v[36:39]
	v_mfma_f32_16x16x32_bf16 v[40:43], v[140:143], v[190:193], v[40:43]
	v_mfma_f32_16x16x32_bf16 v[52:55], v[132:135], v[194:197], v[52:55]
	v_mfma_f32_16x16x32_bf16 v[56:59], v[140:143], v[194:197], v[56:59]
	v_mfma_f32_16x16x32_bf16 v[2:5], v[136:139], v[172:175], v[2:5]
	v_mfma_f32_16x16x32_bf16 v[6:9], v[144:147], v[172:175], v[6:9]
	v_mfma_f32_16x16x32_bf16 v[18:21], v[136:139], v[176:179], v[18:21]
	v_mfma_f32_16x16x32_bf16 v[22:25], v[144:147], v[176:179], v[22:25]
	v_mfma_f32_16x16x32_bf16 v[36:39], v[136:139], v[198:201], v[36:39]
	v_mfma_f32_16x16x32_bf16 v[40:43], v[144:147], v[198:201], v[40:43]
	v_mfma_f32_16x16x32_bf16 v[52:55], v[136:139], v[232:235], v[52:55]
	v_mfma_f32_16x16x32_bf16 v[56:59], v[144:147], v[232:235], v[56:59]
	s_setprio 0
	s_setprio 1
	v_mfma_f32_16x16x32_bf16 v[10:13], v[148:151], v[164:167], v[10:13]
	v_mfma_f32_16x16x32_bf16 v[14:17], v[156:159], v[164:167], v[14:17]
	v_mfma_f32_16x16x32_bf16 v[26:29], v[148:151], v[168:171], v[26:29]
	v_mfma_f32_16x16x32_bf16 v[30:33], v[156:159], v[168:171], v[30:33]
	v_mfma_f32_16x16x32_bf16 v[44:47], v[148:151], v[190:193], v[44:47]
	v_mfma_f32_16x16x32_bf16 v[48:51], v[156:159], v[190:193], v[48:51]
	v_mfma_f32_16x16x32_bf16 v[60:63], v[148:151], v[194:197], v[60:63]
	v_mfma_f32_16x16x32_bf16 v[64:67], v[156:159], v[194:197], v[64:67]
	v_mfma_f32_16x16x32_bf16 v[10:13], v[152:155], v[172:175], v[10:13]
	v_mfma_f32_16x16x32_bf16 v[14:17], v[160:163], v[172:175], v[14:17]
	v_mfma_f32_16x16x32_bf16 v[26:29], v[152:155], v[176:179], v[26:29]
	v_mfma_f32_16x16x32_bf16 v[30:33], v[160:163], v[176:179], v[30:33]
	v_mfma_f32_16x16x32_bf16 v[44:47], v[152:155], v[198:201], v[44:47]
	v_mfma_f32_16x16x32_bf16 v[48:51], v[160:163], v[198:201], v[48:51]
	v_mfma_f32_16x16x32_bf16 v[60:63], v[152:155], v[232:235], v[60:63]
	v_mfma_f32_16x16x32_bf16 v[64:67], v[160:163], v[232:235], v[64:67]
	s_setprio 0
	s_barrier
	s_add_u32 s22, s22, 0x100
	s_addc_u32 s23, s23, 0
	s_add_u32 s21, s21, 0x100
	s_addc_u32 s24, s24, 0
	s_cmp_ge_u32 s30, s9
	s_mov_b32 s25, s30
	s_cbranch_scc1 .Lpeel_done_P3
.LBB0_908:
	s_add_i32 s30, s25, 2
	s_add_u32 s28, s22, 0xfff80080
	s_addc_u32 s29, s23, -1
	s_add_i32 s31, 0, 0x10000
	s_cmp_eq_u32 s20, s25
	s_cselect_b32 s41, s47, s29
	s_cselect_b32 s40, s46, s28
	s_cselect_b32 s29, s49, s24
	s_cselect_b32 s28, s48, s21
	s_add_i32 s25, 0, 0x14000
	ds_read_b128 v[132:135], v1
	ds_read_b128 v[136:139], v204
	ds_read_b128 v[140:143], v1 offset:2048
	ds_read_b128 v[144:147], v204 offset:2048
	ds_read_b128 v[148:151], v1 offset:16384
	ds_read_b128 v[152:155], v204 offset:16384
	ds_read_b128 v[156:159], v1 offset:18432
	ds_read_b128 v[160:163], v204 offset:18432
	s_add_i32 m0, s50, 0xc000
	ds_read_b128 v[164:167], v205
	ds_read_b128 v[168:171], v205 offset:2048
	ds_read_b128 v[172:175], v206
	ds_read_b128 v[176:179], v206 offset:2048
	ds_read_b128 v[190:193], v205 offset:4096
	ds_read_b128 v[194:197], v205 offset:6144
	ds_read_b128 v[198:201], v206 offset:4096
	ds_read_b128 v[232:235], v206 offset:6144
	global_load_lds_dwordx4 v188, s[22:23]
	s_add_i32 m0, s50, 0xe000
	s_nop 0
	global_load_lds_dwordx4 v186, s[22:23]
	s_waitcnt vmcnt(8)
	s_waitcnt lgkmcnt(0)
	s_barrier
	s_setprio 1
	v_mfma_f32_16x16x32_bf16 v[68:71], v[132:135], v[164:167], v[68:71]
	v_mfma_f32_16x16x32_bf16 v[72:75], v[140:143], v[164:167], v[72:75]
	v_mfma_f32_16x16x32_bf16 v[84:87], v[132:135], v[168:171], v[84:87]
	v_mfma_f32_16x16x32_bf16 v[88:91], v[140:143], v[168:171], v[88:91]
	v_mfma_f32_16x16x32_bf16 v[100:103], v[132:135], v[190:193], v[100:103]
	v_mfma_f32_16x16x32_bf16 v[104:107], v[140:143], v[190:193], v[104:107]
	v_mfma_f32_16x16x32_bf16 v[116:119], v[132:135], v[194:197], v[116:119]
	v_mfma_f32_16x16x32_bf16 v[120:123], v[140:143], v[194:197], v[120:123]
	v_mfma_f32_16x16x32_bf16 v[68:71], v[136:139], v[172:175], v[68:71]
	v_mfma_f32_16x16x32_bf16 v[72:75], v[144:147], v[172:175], v[72:75]
	v_mfma_f32_16x16x32_bf16 v[84:87], v[136:139], v[176:179], v[84:87]
	v_mfma_f32_16x16x32_bf16 v[88:91], v[144:147], v[176:179], v[88:91]
	v_mfma_f32_16x16x32_bf16 v[100:103], v[136:139], v[198:201], v[100:103]
	v_mfma_f32_16x16x32_bf16 v[104:107], v[144:147], v[198:201], v[104:107]
	v_mfma_f32_16x16x32_bf16 v[116:119], v[136:139], v[232:235], v[116:119]
	v_mfma_f32_16x16x32_bf16 v[120:123], v[144:147], v[232:235], v[120:123]
	s_setprio 0
	s_setprio 1
	v_mfma_f32_16x16x32_bf16 v[76:79], v[148:151], v[164:167], v[76:79]
	v_mfma_f32_16x16x32_bf16 v[80:83], v[156:159], v[164:167], v[80:83]
	v_mfma_f32_16x16x32_bf16 v[92:95], v[148:151], v[168:171], v[92:95]
	v_mfma_f32_16x16x32_bf16 v[96:99], v[156:159], v[168:171], v[96:99]
	v_mfma_f32_16x16x32_bf16 v[108:111], v[148:151], v[190:193], v[108:111]
	v_mfma_f32_16x16x32_bf16 v[112:115], v[156:159], v[190:193], v[112:115]
	v_mfma_f32_16x16x32_bf16 v[124:127], v[148:151], v[194:197], v[124:127]
	v_mfma_f32_16x16x32_bf16 v[128:131], v[156:159], v[194:197], v[128:131]
	v_mfma_f32_16x16x32_bf16 v[76:79], v[152:155], v[172:175], v[76:79]
	v_mfma_f32_16x16x32_bf16 v[80:83], v[160:163], v[172:175], v[80:83]
	v_mfma_f32_16x16x32_bf16 v[92:95], v[152:155], v[176:179], v[92:95]
	v_mfma_f32_16x16x32_bf16 v[96:99], v[160:163], v[176:179], v[96:99]
	v_mfma_f32_16x16x32_bf16 v[108:111], v[152:155], v[198:201], v[108:111]
	v_mfma_f32_16x16x32_bf16 v[112:115], v[160:163], v[198:201], v[112:115]
	v_mfma_f32_16x16x32_bf16 v[124:127], v[152:155], v[232:235], v[124:127]
	v_mfma_f32_16x16x32_bf16 v[128:131], v[160:163], v[232:235], v[128:131]
	s_setprio 0
	s_barrier
	s_add_i32 s31, s31, s33
	s_mov_b32 m0, s31
	ds_read_b128 v[164:167], v205 offset:16384
	ds_read_b128 v[168:171], v205 offset:18432
	ds_read_b128 v[172:175], v206 offset:16384
	ds_read_b128 v[176:179], v206 offset:18432
	ds_read_b128 v[190:193], v205 offset:20480
	ds_read_b128 v[194:197], v205 offset:22528
	ds_read_b128 v[198:201], v206 offset:20480
	ds_read_b128 v[232:235], v206 offset:22528
	global_load_lds_dwordx4 v34, s[28:29]
	s_add_i32 m0, s31, 0x2000
	s_add_u32 s34, s28, 0x80000
	s_addc_u32 s35, s29, 0
	s_add_i32 s25, s25, s33
	global_load_lds_dwordx4 v184, s[28:29]
	s_mov_b32 m0, s25
	s_nop 0
	global_load_lds_dwordx4 v34, s[34:35]
	s_add_i32 m0, s25, 0x2000
	s_nop 0
	global_load_lds_dwordx4 v184, s[34:35]
	s_mov_b32 m0, s50
	s_nop 0
	global_load_lds_dwordx4 v188, s[40:41]
	s_mov_b32 m0, s51
	s_nop 0
	global_load_lds_dwordx4 v186, s[40:41]
	s_waitcnt vmcnt(8)
	s_waitcnt lgkmcnt(0)
	s_barrier
	s_setprio 1
	v_mfma_f32_16x16x32_bf16 v[2:5], v[132:135], v[164:167], v[2:5]
	v_mfma_f32_16x16x32_bf16 v[6:9], v[140:143], v[164:167], v[6:9]
	v_mfma_f32_16x16x32_bf16 v[18:21], v[132:135], v[168:171], v[18:21]
	v_mfma_f32_16x16x32_bf16 v[22:25], v[140:143], v[168:171], v[22:25]
	v_mfma_f32_16x16x32_bf16 v[36:39], v[132:135], v[190:193], v[36:39]
	v_mfma_f32_16x16x32_bf16 v[40:43], v[140:143], v[190:193], v[40:43]
	v_mfma_f32_16x16x32_bf16 v[52:55], v[132:135], v[194:197], v[52:55]
	v_mfma_f32_16x16x32_bf16 v[56:59], v[140:143], v[194:197], v[56:59]
	v_mfma_f32_16x16x32_bf16 v[2:5], v[136:139], v[172:175], v[2:5]
	v_mfma_f32_16x16x32_bf16 v[6:9], v[144:147], v[172:175], v[6:9]
	v_mfma_f32_16x16x32_bf16 v[18:21], v[136:139], v[176:179], v[18:21]
	v_mfma_f32_16x16x32_bf16 v[22:25], v[144:147], v[176:179], v[22:25]
	v_mfma_f32_16x16x32_bf16 v[36:39], v[136:139], v[198:201], v[36:39]
	v_mfma_f32_16x16x32_bf16 v[40:43], v[144:147], v[198:201], v[40:43]
	v_mfma_f32_16x16x32_bf16 v[52:55], v[136:139], v[232:235], v[52:55]
	v_mfma_f32_16x16x32_bf16 v[56:59], v[144:147], v[232:235], v[56:59]
	s_setprio 0
	s_setprio 1
	v_mfma_f32_16x16x32_bf16 v[10:13], v[148:151], v[164:167], v[10:13]
	v_mfma_f32_16x16x32_bf16 v[14:17], v[156:159], v[164:167], v[14:17]
	v_mfma_f32_16x16x32_bf16 v[26:29], v[148:151], v[168:171], v[26:29]
	v_mfma_f32_16x16x32_bf16 v[30:33], v[156:159], v[168:171], v[30:33]
	v_mfma_f32_16x16x32_bf16 v[44:47], v[148:151], v[190:193], v[44:47]
	v_mfma_f32_16x16x32_bf16 v[48:51], v[156:159], v[190:193], v[48:51]
	v_mfma_f32_16x16x32_bf16 v[60:63], v[148:151], v[194:197], v[60:63]
	v_mfma_f32_16x16x32_bf16 v[64:67], v[156:159], v[194:197], v[64:67]
	v_mfma_f32_16x16x32_bf16 v[10:13], v[152:155], v[172:175], v[10:13]
	v_mfma_f32_16x16x32_bf16 v[14:17], v[160:163], v[172:175], v[14:17]
	v_mfma_f32_16x16x32_bf16 v[26:29], v[152:155], v[176:179], v[26:29]
	v_mfma_f32_16x16x32_bf16 v[30:33], v[160:163], v[176:179], v[30:33]
	v_mfma_f32_16x16x32_bf16 v[44:47], v[152:155], v[198:201], v[44:47]
	v_mfma_f32_16x16x32_bf16 v[48:51], v[160:163], v[198:201], v[48:51]
	v_mfma_f32_16x16x32_bf16 v[60:63], v[152:155], v[232:235], v[60:63]
	v_mfma_f32_16x16x32_bf16 v[64:67], v[160:163], v[232:235], v[64:67]
	s_setprio 0
	s_barrier
	s_add_i32 s25, 0, 0x18000
	s_add_i32 s31, 0, 0x1c000
	ds_read_b128 v[132:135], v1 offset:32768
	ds_read_b128 v[136:139], v204 offset:32768
	ds_read_b128 v[140:143], v1 offset:34816
	ds_read_b128 v[144:147], v204 offset:34816
	ds_read_b128 v[148:151], v1 offset:49152
	ds_read_b128 v[152:155], v204 offset:49152
	ds_read_b128 v[156:159], v1 offset:51200
	ds_read_b128 v[160:163], v204 offset:51200
	s_add_u32 s34, s40, 0x80000
	s_addc_u32 s35, s41, 0
	s_mov_b32 m0, s52
	ds_read_b128 v[164:167], v205 offset:32768
	ds_read_b128 v[168:171], v205 offset:34816
	ds_read_b128 v[172:175], v206 offset:32768
	ds_read_b128 v[176:179], v206 offset:34816
	ds_read_b128 v[190:193], v205 offset:36864
	ds_read_b128 v[194:197], v205 offset:38912
	ds_read_b128 v[198:201], v206 offset:36864
	ds_read_b128 v[232:235], v206 offset:38912
	global_load_lds_dwordx4 v188, s[34:35]
	s_mov_b32 m0, s53
	s_nop 0
	global_load_lds_dwordx4 v186, s[34:35]
	s_waitcnt vmcnt(8)
	s_waitcnt lgkmcnt(0)
	s_barrier
	s_setprio 1
	v_mfma_f32_16x16x32_bf16 v[68:71], v[132:135], v[164:167], v[68:71]
	v_mfma_f32_16x16x32_bf16 v[72:75], v[140:143], v[164:167], v[72:75]
	v_mfma_f32_16x16x32_bf16 v[84:87], v[132:135], v[168:171], v[84:87]
	v_mfma_f32_16x16x32_bf16 v[88:91], v[140:143], v[168:171], v[88:91]
	v_mfma_f32_16x16x32_bf16 v[100:103], v[132:135], v[190:193], v[100:103]
	v_mfma_f32_16x16x32_bf16 v[104:107], v[140:143], v[190:193], v[104:107]
	v_mfma_f32_16x16x32_bf16 v[116:119], v[132:135], v[194:197], v[116:119]
	v_mfma_f32_16x16x32_bf16 v[120:123], v[140:143], v[194:197], v[120:123]
	v_mfma_f32_16x16x32_bf16 v[68:71], v[136:139], v[172:175], v[68:71]
	v_mfma_f32_16x16x32_bf16 v[72:75], v[144:147], v[172:175], v[72:75]
	v_mfma_f32_16x16x32_bf16 v[84:87], v[136:139], v[176:179], v[84:87]
	v_mfma_f32_16x16x32_bf16 v[88:91], v[144:147], v[176:179], v[88:91]
	v_mfma_f32_16x16x32_bf16 v[100:103], v[136:139], v[198:201], v[100:103]
	v_mfma_f32_16x16x32_bf16 v[104:107], v[144:147], v[198:201], v[104:107]
	v_mfma_f32_16x16x32_bf16 v[116:119], v[136:139], v[232:235], v[116:119]
	v_mfma_f32_16x16x32_bf16 v[120:123], v[144:147], v[232:235], v[120:123]
	s_setprio 0
	s_setprio 1
	v_mfma_f32_16x16x32_bf16 v[76:79], v[148:151], v[164:167], v[76:79]
	v_mfma_f32_16x16x32_bf16 v[80:83], v[156:159], v[164:167], v[80:83]
	v_mfma_f32_16x16x32_bf16 v[92:95], v[148:151], v[168:171], v[92:95]
	v_mfma_f32_16x16x32_bf16 v[96:99], v[156:159], v[168:171], v[96:99]
	v_mfma_f32_16x16x32_bf16 v[108:111], v[148:151], v[190:193], v[108:111]
	v_mfma_f32_16x16x32_bf16 v[112:115], v[156:159], v[190:193], v[112:115]
	v_mfma_f32_16x16x32_bf16 v[124:127], v[148:151], v[194:197], v[124:127]
	v_mfma_f32_16x16x32_bf16 v[128:131], v[156:159], v[194:197], v[128:131]
	v_mfma_f32_16x16x32_bf16 v[76:79], v[152:155], v[172:175], v[76:79]
	v_mfma_f32_16x16x32_bf16 v[80:83], v[160:163], v[172:175], v[80:83]
	v_mfma_f32_16x16x32_bf16 v[92:95], v[152:155], v[176:179], v[92:95]
	v_mfma_f32_16x16x32_bf16 v[96:99], v[160:163], v[176:179], v[96:99]
	v_mfma_f32_16x16x32_bf16 v[108:111], v[152:155], v[198:201], v[108:111]
	v_mfma_f32_16x16x32_bf16 v[112:115], v[160:163], v[198:201], v[112:115]
	v_mfma_f32_16x16x32_bf16 v[124:127], v[152:155], v[232:235], v[124:127]
	v_mfma_f32_16x16x32_bf16 v[128:131], v[160:163], v[232:235], v[128:131]
	s_setprio 0
	s_barrier
	s_add_i32 s25, s25, s33
	s_add_i32 m0, s25, 0xffffff80
	ds_read_b128 v[164:167], v205 offset:49152
	ds_read_b128 v[168:171], v205 offset:51200
	ds_read_b128 v[172:175], v206 offset:49152
	ds_read_b128 v[176:179], v206 offset:51200
	ds_read_b128 v[190:193], v205 offset:53248
	ds_read_b128 v[194:197], v205 offset:55296
	ds_read_b128 v[198:201], v206 offset:53248
	ds_read_b128 v[232:235], v206 offset:55296
	global_load_lds_dwordx4 v34, s[28:29] offset:128
	s_add_i32 m0, s25, 0x1f80
	s_mov_b64 s[98:99], s[28:29]
	s_add_u32 s28, s28, 0x80080
	s_addc_u32 s29, s29, 0
	s_add_i32 s25, s31, s33
	global_load_lds_dwordx4 v184, s[98:99] offset:128
	s_mov_b32 m0, s25
	s_nop 0
	global_load_lds_dwordx4 v34, s[28:29]
	s_add_i32 m0, s25, 0x2000
	s_nop 0
	global_load_lds_dwordx4 v184, s[28:29]
	s_add_i32 m0, s54, 0xffffff80
	s_nop 0
	global_load_lds_dwordx4 v188, s[40:41] offset:128
	s_add_i32 m0, s55, 0xffffff80
	s_nop 0
	global_load_lds_dwordx4 v186, s[40:41] offset:128
	s_waitcnt vmcnt(8)
	s_waitcnt lgkmcnt(0)
	s_barrier
	s_setprio 1
	v_mfma_f32_16x16x32_bf16 v[2:5], v[132:135], v[164:167], v[2:5]
	v_mfma_f32_16x16x32_bf16 v[6:9], v[140:143], v[164:167], v[6:9]
	v_mfma_f32_16x16x32_bf16 v[18:21], v[132:135], v[168:171], v[18:21]
	v_mfma_f32_16x16x32_bf16 v[22:25], v[140:143], v[168:171], v[22:25]
	v_mfma_f32_16x16x32_bf16 v[36:39], v[132:135], v[190:193], v[36:39]
	v_mfma_f32_16x16x32_bf16 v[40:43], v[140:143], v[190:193], v[40:43]
	v_mfma_f32_16x16x32_bf16 v[52:55], v[132:135], v[194:197], v[52:55]
	v_mfma_f32_16x16x32_bf16 v[56:59], v[140:143], v[194:197], v[56:59]
	v_mfma_f32_16x16x32_bf16 v[2:5], v[136:139], v[172:175], v[2:5]
	v_mfma_f32_16x16x32_bf16 v[6:9], v[144:147], v[172:175], v[6:9]
	v_mfma_f32_16x16x32_bf16 v[18:21], v[136:139], v[176:179], v[18:21]
	v_mfma_f32_16x16x32_bf16 v[22:25], v[144:147], v[176:179], v[22:25]
	v_mfma_f32_16x16x32_bf16 v[36:39], v[136:139], v[198:201], v[36:39]
	v_mfma_f32_16x16x32_bf16 v[40:43], v[144:147], v[198:201], v[40:43]
	v_mfma_f32_16x16x32_bf16 v[52:55], v[136:139], v[232:235], v[52:55]
	v_mfma_f32_16x16x32_bf16 v[56:59], v[144:147], v[232:235], v[56:59]
	s_setprio 0
	s_setprio 1
	v_mfma_f32_16x16x32_bf16 v[10:13], v[148:151], v[164:167], v[10:13]
	v_mfma_f32_16x16x32_bf16 v[14:17], v[156:159], v[164:167], v[14:17]
	v_mfma_f32_16x16x32_bf16 v[26:29], v[148:151], v[168:171], v[26:29]
	v_mfma_f32_16x16x32_bf16 v[30:33], v[156:159], v[168:171], v[30:33]
	v_mfma_f32_16x16x32_bf16 v[44:47], v[148:151], v[190:193], v[44:47]
	v_mfma_f32_16x16x32_bf16 v[48:51], v[156:159], v[190:193], v[48:51]
	v_mfma_f32_16x16x32_bf16 v[60:63], v[148:151], v[194:197], v[60:63]
	v_mfma_f32_16x16x32_bf16 v[64:67], v[156:159], v[194:197], v[64:67]
	v_mfma_f32_16x16x32_bf16 v[10:13], v[152:155], v[172:175], v[10:13]
	v_mfma_f32_16x16x32_bf16 v[14:17], v[160:163], v[172:175], v[14:17]
	v_mfma_f32_16x16x32_bf16 v[26:29], v[152:155], v[176:179], v[26:29]
	v_mfma_f32_16x16x32_bf16 v[30:33], v[160:163], v[176:179], v[30:33]
	v_mfma_f32_16x16x32_bf16 v[44:47], v[152:155], v[198:201], v[44:47]
	v_mfma_f32_16x16x32_bf16 v[48:51], v[160:163], v[198:201], v[48:51]
	v_mfma_f32_16x16x32_bf16 v[60:63], v[152:155], v[232:235], v[60:63]
	v_mfma_f32_16x16x32_bf16 v[64:67], v[160:163], v[232:235], v[64:67]
	s_setprio 0
	s_barrier
	s_add_u32 s22, s22, 0x100
	s_addc_u32 s23, s23, 0
	s_add_u32 s21, s21, 0x100
	s_addc_u32 s24, s24, 0
	s_cmp_ge_u32 s30, s9
	s_mov_b32 s25, s30
	s_cbranch_scc0 .LBB0_908

.LBB0_1022:
	s_ashr_i32 s23, s22, 31
	s_lshl_b64 s[12:13], s[22:23], 20
	v_readlane_b32 s20, v254, 52
	v_readlane_b32 s21, v254, 53
	s_add_u32 s40, s20, s12
	s_addc_u32 s41, s21, s13
	s_and_b64 s[12:13], s[38:39], exec
	s_cselect_b32 s12, s41, s9
	s_cselect_b32 s13, s40, s8
	s_ashr_i32 s19, s18, 31
	s_lshl_b64 s[20:21], s[18:19], 20
	v_readlane_b32 s24, v254, 48
	v_readlane_b32 s25, v254, 49
	s_add_u32 s42, s24, s20
	s_addc_u32 s43, s25, s21
	s_and_b64 s[20:21], s[38:39], exec
	s_cselect_b32 s19, s43, s29
	s_cselect_b32 s20, s42, s28
	s_add_u32 s8, s8, 0x80080
	s_addc_u32 s9, s9, 0
	s_add_u32 s21, s28, 0x100
	s_addc_u32 s23, s29, 0
	s_mov_b32 s24, -2
	v_readlane_b32 s35, v255, 20
	v_readlane_b32 s57, v255, 21
	v_readlane_b32 s58, v255, 22
	v_readlane_b32 s59, v255, 23
	s_mov_b64 s[60:61], 0x80
	s_add_u32 s25, s8, 0xfff80080
	s_addc_u32 s28, s9, -1
	s_add_i32 s30, 0, 0x10000
	s_cmp_eq_u32 s24, 28
	s_cselect_b32 s45, s12, s28
	s_cselect_b32 s44, s13, s25
	s_cselect_b32 s29, s19, s23
	s_cselect_b32 s28, s20, s21
	s_add_i32 s25, 0, 0x14000
	ds_read_b128 v[138:141], v1
	ds_read_b128 v[142:145], v150
	ds_read_b128 v[146:149], v1 offset:2048
	ds_read_b128 v[154:157], v150 offset:2048
	ds_read_b128 v[158:161], v1 offset:16384
	ds_read_b128 v[162:165], v150 offset:16384
	ds_read_b128 v[166:169], v1 offset:18432
	ds_read_b128 v[170:173], v150 offset:18432
	s_add_i32 m0, s46, 0xc000
	ds_read_b128 v[174:177], v151
	ds_read_b128 v[184:187], v151 offset:2048
	ds_read_b128 v[188:191], v152
	ds_read_b128 v[192:195], v152 offset:2048
	ds_read_b128 v[196:199], v151 offset:4096
	ds_read_b128 v[200:203], v151 offset:6144
	ds_read_b128 v[204:207], v152 offset:4096
	ds_read_b128 v[208:211], v152 offset:6144
	global_load_lds_dwordx4 v136, s[8:9]
	s_add_i32 m0, s46, 0xe000
	s_nop 0
	global_load_lds_dwordx4 v134, s[8:9]
	s_waitcnt vmcnt(8)
	s_waitcnt lgkmcnt(0)
	s_barrier
	s_setprio 1
	v_mfma_f32_16x16x32_bf16 v[128:131], v[138:141], v[174:177], 0
	v_mfma_f32_16x16x32_bf16 v[124:127], v[146:149], v[174:177], 0
	v_mfma_f32_16x16x32_bf16 v[112:115], v[138:141], v[184:187], 0
	v_mfma_f32_16x16x32_bf16 v[108:111], v[146:149], v[184:187], 0
	v_mfma_f32_16x16x32_bf16 v[96:99], v[138:141], v[196:199], 0
	v_mfma_f32_16x16x32_bf16 v[92:95], v[146:149], v[196:199], 0
	v_mfma_f32_16x16x32_bf16 v[80:83], v[138:141], v[200:203], 0
	v_mfma_f32_16x16x32_bf16 v[76:79], v[146:149], v[200:203], 0
	v_mfma_f32_16x16x32_bf16 v[128:131], v[142:145], v[188:191], v[128:131]
	v_mfma_f32_16x16x32_bf16 v[124:127], v[154:157], v[188:191], v[124:127]
	v_mfma_f32_16x16x32_bf16 v[112:115], v[142:145], v[192:195], v[112:115]
	v_mfma_f32_16x16x32_bf16 v[108:111], v[154:157], v[192:195], v[108:111]
	v_mfma_f32_16x16x32_bf16 v[96:99], v[142:145], v[204:207], v[96:99]
	v_mfma_f32_16x16x32_bf16 v[92:95], v[154:157], v[204:207], v[92:95]
	v_mfma_f32_16x16x32_bf16 v[80:83], v[142:145], v[208:211], v[80:83]
	v_mfma_f32_16x16x32_bf16 v[76:79], v[154:157], v[208:211], v[76:79]
	s_setprio 0
	s_setprio 1
	v_mfma_f32_16x16x32_bf16 v[120:123], v[158:161], v[174:177], 0
	v_mfma_f32_16x16x32_bf16 v[116:119], v[166:169], v[174:177], 0
	v_mfma_f32_16x16x32_bf16 v[104:107], v[158:161], v[184:187], 0
	v_mfma_f32_16x16x32_bf16 v[100:103], v[166:169], v[184:187], 0
	v_mfma_f32_16x16x32_bf16 v[88:91], v[158:161], v[196:199], 0
	v_mfma_f32_16x16x32_bf16 v[84:87], v[166:169], v[196:199], 0
	v_mfma_f32_16x16x32_bf16 v[72:75], v[158:161], v[200:203], 0
	v_mfma_f32_16x16x32_bf16 v[68:71], v[166:169], v[200:203], 0
	v_mfma_f32_16x16x32_bf16 v[120:123], v[162:165], v[188:191], v[120:123]
	v_mfma_f32_16x16x32_bf16 v[116:119], v[170:173], v[188:191], v[116:119]
	v_mfma_f32_16x16x32_bf16 v[104:107], v[162:165], v[192:195], v[104:107]
	v_mfma_f32_16x16x32_bf16 v[100:103], v[170:173], v[192:195], v[100:103]
	v_mfma_f32_16x16x32_bf16 v[88:91], v[162:165], v[204:207], v[88:91]
	v_mfma_f32_16x16x32_bf16 v[84:87], v[170:173], v[204:207], v[84:87]
	v_mfma_f32_16x16x32_bf16 v[72:75], v[162:165], v[208:211], v[72:75]
	v_mfma_f32_16x16x32_bf16 v[68:71], v[170:173], v[208:211], v[68:71]
	s_setprio 0
	s_barrier
	s_add_i32 s30, s30, s33
	s_mov_b32 m0, s30
	ds_read_b128 v[174:177], v151 offset:16384
	ds_read_b128 v[184:187], v151 offset:18432
	ds_read_b128 v[188:191], v152 offset:16384
	ds_read_b128 v[192:195], v152 offset:18432
	ds_read_b128 v[196:199], v151 offset:20480
	ds_read_b128 v[200:203], v151 offset:22528
	ds_read_b128 v[204:207], v152 offset:20480
	ds_read_b128 v[208:211], v152 offset:22528
	global_load_lds_dwordx4 v34, s[28:29]
	s_add_i32 m0, s30, 0x2000
	s_add_u32 s30, s28, 0x80000
	s_addc_u32 s31, s29, 0
	s_add_i32 s25, s25, s33
	global_load_lds_dwordx4 v132, s[28:29]
	s_mov_b32 m0, s25
	s_nop 0
	global_load_lds_dwordx4 v34, s[30:31]
	s_add_i32 m0, s25, 0x2000
	s_nop 0
	global_load_lds_dwordx4 v132, s[30:31]
	s_mov_b32 m0, s46
	s_nop 0
	global_load_lds_dwordx4 v136, s[44:45]
	s_mov_b32 m0, s47
	s_nop 0
	global_load_lds_dwordx4 v134, s[44:45]
	s_waitcnt vmcnt(8)
	s_waitcnt lgkmcnt(0)
	s_barrier
	s_setprio 1
	v_mfma_f32_16x16x32_bf16 v[64:67], v[138:141], v[174:177], 0
	v_mfma_f32_16x16x32_bf16 v[60:63], v[146:149], v[174:177], 0
	v_mfma_f32_16x16x32_bf16 v[48:51], v[138:141], v[184:187], 0
	v_mfma_f32_16x16x32_bf16 v[44:47], v[146:149], v[184:187], 0
	v_mfma_f32_16x16x32_bf16 v[30:33], v[138:141], v[196:199], 0
	v_mfma_f32_16x16x32_bf16 v[26:29], v[146:149], v[196:199], 0
	v_mfma_f32_16x16x32_bf16 v[14:17], v[138:141], v[200:203], 0
	v_mfma_f32_16x16x32_bf16 v[10:13], v[146:149], v[200:203], 0
	v_mfma_f32_16x16x32_bf16 v[64:67], v[142:145], v[188:191], v[64:67]
	v_mfma_f32_16x16x32_bf16 v[60:63], v[154:157], v[188:191], v[60:63]
	v_mfma_f32_16x16x32_bf16 v[48:51], v[142:145], v[192:195], v[48:51]
	v_mfma_f32_16x16x32_bf16 v[44:47], v[154:157], v[192:195], v[44:47]
	v_mfma_f32_16x16x32_bf16 v[30:33], v[142:145], v[204:207], v[30:33]
	v_mfma_f32_16x16x32_bf16 v[26:29], v[154:157], v[204:207], v[26:29]
	v_mfma_f32_16x16x32_bf16 v[14:17], v[142:145], v[208:211], v[14:17]
	v_mfma_f32_16x16x32_bf16 v[10:13], v[154:157], v[208:211], v[10:13]
	s_setprio 0
	s_setprio 1
	v_mfma_f32_16x16x32_bf16 v[56:59], v[158:161], v[174:177], 0
	v_mfma_f32_16x16x32_bf16 v[52:55], v[166:169], v[174:177], 0
	v_mfma_f32_16x16x32_bf16 v[40:43], v[158:161], v[184:187], 0
	v_mfma_f32_16x16x32_bf16 v[36:39], v[166:169], v[184:187], 0
	v_mfma_f32_16x16x32_bf16 v[22:25], v[158:161], v[196:199], 0
	v_mfma_f32_16x16x32_bf16 v[18:21], v[166:169], v[196:199], 0
	v_mfma_f32_16x16x32_bf16 v[6:9], v[158:161], v[200:203], 0
	v_mfma_f32_16x16x32_bf16 v[2:5], v[166:169], v[200:203], 0
	v_mfma_f32_16x16x32_bf16 v[56:59], v[162:165], v[188:191], v[56:59]
	v_mfma_f32_16x16x32_bf16 v[52:55], v[170:173], v[188:191], v[52:55]
	v_mfma_f32_16x16x32_bf16 v[40:43], v[162:165], v[192:195], v[40:43]
	v_mfma_f32_16x16x32_bf16 v[36:39], v[170:173], v[192:195], v[36:39]
	v_mfma_f32_16x16x32_bf16 v[22:25], v[162:165], v[204:207], v[22:25]
	v_mfma_f32_16x16x32_bf16 v[18:21], v[170:173], v[204:207], v[18:21]
	v_mfma_f32_16x16x32_bf16 v[6:9], v[162:165], v[208:211], v[6:9]
	v_mfma_f32_16x16x32_bf16 v[2:5], v[170:173], v[208:211], v[2:5]
	s_setprio 0
	s_barrier
	s_add_i32 s25, 0, 0x18000
	s_add_i32 s34, 0, 0x1c000
	ds_read_b128 v[138:141], v1 offset:32768
	ds_read_b128 v[142:145], v150 offset:32768
	ds_read_b128 v[146:149], v1 offset:34816
	ds_read_b128 v[154:157], v150 offset:34816
	ds_read_b128 v[158:161], v1 offset:49152
	ds_read_b128 v[162:165], v150 offset:49152
	ds_read_b128 v[166:169], v1 offset:51200
	ds_read_b128 v[170:173], v150 offset:51200
	s_add_u32 s30, s44, 0x80000
	s_addc_u32 s31, s45, 0
	s_mov_b32 m0, s48
	ds_read_b128 v[174:177], v151 offset:32768
	ds_read_b128 v[184:187], v151 offset:34816
	ds_read_b128 v[188:191], v152 offset:32768
	ds_read_b128 v[192:195], v152 offset:34816
	ds_read_b128 v[196:199], v151 offset:36864
	ds_read_b128 v[200:203], v151 offset:38912
	ds_read_b128 v[204:207], v152 offset:36864
	ds_read_b128 v[208:211], v152 offset:38912
	global_load_lds_dwordx4 v136, s[30:31]
	s_mov_b32 m0, s49
	s_nop 0
	global_load_lds_dwordx4 v134, s[30:31]
	s_waitcnt vmcnt(8)
	s_waitcnt lgkmcnt(0)
	s_barrier
	s_setprio 1
	v_mfma_f32_16x16x32_bf16 v[128:131], v[138:141], v[174:177], v[128:131]
	v_mfma_f32_16x16x32_bf16 v[124:127], v[146:149], v[174:177], v[124:127]
	v_mfma_f32_16x16x32_bf16 v[112:115], v[138:141], v[184:187], v[112:115]
	v_mfma_f32_16x16x32_bf16 v[108:111], v[146:149], v[184:187], v[108:111]
	v_mfma_f32_16x16x32_bf16 v[96:99], v[138:141], v[196:199], v[96:99]
	v_mfma_f32_16x16x32_bf16 v[92:95], v[146:149], v[196:199], v[92:95]
	v_mfma_f32_16x16x32_bf16 v[80:83], v[138:141], v[200:203], v[80:83]
	v_mfma_f32_16x16x32_bf16 v[76:79], v[146:149], v[200:203], v[76:79]
	v_mfma_f32_16x16x32_bf16 v[128:131], v[142:145], v[188:191], v[128:131]
	v_mfma_f32_16x16x32_bf16 v[124:127], v[154:157], v[188:191], v[124:127]
	v_mfma_f32_16x16x32_bf16 v[112:115], v[142:145], v[192:195], v[112:115]
	v_mfma_f32_16x16x32_bf16 v[108:111], v[154:157], v[192:195], v[108:111]
	v_mfma_f32_16x16x32_bf16 v[96:99], v[142:145], v[204:207], v[96:99]
	v_mfma_f32_16x16x32_bf16 v[92:95], v[154:157], v[204:207], v[92:95]
	v_mfma_f32_16x16x32_bf16 v[80:83], v[142:145], v[208:211], v[80:83]
	v_mfma_f32_16x16x32_bf16 v[76:79], v[154:157], v[208:211], v[76:79]
	s_setprio 0
	s_setprio 1
	v_mfma_f32_16x16x32_bf16 v[120:123], v[158:161], v[174:177], v[120:123]
	v_mfma_f32_16x16x32_bf16 v[116:119], v[166:169], v[174:177], v[116:119]
	v_mfma_f32_16x16x32_bf16 v[104:107], v[158:161], v[184:187], v[104:107]
	v_mfma_f32_16x16x32_bf16 v[100:103], v[166:169], v[184:187], v[100:103]
	v_mfma_f32_16x16x32_bf16 v[88:91], v[158:161], v[196:199], v[88:91]
	v_mfma_f32_16x16x32_bf16 v[84:87], v[166:169], v[196:199], v[84:87]
	v_mfma_f32_16x16x32_bf16 v[72:75], v[158:161], v[200:203], v[72:75]
	v_mfma_f32_16x16x32_bf16 v[68:71], v[166:169], v[200:203], v[68:71]
	v_mfma_f32_16x16x32_bf16 v[120:123], v[162:165], v[188:191], v[120:123]
	v_mfma_f32_16x16x32_bf16 v[116:119], v[170:173], v[188:191], v[116:119]
	v_mfma_f32_16x16x32_bf16 v[104:107], v[162:165], v[192:195], v[104:107]
	v_mfma_f32_16x16x32_bf16 v[100:103], v[170:173], v[192:195], v[100:103]
	v_mfma_f32_16x16x32_bf16 v[88:91], v[162:165], v[204:207], v[88:91]
	v_mfma_f32_16x16x32_bf16 v[84:87], v[170:173], v[204:207], v[84:87]
	v_mfma_f32_16x16x32_bf16 v[72:75], v[162:165], v[208:211], v[72:75]
	v_mfma_f32_16x16x32_bf16 v[68:71], v[170:173], v[208:211], v[68:71]
	s_setprio 0
	s_barrier
	s_add_i32 s25, s25, s33
	s_add_i32 m0, s25, 0xffffff80
	ds_read_b128 v[174:177], v151 offset:49152
	ds_read_b128 v[184:187], v151 offset:51200
	ds_read_b128 v[188:191], v152 offset:49152
	ds_read_b128 v[192:195], v152 offset:51200
	ds_read_b128 v[196:199], v151 offset:53248
	ds_read_b128 v[200:203], v151 offset:55296
	ds_read_b128 v[204:207], v152 offset:53248
	ds_read_b128 v[208:211], v152 offset:55296
	global_load_lds_dwordx4 v34, s[28:29] offset:128
	s_add_i32 m0, s25, 0x1f80
	s_mov_b64 s[98:99], s[28:29]
	s_add_u32 s28, s28, 0x80080
	s_addc_u32 s29, s29, 0
	s_add_i32 s25, s34, s33
	global_load_lds_dwordx4 v132, s[98:99] offset:128
	s_mov_b32 m0, s25
	s_nop 0
	global_load_lds_dwordx4 v34, s[28:29]
	s_add_i32 m0, s25, 0x2000
	s_nop 0
	global_load_lds_dwordx4 v132, s[28:29]
	s_add_i32 m0, s52, 0xffffff80
	s_nop 0
	global_load_lds_dwordx4 v136, s[44:45] offset:128
	s_add_i32 m0, s53, 0xffffff80
	s_nop 0
	global_load_lds_dwordx4 v134, s[44:45] offset:128
	s_waitcnt vmcnt(8)
	s_waitcnt lgkmcnt(0)
	s_barrier
	s_setprio 1
	v_mfma_f32_16x16x32_bf16 v[64:67], v[138:141], v[174:177], v[64:67]
	v_mfma_f32_16x16x32_bf16 v[60:63], v[146:149], v[174:177], v[60:63]
	v_mfma_f32_16x16x32_bf16 v[48:51], v[138:141], v[184:187], v[48:51]
	v_mfma_f32_16x16x32_bf16 v[44:47], v[146:149], v[184:187], v[44:47]
	v_mfma_f32_16x16x32_bf16 v[30:33], v[138:141], v[196:199], v[30:33]
	v_mfma_f32_16x16x32_bf16 v[26:29], v[146:149], v[196:199], v[26:29]
	v_mfma_f32_16x16x32_bf16 v[14:17], v[138:141], v[200:203], v[14:17]
	v_mfma_f32_16x16x32_bf16 v[10:13], v[146:149], v[200:203], v[10:13]
	v_mfma_f32_16x16x32_bf16 v[64:67], v[142:145], v[188:191], v[64:67]
	v_mfma_f32_16x16x32_bf16 v[60:63], v[154:157], v[188:191], v[60:63]
	v_mfma_f32_16x16x32_bf16 v[48:51], v[142:145], v[192:195], v[48:51]
	v_mfma_f32_16x16x32_bf16 v[44:47], v[154:157], v[192:195], v[44:47]
	v_mfma_f32_16x16x32_bf16 v[30:33], v[142:145], v[204:207], v[30:33]
	v_mfma_f32_16x16x32_bf16 v[26:29], v[154:157], v[204:207], v[26:29]
	v_mfma_f32_16x16x32_bf16 v[14:17], v[142:145], v[208:211], v[14:17]
	v_mfma_f32_16x16x32_bf16 v[10:13], v[154:157], v[208:211], v[10:13]
	s_setprio 0
	s_setprio 1
	v_mfma_f32_16x16x32_bf16 v[56:59], v[158:161], v[174:177], v[56:59]
	v_mfma_f32_16x16x32_bf16 v[52:55], v[166:169], v[174:177], v[52:55]
	v_mfma_f32_16x16x32_bf16 v[40:43], v[158:161], v[184:187], v[40:43]
	v_mfma_f32_16x16x32_bf16 v[36:39], v[166:169], v[184:187], v[36:39]
	v_mfma_f32_16x16x32_bf16 v[22:25], v[158:161], v[196:199], v[22:25]
	v_mfma_f32_16x16x32_bf16 v[18:21], v[166:169], v[196:199], v[18:21]
	v_mfma_f32_16x16x32_bf16 v[6:9], v[158:161], v[200:203], v[6:9]
	v_mfma_f32_16x16x32_bf16 v[2:5], v[166:169], v[200:203], v[2:5]
	v_mfma_f32_16x16x32_bf16 v[56:59], v[162:165], v[188:191], v[56:59]
	v_mfma_f32_16x16x32_bf16 v[52:55], v[170:173], v[188:191], v[52:55]
	v_mfma_f32_16x16x32_bf16 v[40:43], v[162:165], v[192:195], v[40:43]
	v_mfma_f32_16x16x32_bf16 v[36:39], v[170:173], v[192:195], v[36:39]
	v_mfma_f32_16x16x32_bf16 v[22:25], v[162:165], v[204:207], v[22:25]
	v_mfma_f32_16x16x32_bf16 v[18:21], v[170:173], v[204:207], v[18:21]
	v_mfma_f32_16x16x32_bf16 v[6:9], v[162:165], v[208:211], v[6:9]
	v_mfma_f32_16x16x32_bf16 v[2:5], v[170:173], v[208:211], v[2:5]
	s_setprio 0
	s_barrier
	s_add_i32 s24, s24, 2
	s_add_u32 s8, s8, 0x100
	s_addc_u32 s9, s9, 0
	s_add_u32 s21, s21, 0x100
	s_addc_u32 s23, s23, 0
	s_cmp_gt_u32 s24, 29
	s_cbranch_scc1 .Lpeel_done_P4
.LBB0_1023:
	s_add_u32 s25, s8, 0xfff80080
	s_addc_u32 s28, s9, -1
	s_add_i32 s30, 0, 0x10000
	s_cmp_eq_u32 s24, 28
	s_cselect_b32 s45, s12, s28
	s_cselect_b32 s44, s13, s25
	s_cselect_b32 s29, s19, s23
	s_cselect_b32 s28, s20, s21
	s_add_i32 s25, 0, 0x14000
	ds_read_b128 v[138:141], v1
	ds_read_b128 v[142:145], v150
	ds_read_b128 v[146:149], v1 offset:2048
	ds_read_b128 v[154:157], v150 offset:2048
	ds_read_b128 v[158:161], v1 offset:16384
	ds_read_b128 v[162:165], v150 offset:16384
	ds_read_b128 v[166:169], v1 offset:18432
	ds_read_b128 v[170:173], v150 offset:18432
	s_add_i32 m0, s46, 0xc000
	ds_read_b128 v[174:177], v151
	ds_read_b128 v[184:187], v151 offset:2048
	ds_read_b128 v[188:191], v152
	ds_read_b128 v[192:195], v152 offset:2048
	ds_read_b128 v[196:199], v151 offset:4096
	ds_read_b128 v[200:203], v151 offset:6144
	ds_read_b128 v[204:207], v152 offset:4096
	ds_read_b128 v[208:211], v152 offset:6144
	global_load_lds_dwordx4 v136, s[8:9]
	s_add_i32 m0, s46, 0xe000
	s_nop 0
	global_load_lds_dwordx4 v134, s[8:9]
	s_waitcnt vmcnt(8)
	s_waitcnt lgkmcnt(0)
	s_barrier
	s_setprio 1
	v_mfma_f32_16x16x32_bf16 v[128:131], v[138:141], v[174:177], v[128:131]
	v_mfma_f32_16x16x32_bf16 v[124:127], v[146:149], v[174:177], v[124:127]
	v_mfma_f32_16x16x32_bf16 v[112:115], v[138:141], v[184:187], v[112:115]
	v_mfma_f32_16x16x32_bf16 v[108:111], v[146:149], v[184:187], v[108:111]
	v_mfma_f32_16x16x32_bf16 v[96:99], v[138:141], v[196:199], v[96:99]
	v_mfma_f32_16x16x32_bf16 v[92:95], v[146:149], v[196:199], v[92:95]
	v_mfma_f32_16x16x32_bf16 v[80:83], v[138:141], v[200:203], v[80:83]
	v_mfma_f32_16x16x32_bf16 v[76:79], v[146:149], v[200:203], v[76:79]
	v_mfma_f32_16x16x32_bf16 v[128:131], v[142:145], v[188:191], v[128:131]
	v_mfma_f32_16x16x32_bf16 v[124:127], v[154:157], v[188:191], v[124:127]
	v_mfma_f32_16x16x32_bf16 v[112:115], v[142:145], v[192:195], v[112:115]
	v_mfma_f32_16x16x32_bf16 v[108:111], v[154:157], v[192:195], v[108:111]
	v_mfma_f32_16x16x32_bf16 v[96:99], v[142:145], v[204:207], v[96:99]
	v_mfma_f32_16x16x32_bf16 v[92:95], v[154:157], v[204:207], v[92:95]
	v_mfma_f32_16x16x32_bf16 v[80:83], v[142:145], v[208:211], v[80:83]
	v_mfma_f32_16x16x32_bf16 v[76:79], v[154:157], v[208:211], v[76:79]
	s_setprio 0
	s_setprio 1
	v_mfma_f32_16x16x32_bf16 v[120:123], v[158:161], v[174:177], v[120:123]
	v_mfma_f32_16x16x32_bf16 v[116:119], v[166:169], v[174:177], v[116:119]
	v_mfma_f32_16x16x32_bf16 v[104:107], v[158:161], v[184:187], v[104:107]
	v_mfma_f32_16x16x32_bf16 v[100:103], v[166:169], v[184:187], v[100:103]
	v_mfma_f32_16x16x32_bf16 v[88:91], v[158:161], v[196:199], v[88:91]
	v_mfma_f32_16x16x32_bf16 v[84:87], v[166:169], v[196:199], v[84:87]
	v_mfma_f32_16x16x32_bf16 v[72:75], v[158:161], v[200:203], v[72:75]
	v_mfma_f32_16x16x32_bf16 v[68:71], v[166:169], v[200:203], v[68:71]
	v_mfma_f32_16x16x32_bf16 v[120:123], v[162:165], v[188:191], v[120:123]
	v_mfma_f32_16x16x32_bf16 v[116:119], v[170:173], v[188:191], v[116:119]
	v_mfma_f32_16x16x32_bf16 v[104:107], v[162:165], v[192:195], v[104:107]
	v_mfma_f32_16x16x32_bf16 v[100:103], v[170:173], v[192:195], v[100:103]
	v_mfma_f32_16x16x32_bf16 v[88:91], v[162:165], v[204:207], v[88:91]
	v_mfma_f32_16x16x32_bf16 v[84:87], v[170:173], v[204:207], v[84:87]
	v_mfma_f32_16x16x32_bf16 v[72:75], v[162:165], v[208:211], v[72:75]
	v_mfma_f32_16x16x32_bf16 v[68:71], v[170:173], v[208:211], v[68:71]
	s_setprio 0
	s_barrier
	s_add_i32 s30, s30, s33
	s_mov_b32 m0, s30
	ds_read_b128 v[174:177], v151 offset:16384
	ds_read_b128 v[184:187], v151 offset:18432
	ds_read_b128 v[188:191], v152 offset:16384
	ds_read_b128 v[192:195], v152 offset:18432
	ds_read_b128 v[196:199], v151 offset:20480
	ds_read_b128 v[200:203], v151 offset:22528
	ds_read_b128 v[204:207], v152 offset:20480
	ds_read_b128 v[208:211], v152 offset:22528
	global_load_lds_dwordx4 v34, s[28:29]
	s_add_i32 m0, s30, 0x2000
	s_add_u32 s30, s28, 0x80000
	s_addc_u32 s31, s29, 0
	s_add_i32 s25, s25, s33
	global_load_lds_dwordx4 v132, s[28:29]
	s_mov_b32 m0, s25
	s_nop 0
	global_load_lds_dwordx4 v34, s[30:31]
	s_add_i32 m0, s25, 0x2000
	s_nop 0
	global_load_lds_dwordx4 v132, s[30:31]
	s_mov_b32 m0, s46
	s_nop 0
	global_load_lds_dwordx4 v136, s[44:45]
	s_mov_b32 m0, s47
	s_nop 0
	global_load_lds_dwordx4 v134, s[44:45]
	s_waitcnt vmcnt(8)
	s_waitcnt lgkmcnt(0)
	s_barrier
	s_setprio 1
	v_mfma_f32_16x16x32_bf16 v[64:67], v[138:141], v[174:177], v[64:67]
	v_mfma_f32_16x16x32_bf16 v[60:63], v[146:149], v[174:177], v[60:63]
	v_mfma_f32_16x16x32_bf16 v[48:51], v[138:141], v[184:187], v[48:51]
	v_mfma_f32_16x16x32_bf16 v[44:47], v[146:149], v[184:187], v[44:47]
	v_mfma_f32_16x16x32_bf16 v[30:33], v[138:141], v[196:199], v[30:33]
	v_mfma_f32_16x16x32_bf16 v[26:29], v[146:149], v[196:199], v[26:29]
	v_mfma_f32_16x16x32_bf16 v[14:17], v[138:141], v[200:203], v[14:17]
	v_mfma_f32_16x16x32_bf16 v[10:13], v[146:149], v[200:203], v[10:13]
	v_mfma_f32_16x16x32_bf16 v[64:67], v[142:145], v[188:191], v[64:67]
	v_mfma_f32_16x16x32_bf16 v[60:63], v[154:157], v[188:191], v[60:63]
	v_mfma_f32_16x16x32_bf16 v[48:51], v[142:145], v[192:195], v[48:51]
	v_mfma_f32_16x16x32_bf16 v[44:47], v[154:157], v[192:195], v[44:47]
	v_mfma_f32_16x16x32_bf16 v[30:33], v[142:145], v[204:207], v[30:33]
	v_mfma_f32_16x16x32_bf16 v[26:29], v[154:157], v[204:207], v[26:29]
	v_mfma_f32_16x16x32_bf16 v[14:17], v[142:145], v[208:211], v[14:17]
	v_mfma_f32_16x16x32_bf16 v[10:13], v[154:157], v[208:211], v[10:13]
	s_setprio 0
	s_setprio 1
	v_mfma_f32_16x16x32_bf16 v[56:59], v[158:161], v[174:177], v[56:59]
	v_mfma_f32_16x16x32_bf16 v[52:55], v[166:169], v[174:177], v[52:55]
	v_mfma_f32_16x16x32_bf16 v[40:43], v[158:161], v[184:187], v[40:43]
	v_mfma_f32_16x16x32_bf16 v[36:39], v[166:169], v[184:187], v[36:39]
	v_mfma_f32_16x16x32_bf16 v[22:25], v[158:161], v[196:199], v[22:25]
	v_mfma_f32_16x16x32_bf16 v[18:21], v[166:169], v[196:199], v[18:21]
	v_mfma_f32_16x16x32_bf16 v[6:9], v[158:161], v[200:203], v[6:9]
	v_mfma_f32_16x16x32_bf16 v[2:5], v[166:169], v[200:203], v[2:5]
	v_mfma_f32_16x16x32_bf16 v[56:59], v[162:165], v[188:191], v[56:59]
	v_mfma_f32_16x16x32_bf16 v[52:55], v[170:173], v[188:191], v[52:55]
	v_mfma_f32_16x16x32_bf16 v[40:43], v[162:165], v[192:195], v[40:43]
	v_mfma_f32_16x16x32_bf16 v[36:39], v[170:173], v[192:195], v[36:39]
	v_mfma_f32_16x16x32_bf16 v[22:25], v[162:165], v[204:207], v[22:25]
	v_mfma_f32_16x16x32_bf16 v[18:21], v[170:173], v[204:207], v[18:21]
	v_mfma_f32_16x16x32_bf16 v[6:9], v[162:165], v[208:211], v[6:9]
	v_mfma_f32_16x16x32_bf16 v[2:5], v[170:173], v[208:211], v[2:5]
	s_setprio 0
	s_barrier
	s_add_i32 s25, 0, 0x18000
	s_add_i32 s34, 0, 0x1c000
	ds_read_b128 v[138:141], v1 offset:32768
	ds_read_b128 v[142:145], v150 offset:32768
	ds_read_b128 v[146:149], v1 offset:34816
	ds_read_b128 v[154:157], v150 offset:34816
	ds_read_b128 v[158:161], v1 offset:49152
	ds_read_b128 v[162:165], v150 offset:49152
	ds_read_b128 v[166:169], v1 offset:51200
	ds_read_b128 v[170:173], v150 offset:51200
	s_add_u32 s30, s44, 0x80000
	s_addc_u32 s31, s45, 0
	s_mov_b32 m0, s48
	ds_read_b128 v[174:177], v151 offset:32768
	ds_read_b128 v[184:187], v151 offset:34816
	ds_read_b128 v[188:191], v152 offset:32768
	ds_read_b128 v[192:195], v152 offset:34816
	ds_read_b128 v[196:199], v151 offset:36864
	ds_read_b128 v[200:203], v151 offset:38912
	ds_read_b128 v[204:207], v152 offset:36864
	ds_read_b128 v[208:211], v152 offset:38912
	global_load_lds_dwordx4 v136, s[30:31]
	s_mov_b32 m0, s49
	s_nop 0
	global_load_lds_dwordx4 v134, s[30:31]
	s_waitcnt vmcnt(8)
	s_waitcnt lgkmcnt(0)
	s_barrier
	s_setprio 1
	v_mfma_f32_16x16x32_bf16 v[128:131], v[138:141], v[174:177], v[128:131]
	v_mfma_f32_16x16x32_bf16 v[124:127], v[146:149], v[174:177], v[124:127]
	v_mfma_f32_16x16x32_bf16 v[112:115], v[138:141], v[184:187], v[112:115]
	v_mfma_f32_16x16x32_bf16 v[108:111], v[146:149], v[184:187], v[108:111]
	v_mfma_f32_16x16x32_bf16 v[96:99], v[138:141], v[196:199], v[96:99]
	v_mfma_f32_16x16x32_bf16 v[92:95], v[146:149], v[196:199], v[92:95]
	v_mfma_f32_16x16x32_bf16 v[80:83], v[138:141], v[200:203], v[80:83]
	v_mfma_f32_16x16x32_bf16 v[76:79], v[146:149], v[200:203], v[76:79]
	v_mfma_f32_16x16x32_bf16 v[128:131], v[142:145], v[188:191], v[128:131]
	v_mfma_f32_16x16x32_bf16 v[124:127], v[154:157], v[188:191], v[124:127]
	v_mfma_f32_16x16x32_bf16 v[112:115], v[142:145], v[192:195], v[112:115]
	v_mfma_f32_16x16x32_bf16 v[108:111], v[154:157], v[192:195], v[108:111]
	v_mfma_f32_16x16x32_bf16 v[96:99], v[142:145], v[204:207], v[96:99]
	v_mfma_f32_16x16x32_bf16 v[92:95], v[154:157], v[204:207], v[92:95]
	v_mfma_f32_16x16x32_bf16 v[80:83], v[142:145], v[208:211], v[80:83]
	v_mfma_f32_16x16x32_bf16 v[76:79], v[154:157], v[208:211], v[76:79]
	s_setprio 0
	s_setprio 1
	v_mfma_f32_16x16x32_bf16 v[120:123], v[158:161], v[174:177], v[120:123]
	v_mfma_f32_16x16x32_bf16 v[116:119], v[166:169], v[174:177], v[116:119]
	v_mfma_f32_16x16x32_bf16 v[104:107], v[158:161], v[184:187], v[104:107]
	v_mfma_f32_16x16x32_bf16 v[100:103], v[166:169], v[184:187], v[100:103]
	v_mfma_f32_16x16x32_bf16 v[88:91], v[158:161], v[196:199], v[88:91]
	v_mfma_f32_16x16x32_bf16 v[84:87], v[166:169], v[196:199], v[84:87]
	v_mfma_f32_16x16x32_bf16 v[72:75], v[158:161], v[200:203], v[72:75]
	v_mfma_f32_16x16x32_bf16 v[68:71], v[166:169], v[200:203], v[68:71]
	v_mfma_f32_16x16x32_bf16 v[120:123], v[162:165], v[188:191], v[120:123]
	v_mfma_f32_16x16x32_bf16 v[116:119], v[170:173], v[188:191], v[116:119]
	v_mfma_f32_16x16x32_bf16 v[104:107], v[162:165], v[192:195], v[104:107]
	v_mfma_f32_16x16x32_bf16 v[100:103], v[170:173], v[192:195], v[100:103]
	v_mfma_f32_16x16x32_bf16 v[88:91], v[162:165], v[204:207], v[88:91]
	v_mfma_f32_16x16x32_bf16 v[84:87], v[170:173], v[204:207], v[84:87]
	v_mfma_f32_16x16x32_bf16 v[72:75], v[162:165], v[208:211], v[72:75]
	v_mfma_f32_16x16x32_bf16 v[68:71], v[170:173], v[208:211], v[68:71]
	s_setprio 0
	s_barrier
	s_add_i32 s25, s25, s33
	s_add_i32 m0, s25, 0xffffff80
	ds_read_b128 v[174:177], v151 offset:49152
	ds_read_b128 v[184:187], v151 offset:51200
	ds_read_b128 v[188:191], v152 offset:49152
	ds_read_b128 v[192:195], v152 offset:51200
	ds_read_b128 v[196:199], v151 offset:53248
	ds_read_b128 v[200:203], v151 offset:55296
	ds_read_b128 v[204:207], v152 offset:53248
	ds_read_b128 v[208:211], v152 offset:55296
	global_load_lds_dwordx4 v34, s[28:29] offset:128
	s_add_i32 m0, s25, 0x1f80
	s_mov_b64 s[98:99], s[28:29]
	s_add_u32 s28, s28, 0x80080
	s_addc_u32 s29, s29, 0
	s_add_i32 s25, s34, s33
	global_load_lds_dwordx4 v132, s[98:99] offset:128
	s_mov_b32 m0, s25
	s_nop 0
	global_load_lds_dwordx4 v34, s[28:29]
	s_add_i32 m0, s25, 0x2000
	s_nop 0
	global_load_lds_dwordx4 v132, s[28:29]
	s_add_i32 m0, s52, 0xffffff80
	s_nop 0
	global_load_lds_dwordx4 v136, s[44:45] offset:128
	s_add_i32 m0, s53, 0xffffff80
	s_nop 0
	global_load_lds_dwordx4 v134, s[44:45] offset:128
	s_waitcnt vmcnt(8)
	s_waitcnt lgkmcnt(0)
	s_barrier
	s_setprio 1
	v_mfma_f32_16x16x32_bf16 v[64:67], v[138:141], v[174:177], v[64:67]
	v_mfma_f32_16x16x32_bf16 v[60:63], v[146:149], v[174:177], v[60:63]
	v_mfma_f32_16x16x32_bf16 v[48:51], v[138:141], v[184:187], v[48:51]
	v_mfma_f32_16x16x32_bf16 v[44:47], v[146:149], v[184:187], v[44:47]
	v_mfma_f32_16x16x32_bf16 v[30:33], v[138:141], v[196:199], v[30:33]
	v_mfma_f32_16x16x32_bf16 v[26:29], v[146:149], v[196:199], v[26:29]
	v_mfma_f32_16x16x32_bf16 v[14:17], v[138:141], v[200:203], v[14:17]
	v_mfma_f32_16x16x32_bf16 v[10:13], v[146:149], v[200:203], v[10:13]
	v_mfma_f32_16x16x32_bf16 v[64:67], v[142:145], v[188:191], v[64:67]
	v_mfma_f32_16x16x32_bf16 v[60:63], v[154:157], v[188:191], v[60:63]
	v_mfma_f32_16x16x32_bf16 v[48:51], v[142:145], v[192:195], v[48:51]
	v_mfma_f32_16x16x32_bf16 v[44:47], v[154:157], v[192:195], v[44:47]
	v_mfma_f32_16x16x32_bf16 v[30:33], v[142:145], v[204:207], v[30:33]
	v_mfma_f32_16x16x32_bf16 v[26:29], v[154:157], v[204:207], v[26:29]
	v_mfma_f32_16x16x32_bf16 v[14:17], v[142:145], v[208:211], v[14:17]
	v_mfma_f32_16x16x32_bf16 v[10:13], v[154:157], v[208:211], v[10:13]
	s_setprio 0
	s_setprio 1
	v_mfma_f32_16x16x32_bf16 v[56:59], v[158:161], v[174:177], v[56:59]
	v_mfma_f32_16x16x32_bf16 v[52:55], v[166:169], v[174:177], v[52:55]
	v_mfma_f32_16x16x32_bf16 v[40:43], v[158:161], v[184:187], v[40:43]
	v_mfma_f32_16x16x32_bf16 v[36:39], v[166:169], v[184:187], v[36:39]
	v_mfma_f32_16x16x32_bf16 v[22:25], v[158:161], v[196:199], v[22:25]
	v_mfma_f32_16x16x32_bf16 v[18:21], v[166:169], v[196:199], v[18:21]
	v_mfma_f32_16x16x32_bf16 v[6:9], v[158:161], v[200:203], v[6:9]
	v_mfma_f32_16x16x32_bf16 v[2:5], v[166:169], v[200:203], v[2:5]
	v_mfma_f32_16x16x32_bf16 v[56:59], v[162:165], v[188:191], v[56:59]
	v_mfma_f32_16x16x32_bf16 v[52:55], v[170:173], v[188:191], v[52:55]
	v_mfma_f32_16x16x32_bf16 v[40:43], v[162:165], v[192:195], v[40:43]
	v_mfma_f32_16x16x32_bf16 v[36:39], v[170:173], v[192:195], v[36:39]
	v_mfma_f32_16x16x32_bf16 v[22:25], v[162:165], v[204:207], v[22:25]
	v_mfma_f32_16x16x32_bf16 v[18:21], v[170:173], v[204:207], v[18:21]
	v_mfma_f32_16x16x32_bf16 v[6:9], v[162:165], v[208:211], v[6:9]
	v_mfma_f32_16x16x32_bf16 v[2:5], v[170:173], v[208:211], v[2:5]
	s_setprio 0
	s_barrier
	s_add_i32 s24, s24, 2
	s_add_u32 s8, s8, 0x100
	s_addc_u32 s9, s9, 0
	s_add_u32 s21, s21, 0x100
	s_addc_u32 s23, s23, 0
	s_cmp_gt_u32 s24, 29
	s_cbranch_scc0 .LBB0_1023

.LBB0_1113:
	s_ashr_i32 s19, s18, 31
	s_lshl_b64 s[20:21], s[18:19], 20
	v_readlane_b32 s22, v254, 38
	v_readlane_b32 s23, v254, 39
	s_add_u32 s22, s22, s20
	s_addc_u32 s23, s23, s21
	s_and_b64 s[20:21], s[38:39], exec
	s_cselect_b32 s13, s23, s9
	s_cselect_b32 s19, s22, s8
	s_ashr_i32 s11, s10, 31
	s_lshl_b64 s[20:21], s[10:11], 20
	v_readlane_b32 s30, v254, 8
	v_readlane_b32 s31, v254, 9
	s_add_u32 s40, s30, s20
	s_addc_u32 s41, s31, s21
	v_mov_b32_e32 v2, v0
	s_and_b64 s[20:21], s[38:39], exec
	s_cselect_b32 s20, s41, s29
	s_cselect_b32 s21, s40, s28
	s_lshl_b32 s11, s24, 8
	v_and_or_b32 v2, v2, 63, s50
	v_or_b32_e32 v2, s11, v2
	v_ashrrev_i32_e32 v3, 31, v2
	v_readlane_b32 s24, v252, 61
	v_lshlrev_b64 v[2:3], 5, v[2:3]
	v_readlane_b32 s25, v252, 62
	s_add_u32 s8, s8, 0x80080
	s_addc_u32 s9, s9, 0
	v_lshl_add_u64 v[2:3], s[24:25], 0, v[2:3]
	global_load_dwordx4 v[116:119], v[2:3], off offset:16
	global_load_dwordx4 v[120:123], v[2:3], off
	s_add_u32 s24, s28, 0x100
	s_addc_u32 s25, s29, 0
	s_mov_b32 s30, -2
	v_readlane_b32 s57, v255, 20
	v_readlane_b32 s58, v255, 21
	v_readlane_b32 s59, v255, 22
	v_readlane_b32 s60, v255, 23
	s_mov_b64 s[62:63], 0x80
	s_add_u32 s28, s8, 0xfff80080
	s_addc_u32 s29, s9, -1
	s_add_i32 s31, 0, 0x10000
	s_cmp_eq_u32 s30, 28
	s_cselect_b32 s43, s13, s29
	s_cselect_b32 s42, s19, s28
	ds_read_b128 v[150:153], v1
	ds_read_b128 v[154:157], v146
	s_cselect_b32 s29, s20, s25
	s_cselect_b32 s28, s21, s24
	s_add_i32 s56, 0, 0x14000
	ds_read_b128 v[158:161], v1 offset:2048
	ds_read_b128 v[162:165], v146 offset:2048
	ds_read_b128 v[166:169], v1 offset:16384
	ds_read_b128 v[170:173], v146 offset:16384
	ds_read_b128 v[174:177], v1 offset:18432
	ds_read_b128 v[184:187], v146 offset:18432
	s_add_i32 m0, s34, 0xc000
	ds_read_b128 v[188:191], v147
	ds_read_b128 v[192:195], v147 offset:2048
	ds_read_b128 v[196:199], v148
	ds_read_b128 v[200:203], v148 offset:2048
	ds_read_b128 v[204:207], v147 offset:4096
	ds_read_b128 v[208:211], v147 offset:6144
	ds_read_b128 v[224:227], v148 offset:4096
	ds_read_b128 v[228:231], v148 offset:6144
	global_load_lds_dwordx4 v144, s[8:9]
	s_add_i32 m0, s34, 0xe000
	s_nop 0
	global_load_lds_dwordx4 v142, s[8:9]
	s_waitcnt vmcnt(8)
	s_waitcnt lgkmcnt(0)
	s_barrier
	s_setprio 1
	v_mfma_f32_16x16x32_bf16 v[132:135], v[150:153], v[188:191], 0
	v_mfma_f32_16x16x32_bf16 v[124:127], v[158:161], v[188:191], 0
	v_mfma_f32_16x16x32_bf16 v[108:111], v[150:153], v[192:195], 0
	v_mfma_f32_16x16x32_bf16 v[100:103], v[158:161], v[192:195], 0
	v_mfma_f32_16x16x32_bf16 v[92:95], v[150:153], v[204:207], 0
	v_mfma_f32_16x16x32_bf16 v[84:87], v[158:161], v[204:207], 0
	v_mfma_f32_16x16x32_bf16 v[76:79], v[150:153], v[208:211], 0
	v_mfma_f32_16x16x32_bf16 v[68:71], v[158:161], v[208:211], 0
	v_mfma_f32_16x16x32_bf16 v[132:135], v[154:157], v[196:199], v[132:135]
	v_mfma_f32_16x16x32_bf16 v[124:127], v[162:165], v[196:199], v[124:127]
	v_mfma_f32_16x16x32_bf16 v[108:111], v[154:157], v[200:203], v[108:111]
	v_mfma_f32_16x16x32_bf16 v[100:103], v[162:165], v[200:203], v[100:103]
	v_mfma_f32_16x16x32_bf16 v[92:95], v[154:157], v[224:227], v[92:95]
	v_mfma_f32_16x16x32_bf16 v[84:87], v[162:165], v[224:227], v[84:87]
	v_mfma_f32_16x16x32_bf16 v[76:79], v[154:157], v[228:231], v[76:79]
	v_mfma_f32_16x16x32_bf16 v[68:71], v[162:165], v[228:231], v[68:71]
	s_setprio 0
	s_setprio 1
	v_mfma_f32_16x16x32_bf16 v[136:139], v[166:169], v[188:191], 0
	v_mfma_f32_16x16x32_bf16 v[128:131], v[174:177], v[188:191], 0
	v_mfma_f32_16x16x32_bf16 v[112:115], v[166:169], v[192:195], 0
	v_mfma_f32_16x16x32_bf16 v[104:107], v[174:177], v[192:195], 0
	v_mfma_f32_16x16x32_bf16 v[96:99], v[166:169], v[204:207], 0
	v_mfma_f32_16x16x32_bf16 v[88:91], v[174:177], v[204:207], 0
	v_mfma_f32_16x16x32_bf16 v[80:83], v[166:169], v[208:211], 0
	v_mfma_f32_16x16x32_bf16 v[72:75], v[174:177], v[208:211], 0
	v_mfma_f32_16x16x32_bf16 v[136:139], v[170:173], v[196:199], v[136:139]
	v_mfma_f32_16x16x32_bf16 v[128:131], v[184:187], v[196:199], v[128:131]
	v_mfma_f32_16x16x32_bf16 v[112:115], v[170:173], v[200:203], v[112:115]
	v_mfma_f32_16x16x32_bf16 v[104:107], v[184:187], v[200:203], v[104:107]
	v_mfma_f32_16x16x32_bf16 v[96:99], v[170:173], v[224:227], v[96:99]
	v_mfma_f32_16x16x32_bf16 v[88:91], v[184:187], v[224:227], v[88:91]
	v_mfma_f32_16x16x32_bf16 v[80:83], v[170:173], v[228:231], v[80:83]
	v_mfma_f32_16x16x32_bf16 v[72:75], v[184:187], v[228:231], v[72:75]
	s_setprio 0
	s_barrier
	s_add_i32 s31, s31, s33
	s_mov_b32 m0, s31
	ds_read_b128 v[188:191], v147 offset:16384
	ds_read_b128 v[192:195], v147 offset:18432
	ds_read_b128 v[196:199], v148 offset:16384
	ds_read_b128 v[200:203], v148 offset:18432
	ds_read_b128 v[204:207], v147 offset:20480
	ds_read_b128 v[208:211], v147 offset:22528
	ds_read_b128 v[224:227], v148 offset:20480
	ds_read_b128 v[228:231], v148 offset:22528
	global_load_lds_dwordx4 v34, s[28:29]
	s_add_i32 m0, s31, 0x2000
	s_add_u32 s54, s28, 0x80000
	s_addc_u32 s55, s29, 0
	s_add_i32 s31, s56, s33
	global_load_lds_dwordx4 v140, s[28:29]
	s_mov_b32 m0, s31
	s_nop 0
	global_load_lds_dwordx4 v34, s[54:55]
	s_add_i32 m0, s31, 0x2000
	s_nop 0
	global_load_lds_dwordx4 v140, s[54:55]
	s_mov_b32 m0, s34
	s_nop 0
	global_load_lds_dwordx4 v144, s[42:43]
	s_mov_b32 m0, s35
	s_nop 0
	global_load_lds_dwordx4 v142, s[42:43]
	s_waitcnt vmcnt(8)
	s_waitcnt lgkmcnt(0)
	s_barrier
	s_setprio 1
	v_mfma_f32_16x16x32_bf16 v[60:63], v[150:153], v[188:191], 0
	v_mfma_f32_16x16x32_bf16 v[52:55], v[158:161], v[188:191], 0
	v_mfma_f32_16x16x32_bf16 v[44:47], v[150:153], v[192:195], 0
	v_mfma_f32_16x16x32_bf16 v[36:39], v[158:161], v[192:195], 0
	v_mfma_f32_16x16x32_bf16 v[26:29], v[150:153], v[204:207], 0
	v_mfma_f32_16x16x32_bf16 v[18:21], v[158:161], v[204:207], 0
	v_mfma_f32_16x16x32_bf16 v[10:13], v[150:153], v[208:211], 0
	v_mfma_f32_16x16x32_bf16 v[6:9], v[158:161], v[208:211], 0
	v_mfma_f32_16x16x32_bf16 v[60:63], v[154:157], v[196:199], v[60:63]
	v_mfma_f32_16x16x32_bf16 v[52:55], v[162:165], v[196:199], v[52:55]
	v_mfma_f32_16x16x32_bf16 v[44:47], v[154:157], v[200:203], v[44:47]
	v_mfma_f32_16x16x32_bf16 v[36:39], v[162:165], v[200:203], v[36:39]
	v_mfma_f32_16x16x32_bf16 v[26:29], v[154:157], v[224:227], v[26:29]
	v_mfma_f32_16x16x32_bf16 v[18:21], v[162:165], v[224:227], v[18:21]
	v_mfma_f32_16x16x32_bf16 v[10:13], v[154:157], v[228:231], v[10:13]
	v_mfma_f32_16x16x32_bf16 v[6:9], v[162:165], v[228:231], v[6:9]
	s_setprio 0
	s_setprio 1
	v_mfma_f32_16x16x32_bf16 v[64:67], v[166:169], v[188:191], 0
	v_mfma_f32_16x16x32_bf16 v[56:59], v[174:177], v[188:191], 0
	v_mfma_f32_16x16x32_bf16 v[48:51], v[166:169], v[192:195], 0
	v_mfma_f32_16x16x32_bf16 v[40:43], v[174:177], v[192:195], 0
	v_mfma_f32_16x16x32_bf16 v[30:33], v[166:169], v[204:207], 0
	v_mfma_f32_16x16x32_bf16 v[22:25], v[174:177], v[204:207], 0
	v_mfma_f32_16x16x32_bf16 v[14:17], v[166:169], v[208:211], 0
	v_mfma_f32_16x16x32_bf16 v[2:5], v[174:177], v[208:211], 0
	v_mfma_f32_16x16x32_bf16 v[64:67], v[170:173], v[196:199], v[64:67]
	v_mfma_f32_16x16x32_bf16 v[56:59], v[184:187], v[196:199], v[56:59]
	v_mfma_f32_16x16x32_bf16 v[48:51], v[170:173], v[200:203], v[48:51]
	v_mfma_f32_16x16x32_bf16 v[40:43], v[184:187], v[200:203], v[40:43]
	v_mfma_f32_16x16x32_bf16 v[30:33], v[170:173], v[224:227], v[30:33]
	v_mfma_f32_16x16x32_bf16 v[22:25], v[184:187], v[224:227], v[22:25]
	v_mfma_f32_16x16x32_bf16 v[14:17], v[170:173], v[228:231], v[14:17]
	v_mfma_f32_16x16x32_bf16 v[2:5], v[184:187], v[228:231], v[2:5]
	s_setprio 0
	s_barrier
	s_add_i32 s31, 0, 0x18000
	ds_read_b128 v[150:153], v1 offset:32768
	ds_read_b128 v[154:157], v146 offset:32768
	s_add_i32 s54, 0, 0x1c000
	ds_read_b128 v[158:161], v1 offset:34816
	ds_read_b128 v[162:165], v146 offset:34816
	ds_read_b128 v[166:169], v1 offset:49152
	ds_read_b128 v[170:173], v146 offset:49152
	ds_read_b128 v[174:177], v1 offset:51200
	ds_read_b128 v[184:187], v146 offset:51200
	s_mov_b64 s[100:101], s[42:43]
	s_add_u32 s42, s42, 0x80000
	s_addc_u32 s43, s43, 0
	s_mov_b32 m0, s44
	ds_read_b128 v[188:191], v147 offset:32768
	ds_read_b128 v[192:195], v147 offset:34816
	ds_read_b128 v[196:199], v148 offset:32768
	ds_read_b128 v[200:203], v148 offset:34816
	ds_read_b128 v[204:207], v147 offset:36864
	ds_read_b128 v[208:211], v147 offset:38912
	ds_read_b128 v[224:227], v148 offset:36864
	ds_read_b128 v[228:231], v148 offset:38912
	global_load_lds_dwordx4 v144, s[42:43]
	s_mov_b32 m0, s45
	s_nop 0
	global_load_lds_dwordx4 v142, s[42:43]
	s_waitcnt vmcnt(8)
	s_waitcnt lgkmcnt(0)
	s_barrier
	s_setprio 1
	v_mfma_f32_16x16x32_bf16 v[132:135], v[150:153], v[188:191], v[132:135]
	v_mfma_f32_16x16x32_bf16 v[124:127], v[158:161], v[188:191], v[124:127]
	v_mfma_f32_16x16x32_bf16 v[108:111], v[150:153], v[192:195], v[108:111]
	v_mfma_f32_16x16x32_bf16 v[100:103], v[158:161], v[192:195], v[100:103]
	v_mfma_f32_16x16x32_bf16 v[92:95], v[150:153], v[204:207], v[92:95]
	v_mfma_f32_16x16x32_bf16 v[84:87], v[158:161], v[204:207], v[84:87]
	v_mfma_f32_16x16x32_bf16 v[76:79], v[150:153], v[208:211], v[76:79]
	v_mfma_f32_16x16x32_bf16 v[68:71], v[158:161], v[208:211], v[68:71]
	v_mfma_f32_16x16x32_bf16 v[132:135], v[154:157], v[196:199], v[132:135]
	v_mfma_f32_16x16x32_bf16 v[124:127], v[162:165], v[196:199], v[124:127]
	v_mfma_f32_16x16x32_bf16 v[108:111], v[154:157], v[200:203], v[108:111]
	v_mfma_f32_16x16x32_bf16 v[100:103], v[162:165], v[200:203], v[100:103]
	v_mfma_f32_16x16x32_bf16 v[92:95], v[154:157], v[224:227], v[92:95]
	v_mfma_f32_16x16x32_bf16 v[84:87], v[162:165], v[224:227], v[84:87]
	v_mfma_f32_16x16x32_bf16 v[76:79], v[154:157], v[228:231], v[76:79]
	v_mfma_f32_16x16x32_bf16 v[68:71], v[162:165], v[228:231], v[68:71]
	s_setprio 0
	s_setprio 1
	v_mfma_f32_16x16x32_bf16 v[136:139], v[166:169], v[188:191], v[136:139]
	v_mfma_f32_16x16x32_bf16 v[128:131], v[174:177], v[188:191], v[128:131]
	v_mfma_f32_16x16x32_bf16 v[112:115], v[166:169], v[192:195], v[112:115]
	v_mfma_f32_16x16x32_bf16 v[104:107], v[174:177], v[192:195], v[104:107]
	v_mfma_f32_16x16x32_bf16 v[96:99], v[166:169], v[204:207], v[96:99]
	v_mfma_f32_16x16x32_bf16 v[88:91], v[174:177], v[204:207], v[88:91]
	v_mfma_f32_16x16x32_bf16 v[80:83], v[166:169], v[208:211], v[80:83]
	v_mfma_f32_16x16x32_bf16 v[72:75], v[174:177], v[208:211], v[72:75]
	v_mfma_f32_16x16x32_bf16 v[136:139], v[170:173], v[196:199], v[136:139]
	v_mfma_f32_16x16x32_bf16 v[128:131], v[184:187], v[196:199], v[128:131]
	v_mfma_f32_16x16x32_bf16 v[112:115], v[170:173], v[200:203], v[112:115]
	v_mfma_f32_16x16x32_bf16 v[104:107], v[184:187], v[200:203], v[104:107]
	v_mfma_f32_16x16x32_bf16 v[96:99], v[170:173], v[224:227], v[96:99]
	v_mfma_f32_16x16x32_bf16 v[88:91], v[184:187], v[224:227], v[88:91]
	v_mfma_f32_16x16x32_bf16 v[80:83], v[170:173], v[228:231], v[80:83]
	v_mfma_f32_16x16x32_bf16 v[72:75], v[184:187], v[228:231], v[72:75]
	s_setprio 0
	s_barrier
	s_add_i32 s31, s31, s33
	s_add_i32 m0, s31, 0xffffff80
	ds_read_b128 v[188:191], v147 offset:49152
	ds_read_b128 v[192:195], v147 offset:51200
	ds_read_b128 v[196:199], v148 offset:49152
	ds_read_b128 v[200:203], v148 offset:51200
	ds_read_b128 v[204:207], v147 offset:53248
	ds_read_b128 v[208:211], v147 offset:55296
	ds_read_b128 v[224:227], v148 offset:53248
	ds_read_b128 v[228:231], v148 offset:55296
	global_load_lds_dwordx4 v34, s[28:29] offset:128
	s_add_i32 m0, s31, 0x1f80
	s_mov_b64 s[98:99], s[28:29]
	s_add_u32 s28, s28, 0x80080
	s_addc_u32 s29, s29, 0
	s_add_i32 s31, s54, s33
	global_load_lds_dwordx4 v140, s[98:99] offset:128
	s_mov_b32 m0, s31
	s_nop 0
	global_load_lds_dwordx4 v34, s[28:29]
	s_add_i32 m0, s31, 0x2000
	s_nop 0
	global_load_lds_dwordx4 v140, s[28:29]
	s_add_i32 m0, s48, 0xffffff80
	s_nop 0
	global_load_lds_dwordx4 v144, s[100:101] offset:128
	s_add_i32 m0, s49, 0xffffff80
	s_nop 0
	global_load_lds_dwordx4 v142, s[100:101] offset:128
	s_waitcnt vmcnt(8)
	s_waitcnt lgkmcnt(0)
	s_barrier
	s_setprio 1
	v_mfma_f32_16x16x32_bf16 v[60:63], v[150:153], v[188:191], v[60:63]
	v_mfma_f32_16x16x32_bf16 v[52:55], v[158:161], v[188:191], v[52:55]
	v_mfma_f32_16x16x32_bf16 v[44:47], v[150:153], v[192:195], v[44:47]
	v_mfma_f32_16x16x32_bf16 v[36:39], v[158:161], v[192:195], v[36:39]
	v_mfma_f32_16x16x32_bf16 v[26:29], v[150:153], v[204:207], v[26:29]
	v_mfma_f32_16x16x32_bf16 v[18:21], v[158:161], v[204:207], v[18:21]
	v_mfma_f32_16x16x32_bf16 v[10:13], v[150:153], v[208:211], v[10:13]
	v_mfma_f32_16x16x32_bf16 v[6:9], v[158:161], v[208:211], v[6:9]
	v_mfma_f32_16x16x32_bf16 v[60:63], v[154:157], v[196:199], v[60:63]
	v_mfma_f32_16x16x32_bf16 v[52:55], v[162:165], v[196:199], v[52:55]
	v_mfma_f32_16x16x32_bf16 v[44:47], v[154:157], v[200:203], v[44:47]
	v_mfma_f32_16x16x32_bf16 v[36:39], v[162:165], v[200:203], v[36:39]
	v_mfma_f32_16x16x32_bf16 v[26:29], v[154:157], v[224:227], v[26:29]
	v_mfma_f32_16x16x32_bf16 v[18:21], v[162:165], v[224:227], v[18:21]
	v_mfma_f32_16x16x32_bf16 v[10:13], v[154:157], v[228:231], v[10:13]
	v_mfma_f32_16x16x32_bf16 v[6:9], v[162:165], v[228:231], v[6:9]
	s_setprio 0
	s_setprio 1
	v_mfma_f32_16x16x32_bf16 v[64:67], v[166:169], v[188:191], v[64:67]
	v_mfma_f32_16x16x32_bf16 v[56:59], v[174:177], v[188:191], v[56:59]
	v_mfma_f32_16x16x32_bf16 v[48:51], v[166:169], v[192:195], v[48:51]
	v_mfma_f32_16x16x32_bf16 v[40:43], v[174:177], v[192:195], v[40:43]
	v_mfma_f32_16x16x32_bf16 v[30:33], v[166:169], v[204:207], v[30:33]
	v_mfma_f32_16x16x32_bf16 v[22:25], v[174:177], v[204:207], v[22:25]
	v_mfma_f32_16x16x32_bf16 v[14:17], v[166:169], v[208:211], v[14:17]
	v_mfma_f32_16x16x32_bf16 v[2:5], v[174:177], v[208:211], v[2:5]
	v_mfma_f32_16x16x32_bf16 v[64:67], v[170:173], v[196:199], v[64:67]
	v_mfma_f32_16x16x32_bf16 v[56:59], v[184:187], v[196:199], v[56:59]
	v_mfma_f32_16x16x32_bf16 v[48:51], v[170:173], v[200:203], v[48:51]
	v_mfma_f32_16x16x32_bf16 v[40:43], v[184:187], v[200:203], v[40:43]
	v_mfma_f32_16x16x32_bf16 v[30:33], v[170:173], v[224:227], v[30:33]
	v_mfma_f32_16x16x32_bf16 v[22:25], v[184:187], v[224:227], v[22:25]
	v_mfma_f32_16x16x32_bf16 v[14:17], v[170:173], v[228:231], v[14:17]
	v_mfma_f32_16x16x32_bf16 v[2:5], v[184:187], v[228:231], v[2:5]
	s_setprio 0
	s_barrier
	s_add_i32 s30, s30, 2
	s_add_u32 s8, s8, 0x100
	s_addc_u32 s9, s9, 0
	s_add_u32 s24, s24, 0x100
	s_addc_u32 s25, s25, 0
	s_cmp_gt_u32 s30, 29
	s_cbranch_scc1 .Lpeel_done_P6
.LBB0_1114:
	s_add_u32 s28, s8, 0xfff80080
	s_addc_u32 s29, s9, -1
	s_add_i32 s31, 0, 0x10000
	s_cmp_eq_u32 s30, 28
	s_cselect_b32 s43, s13, s29
	s_cselect_b32 s42, s19, s28
	ds_read_b128 v[150:153], v1
	ds_read_b128 v[154:157], v146
	s_cselect_b32 s29, s20, s25
	s_cselect_b32 s28, s21, s24
	s_add_i32 s56, 0, 0x14000
	ds_read_b128 v[158:161], v1 offset:2048
	ds_read_b128 v[162:165], v146 offset:2048
	ds_read_b128 v[166:169], v1 offset:16384
	ds_read_b128 v[170:173], v146 offset:16384
	ds_read_b128 v[174:177], v1 offset:18432
	ds_read_b128 v[184:187], v146 offset:18432
	s_add_i32 m0, s34, 0xc000
	ds_read_b128 v[188:191], v147
	ds_read_b128 v[192:195], v147 offset:2048
	ds_read_b128 v[196:199], v148
	ds_read_b128 v[200:203], v148 offset:2048
	ds_read_b128 v[204:207], v147 offset:4096
	ds_read_b128 v[208:211], v147 offset:6144
	ds_read_b128 v[224:227], v148 offset:4096
	ds_read_b128 v[228:231], v148 offset:6144
	global_load_lds_dwordx4 v144, s[8:9]
	s_add_i32 m0, s34, 0xe000
	s_nop 0
	global_load_lds_dwordx4 v142, s[8:9]
	s_waitcnt vmcnt(8)
	s_waitcnt lgkmcnt(0)
	s_barrier
	s_setprio 1
	v_mfma_f32_16x16x32_bf16 v[132:135], v[150:153], v[188:191], v[132:135]
	v_mfma_f32_16x16x32_bf16 v[124:127], v[158:161], v[188:191], v[124:127]
	v_mfma_f32_16x16x32_bf16 v[108:111], v[150:153], v[192:195], v[108:111]
	v_mfma_f32_16x16x32_bf16 v[100:103], v[158:161], v[192:195], v[100:103]
	v_mfma_f32_16x16x32_bf16 v[92:95], v[150:153], v[204:207], v[92:95]
	v_mfma_f32_16x16x32_bf16 v[84:87], v[158:161], v[204:207], v[84:87]
	v_mfma_f32_16x16x32_bf16 v[76:79], v[150:153], v[208:211], v[76:79]
	v_mfma_f32_16x16x32_bf16 v[68:71], v[158:161], v[208:211], v[68:71]
	v_mfma_f32_16x16x32_bf16 v[132:135], v[154:157], v[196:199], v[132:135]
	v_mfma_f32_16x16x32_bf16 v[124:127], v[162:165], v[196:199], v[124:127]
	v_mfma_f32_16x16x32_bf16 v[108:111], v[154:157], v[200:203], v[108:111]
	v_mfma_f32_16x16x32_bf16 v[100:103], v[162:165], v[200:203], v[100:103]
	v_mfma_f32_16x16x32_bf16 v[92:95], v[154:157], v[224:227], v[92:95]
	v_mfma_f32_16x16x32_bf16 v[84:87], v[162:165], v[224:227], v[84:87]
	v_mfma_f32_16x16x32_bf16 v[76:79], v[154:157], v[228:231], v[76:79]
	v_mfma_f32_16x16x32_bf16 v[68:71], v[162:165], v[228:231], v[68:71]
	s_setprio 0
	s_setprio 1
	v_mfma_f32_16x16x32_bf16 v[136:139], v[166:169], v[188:191], v[136:139]
	v_mfma_f32_16x16x32_bf16 v[128:131], v[174:177], v[188:191], v[128:131]
	v_mfma_f32_16x16x32_bf16 v[112:115], v[166:169], v[192:195], v[112:115]
	v_mfma_f32_16x16x32_bf16 v[104:107], v[174:177], v[192:195], v[104:107]
	v_mfma_f32_16x16x32_bf16 v[96:99], v[166:169], v[204:207], v[96:99]
	v_mfma_f32_16x16x32_bf16 v[88:91], v[174:177], v[204:207], v[88:91]
	v_mfma_f32_16x16x32_bf16 v[80:83], v[166:169], v[208:211], v[80:83]
	v_mfma_f32_16x16x32_bf16 v[72:75], v[174:177], v[208:211], v[72:75]
	v_mfma_f32_16x16x32_bf16 v[136:139], v[170:173], v[196:199], v[136:139]
	v_mfma_f32_16x16x32_bf16 v[128:131], v[184:187], v[196:199], v[128:131]
	v_mfma_f32_16x16x32_bf16 v[112:115], v[170:173], v[200:203], v[112:115]
	v_mfma_f32_16x16x32_bf16 v[104:107], v[184:187], v[200:203], v[104:107]
	v_mfma_f32_16x16x32_bf16 v[96:99], v[170:173], v[224:227], v[96:99]
	v_mfma_f32_16x16x32_bf16 v[88:91], v[184:187], v[224:227], v[88:91]
	v_mfma_f32_16x16x32_bf16 v[80:83], v[170:173], v[228:231], v[80:83]
	v_mfma_f32_16x16x32_bf16 v[72:75], v[184:187], v[228:231], v[72:75]
	s_setprio 0
	s_barrier
	s_add_i32 s31, s31, s33
	s_mov_b32 m0, s31
	ds_read_b128 v[188:191], v147 offset:16384
	ds_read_b128 v[192:195], v147 offset:18432
	ds_read_b128 v[196:199], v148 offset:16384
	ds_read_b128 v[200:203], v148 offset:18432
	ds_read_b128 v[204:207], v147 offset:20480
	ds_read_b128 v[208:211], v147 offset:22528
	ds_read_b128 v[224:227], v148 offset:20480
	ds_read_b128 v[228:231], v148 offset:22528
	global_load_lds_dwordx4 v34, s[28:29]
	s_add_i32 m0, s31, 0x2000
	s_add_u32 s54, s28, 0x80000
	s_addc_u32 s55, s29, 0
	s_add_i32 s31, s56, s33
	global_load_lds_dwordx4 v140, s[28:29]
	s_mov_b32 m0, s31
	s_nop 0
	global_load_lds_dwordx4 v34, s[54:55]
	s_add_i32 m0, s31, 0x2000
	s_nop 0
	global_load_lds_dwordx4 v140, s[54:55]
	s_mov_b32 m0, s34
	s_nop 0
	global_load_lds_dwordx4 v144, s[42:43]
	s_mov_b32 m0, s35
	s_nop 0
	global_load_lds_dwordx4 v142, s[42:43]
	s_waitcnt vmcnt(8)
	s_waitcnt lgkmcnt(0)
	s_barrier
	s_setprio 1
	v_mfma_f32_16x16x32_bf16 v[60:63], v[150:153], v[188:191], v[60:63]
	v_mfma_f32_16x16x32_bf16 v[52:55], v[158:161], v[188:191], v[52:55]
	v_mfma_f32_16x16x32_bf16 v[44:47], v[150:153], v[192:195], v[44:47]
	v_mfma_f32_16x16x32_bf16 v[36:39], v[158:161], v[192:195], v[36:39]
	v_mfma_f32_16x16x32_bf16 v[26:29], v[150:153], v[204:207], v[26:29]
	v_mfma_f32_16x16x32_bf16 v[18:21], v[158:161], v[204:207], v[18:21]
	v_mfma_f32_16x16x32_bf16 v[10:13], v[150:153], v[208:211], v[10:13]
	v_mfma_f32_16x16x32_bf16 v[6:9], v[158:161], v[208:211], v[6:9]
	v_mfma_f32_16x16x32_bf16 v[60:63], v[154:157], v[196:199], v[60:63]
	v_mfma_f32_16x16x32_bf16 v[52:55], v[162:165], v[196:199], v[52:55]
	v_mfma_f32_16x16x32_bf16 v[44:47], v[154:157], v[200:203], v[44:47]
	v_mfma_f32_16x16x32_bf16 v[36:39], v[162:165], v[200:203], v[36:39]
	v_mfma_f32_16x16x32_bf16 v[26:29], v[154:157], v[224:227], v[26:29]
	v_mfma_f32_16x16x32_bf16 v[18:21], v[162:165], v[224:227], v[18:21]
	v_mfma_f32_16x16x32_bf16 v[10:13], v[154:157], v[228:231], v[10:13]
	v_mfma_f32_16x16x32_bf16 v[6:9], v[162:165], v[228:231], v[6:9]
	s_setprio 0
	s_setprio 1
	v_mfma_f32_16x16x32_bf16 v[64:67], v[166:169], v[188:191], v[64:67]
	v_mfma_f32_16x16x32_bf16 v[56:59], v[174:177], v[188:191], v[56:59]
	v_mfma_f32_16x16x32_bf16 v[48:51], v[166:169], v[192:195], v[48:51]
	v_mfma_f32_16x16x32_bf16 v[40:43], v[174:177], v[192:195], v[40:43]
	v_mfma_f32_16x16x32_bf16 v[30:33], v[166:169], v[204:207], v[30:33]
	v_mfma_f32_16x16x32_bf16 v[22:25], v[174:177], v[204:207], v[22:25]
	v_mfma_f32_16x16x32_bf16 v[14:17], v[166:169], v[208:211], v[14:17]
	v_mfma_f32_16x16x32_bf16 v[2:5], v[174:177], v[208:211], v[2:5]
	v_mfma_f32_16x16x32_bf16 v[64:67], v[170:173], v[196:199], v[64:67]
	v_mfma_f32_16x16x32_bf16 v[56:59], v[184:187], v[196:199], v[56:59]
	v_mfma_f32_16x16x32_bf16 v[48:51], v[170:173], v[200:203], v[48:51]
	v_mfma_f32_16x16x32_bf16 v[40:43], v[184:187], v[200:203], v[40:43]
	v_mfma_f32_16x16x32_bf16 v[30:33], v[170:173], v[224:227], v[30:33]
	v_mfma_f32_16x16x32_bf16 v[22:25], v[184:187], v[224:227], v[22:25]
	v_mfma_f32_16x16x32_bf16 v[14:17], v[170:173], v[228:231], v[14:17]
	v_mfma_f32_16x16x32_bf16 v[2:5], v[184:187], v[228:231], v[2:5]
	s_setprio 0
	s_barrier
	s_add_i32 s31, 0, 0x18000
	ds_read_b128 v[150:153], v1 offset:32768
	ds_read_b128 v[154:157], v146 offset:32768
	s_add_i32 s54, 0, 0x1c000
	ds_read_b128 v[158:161], v1 offset:34816
	ds_read_b128 v[162:165], v146 offset:34816
	ds_read_b128 v[166:169], v1 offset:49152
	ds_read_b128 v[170:173], v146 offset:49152
	ds_read_b128 v[174:177], v1 offset:51200
	ds_read_b128 v[184:187], v146 offset:51200
	s_mov_b64 s[100:101], s[42:43]
	s_add_u32 s42, s42, 0x80000
	s_addc_u32 s43, s43, 0
	s_mov_b32 m0, s44
	ds_read_b128 v[188:191], v147 offset:32768
	ds_read_b128 v[192:195], v147 offset:34816
	ds_read_b128 v[196:199], v148 offset:32768
	ds_read_b128 v[200:203], v148 offset:34816
	ds_read_b128 v[204:207], v147 offset:36864
	ds_read_b128 v[208:211], v147 offset:38912
	ds_read_b128 v[224:227], v148 offset:36864
	ds_read_b128 v[228:231], v148 offset:38912
	global_load_lds_dwordx4 v144, s[42:43]
	s_mov_b32 m0, s45
	s_nop 0
	global_load_lds_dwordx4 v142, s[42:43]
	s_waitcnt vmcnt(8)
	s_waitcnt lgkmcnt(0)
	s_barrier
	s_setprio 1
	v_mfma_f32_16x16x32_bf16 v[132:135], v[150:153], v[188:191], v[132:135]
	v_mfma_f32_16x16x32_bf16 v[124:127], v[158:161], v[188:191], v[124:127]
	v_mfma_f32_16x16x32_bf16 v[108:111], v[150:153], v[192:195], v[108:111]
	v_mfma_f32_16x16x32_bf16 v[100:103], v[158:161], v[192:195], v[100:103]
	v_mfma_f32_16x16x32_bf16 v[92:95], v[150:153], v[204:207], v[92:95]
	v_mfma_f32_16x16x32_bf16 v[84:87], v[158:161], v[204:207], v[84:87]
	v_mfma_f32_16x16x32_bf16 v[76:79], v[150:153], v[208:211], v[76:79]
	v_mfma_f32_16x16x32_bf16 v[68:71], v[158:161], v[208:211], v[68:71]
	v_mfma_f32_16x16x32_bf16 v[132:135], v[154:157], v[196:199], v[132:135]
	v_mfma_f32_16x16x32_bf16 v[124:127], v[162:165], v[196:199], v[124:127]
	v_mfma_f32_16x16x32_bf16 v[108:111], v[154:157], v[200:203], v[108:111]
	v_mfma_f32_16x16x32_bf16 v[100:103], v[162:165], v[200:203], v[100:103]
	v_mfma_f32_16x16x32_bf16 v[92:95], v[154:157], v[224:227], v[92:95]
	v_mfma_f32_16x16x32_bf16 v[84:87], v[162:165], v[224:227], v[84:87]
	v_mfma_f32_16x16x32_bf16 v[76:79], v[154:157], v[228:231], v[76:79]
	v_mfma_f32_16x16x32_bf16 v[68:71], v[162:165], v[228:231], v[68:71]
	s_setprio 0
	s_setprio 1
	v_mfma_f32_16x16x32_bf16 v[136:139], v[166:169], v[188:191], v[136:139]
	v_mfma_f32_16x16x32_bf16 v[128:131], v[174:177], v[188:191], v[128:131]
	v_mfma_f32_16x16x32_bf16 v[112:115], v[166:169], v[192:195], v[112:115]
	v_mfma_f32_16x16x32_bf16 v[104:107], v[174:177], v[192:195], v[104:107]
	v_mfma_f32_16x16x32_bf16 v[96:99], v[166:169], v[204:207], v[96:99]
	v_mfma_f32_16x16x32_bf16 v[88:91], v[174:177], v[204:207], v[88:91]
	v_mfma_f32_16x16x32_bf16 v[80:83], v[166:169], v[208:211], v[80:83]
	v_mfma_f32_16x16x32_bf16 v[72:75], v[174:177], v[208:211], v[72:75]
	v_mfma_f32_16x16x32_bf16 v[136:139], v[170:173], v[196:199], v[136:139]
	v_mfma_f32_16x16x32_bf16 v[128:131], v[184:187], v[196:199], v[128:131]
	v_mfma_f32_16x16x32_bf16 v[112:115], v[170:173], v[200:203], v[112:115]
	v_mfma_f32_16x16x32_bf16 v[104:107], v[184:187], v[200:203], v[104:107]
	v_mfma_f32_16x16x32_bf16 v[96:99], v[170:173], v[224:227], v[96:99]
	v_mfma_f32_16x16x32_bf16 v[88:91], v[184:187], v[224:227], v[88:91]
	v_mfma_f32_16x16x32_bf16 v[80:83], v[170:173], v[228:231], v[80:83]
	v_mfma_f32_16x16x32_bf16 v[72:75], v[184:187], v[228:231], v[72:75]
	s_setprio 0
	s_barrier
	s_add_i32 s31, s31, s33
	s_add_i32 m0, s31, 0xffffff80
	ds_read_b128 v[188:191], v147 offset:49152
	ds_read_b128 v[192:195], v147 offset:51200
	ds_read_b128 v[196:199], v148 offset:49152
	ds_read_b128 v[200:203], v148 offset:51200
	ds_read_b128 v[204:207], v147 offset:53248
	ds_read_b128 v[208:211], v147 offset:55296
	ds_read_b128 v[224:227], v148 offset:53248
	ds_read_b128 v[228:231], v148 offset:55296
	global_load_lds_dwordx4 v34, s[28:29] offset:128
	s_add_i32 m0, s31, 0x1f80
	s_mov_b64 s[98:99], s[28:29]
	s_add_u32 s28, s28, 0x80080
	s_addc_u32 s29, s29, 0
	s_add_i32 s31, s54, s33
	global_load_lds_dwordx4 v140, s[98:99] offset:128
	s_mov_b32 m0, s31
	s_nop 0
	global_load_lds_dwordx4 v34, s[28:29]
	s_add_i32 m0, s31, 0x2000
	s_nop 0
	global_load_lds_dwordx4 v140, s[28:29]
	s_add_i32 m0, s48, 0xffffff80
	s_nop 0
	global_load_lds_dwordx4 v144, s[100:101] offset:128
	s_add_i32 m0, s49, 0xffffff80
	s_nop 0
	global_load_lds_dwordx4 v142, s[100:101] offset:128
	s_waitcnt vmcnt(8)
	s_waitcnt lgkmcnt(0)
	s_barrier
	s_setprio 1
	v_mfma_f32_16x16x32_bf16 v[60:63], v[150:153], v[188:191], v[60:63]
	v_mfma_f32_16x16x32_bf16 v[52:55], v[158:161], v[188:191], v[52:55]
	v_mfma_f32_16x16x32_bf16 v[44:47], v[150:153], v[192:195], v[44:47]
	v_mfma_f32_16x16x32_bf16 v[36:39], v[158:161], v[192:195], v[36:39]
	v_mfma_f32_16x16x32_bf16 v[26:29], v[150:153], v[204:207], v[26:29]
	v_mfma_f32_16x16x32_bf16 v[18:21], v[158:161], v[204:207], v[18:21]
	v_mfma_f32_16x16x32_bf16 v[10:13], v[150:153], v[208:211], v[10:13]
	v_mfma_f32_16x16x32_bf16 v[6:9], v[158:161], v[208:211], v[6:9]
	v_mfma_f32_16x16x32_bf16 v[60:63], v[154:157], v[196:199], v[60:63]
	v_mfma_f32_16x16x32_bf16 v[52:55], v[162:165], v[196:199], v[52:55]
	v_mfma_f32_16x16x32_bf16 v[44:47], v[154:157], v[200:203], v[44:47]
	v_mfma_f32_16x16x32_bf16 v[36:39], v[162:165], v[200:203], v[36:39]
	v_mfma_f32_16x16x32_bf16 v[26:29], v[154:157], v[224:227], v[26:29]
	v_mfma_f32_16x16x32_bf16 v[18:21], v[162:165], v[224:227], v[18:21]
	v_mfma_f32_16x16x32_bf16 v[10:13], v[154:157], v[228:231], v[10:13]
	v_mfma_f32_16x16x32_bf16 v[6:9], v[162:165], v[228:231], v[6:9]
	s_setprio 0
	s_setprio 1
	v_mfma_f32_16x16x32_bf16 v[64:67], v[166:169], v[188:191], v[64:67]
	v_mfma_f32_16x16x32_bf16 v[56:59], v[174:177], v[188:191], v[56:59]
	v_mfma_f32_16x16x32_bf16 v[48:51], v[166:169], v[192:195], v[48:51]
	v_mfma_f32_16x16x32_bf16 v[40:43], v[174:177], v[192:195], v[40:43]
	v_mfma_f32_16x16x32_bf16 v[30:33], v[166:169], v[204:207], v[30:33]
	v_mfma_f32_16x16x32_bf16 v[22:25], v[174:177], v[204:207], v[22:25]
	v_mfma_f32_16x16x32_bf16 v[14:17], v[166:169], v[208:211], v[14:17]
	v_mfma_f32_16x16x32_bf16 v[2:5], v[174:177], v[208:211], v[2:5]
	v_mfma_f32_16x16x32_bf16 v[64:67], v[170:173], v[196:199], v[64:67]
	v_mfma_f32_16x16x32_bf16 v[56:59], v[184:187], v[196:199], v[56:59]
	v_mfma_f32_16x16x32_bf16 v[48:51], v[170:173], v[200:203], v[48:51]
	v_mfma_f32_16x16x32_bf16 v[40:43], v[184:187], v[200:203], v[40:43]
	v_mfma_f32_16x16x32_bf16 v[30:33], v[170:173], v[224:227], v[30:33]
	v_mfma_f32_16x16x32_bf16 v[22:25], v[184:187], v[224:227], v[22:25]
	v_mfma_f32_16x16x32_bf16 v[14:17], v[170:173], v[228:231], v[14:17]
	v_mfma_f32_16x16x32_bf16 v[2:5], v[184:187], v[228:231], v[2:5]
	s_setprio 0
	s_barrier
	s_add_i32 s30, s30, 2
	s_add_u32 s8, s8, 0x100
	s_addc_u32 s9, s9, 0
	s_add_u32 s24, s24, 0x100
	s_addc_u32 s25, s25, 0
	s_cmp_gt_u32 s30, 29
	s_cbranch_scc0 .LBB0_1114

.LBB0_1194:
	s_add_u32 s8, s8, 0x160080
	s_addc_u32 s9, s9, 0
	s_add_u32 s20, s18, 0x100
	s_addc_u32 s21, s19, 0
	s_mov_b32 s24, -2
	v_readlane_b32 s35, v255, 20
	v_readlane_b32 s40, v255, 21
	v_readlane_b32 s41, v255, 22
	v_readlane_b32 s57, v255, 23
	s_mov_b64 s[58:59], 0x80
	s_add_u32 s18, s8, 0xffea0080
	s_addc_u32 s19, s9, -1
	s_add_i32 s25, 0, 0x10000
	s_cmpk_eq_i32 s24, 0x54
	s_cselect_b32 s23, s45, s19
	s_cselect_b32 s22, s44, s18
	s_cselect_b32 s19, s47, s21
	s_cselect_b32 s18, s46, s20
	s_add_i32 s34, 0, 0x14000
	ds_read_b128 v[138:141], v1
	ds_read_b128 v[142:145], v160
	ds_read_b128 v[146:149], v1 offset:2048
	ds_read_b128 v[150:153], v160 offset:2048
	ds_read_b128 v[154:157], v1 offset:16384
	ds_read_b128 v[164:167], v160 offset:16384
	ds_read_b128 v[168:171], v1 offset:18432
	ds_read_b128 v[172:175], v160 offset:18432
	s_add_i32 m0, s29, 0xc000
	ds_read_b128 v[176:179], v161
	ds_read_b128 v[184:187], v161 offset:2048
	ds_read_b128 v[188:191], v162
	ds_read_b128 v[192:195], v162 offset:2048
	ds_read_b128 v[196:199], v161 offset:4096
	ds_read_b128 v[200:203], v161 offset:6144
	ds_read_b128 v[204:207], v162 offset:4096
	ds_read_b128 v[208:211], v162 offset:6144
	global_load_lds_dwordx4 v136, s[8:9]
	s_add_i32 m0, s29, 0xe000
	s_nop 0
	global_load_lds_dwordx4 v134, s[8:9]
	s_waitcnt vmcnt(8)
	s_waitcnt lgkmcnt(0)
	s_barrier
	s_setprio 1
	v_mfma_f32_16x16x32_bf16 v[128:131], v[138:141], v[176:179], 0
	v_mfma_f32_16x16x32_bf16 v[124:127], v[146:149], v[176:179], 0
	v_mfma_f32_16x16x32_bf16 v[112:115], v[138:141], v[184:187], 0
	v_mfma_f32_16x16x32_bf16 v[108:111], v[146:149], v[184:187], 0
	v_mfma_f32_16x16x32_bf16 v[96:99], v[138:141], v[196:199], 0
	v_mfma_f32_16x16x32_bf16 v[92:95], v[146:149], v[196:199], 0
	v_mfma_f32_16x16x32_bf16 v[80:83], v[138:141], v[200:203], 0
	v_mfma_f32_16x16x32_bf16 v[76:79], v[146:149], v[200:203], 0
	v_mfma_f32_16x16x32_bf16 v[128:131], v[142:145], v[188:191], v[128:131]
	v_mfma_f32_16x16x32_bf16 v[124:127], v[150:153], v[188:191], v[124:127]
	v_mfma_f32_16x16x32_bf16 v[112:115], v[142:145], v[192:195], v[112:115]
	v_mfma_f32_16x16x32_bf16 v[108:111], v[150:153], v[192:195], v[108:111]
	v_mfma_f32_16x16x32_bf16 v[96:99], v[142:145], v[204:207], v[96:99]
	v_mfma_f32_16x16x32_bf16 v[92:95], v[150:153], v[204:207], v[92:95]
	v_mfma_f32_16x16x32_bf16 v[80:83], v[142:145], v[208:211], v[80:83]
	v_mfma_f32_16x16x32_bf16 v[76:79], v[150:153], v[208:211], v[76:79]
	s_setprio 0
	s_setprio 1
	v_mfma_f32_16x16x32_bf16 v[120:123], v[154:157], v[176:179], 0
	v_mfma_f32_16x16x32_bf16 v[116:119], v[168:171], v[176:179], 0
	v_mfma_f32_16x16x32_bf16 v[104:107], v[154:157], v[184:187], 0
	v_mfma_f32_16x16x32_bf16 v[100:103], v[168:171], v[184:187], 0
	v_mfma_f32_16x16x32_bf16 v[88:91], v[154:157], v[196:199], 0
	v_mfma_f32_16x16x32_bf16 v[84:87], v[168:171], v[196:199], 0
	v_mfma_f32_16x16x32_bf16 v[72:75], v[154:157], v[200:203], 0
	v_mfma_f32_16x16x32_bf16 v[68:71], v[168:171], v[200:203], 0
	v_mfma_f32_16x16x32_bf16 v[120:123], v[164:167], v[188:191], v[120:123]
	v_mfma_f32_16x16x32_bf16 v[116:119], v[172:175], v[188:191], v[116:119]
	v_mfma_f32_16x16x32_bf16 v[104:107], v[164:167], v[192:195], v[104:107]
	v_mfma_f32_16x16x32_bf16 v[100:103], v[172:175], v[192:195], v[100:103]
	v_mfma_f32_16x16x32_bf16 v[88:91], v[164:167], v[204:207], v[88:91]
	v_mfma_f32_16x16x32_bf16 v[84:87], v[172:175], v[204:207], v[84:87]
	v_mfma_f32_16x16x32_bf16 v[72:75], v[164:167], v[208:211], v[72:75]
	v_mfma_f32_16x16x32_bf16 v[68:71], v[172:175], v[208:211], v[68:71]
	s_setprio 0
	s_barrier
	s_add_i32 s25, s25, s28
	s_mov_b32 m0, s25
	ds_read_b128 v[176:179], v161 offset:16384
	ds_read_b128 v[184:187], v161 offset:18432
	ds_read_b128 v[188:191], v162 offset:16384
	ds_read_b128 v[192:195], v162 offset:18432
	ds_read_b128 v[196:199], v161 offset:20480
	ds_read_b128 v[200:203], v161 offset:22528
	ds_read_b128 v[204:207], v162 offset:20480
	ds_read_b128 v[208:211], v162 offset:22528
	global_load_lds_dwordx4 v34, s[18:19]
	s_add_i32 m0, s25, 0x2000
	s_add_u32 s30, s18, 0x160000
	s_addc_u32 s31, s19, 0
	s_add_i32 s25, s34, s28
	global_load_lds_dwordx4 v132, s[18:19]
	s_mov_b32 m0, s25
	s_nop 0
	global_load_lds_dwordx4 v34, s[30:31]
	s_add_i32 m0, s25, 0x2000
	s_nop 0
	global_load_lds_dwordx4 v132, s[30:31]
	s_mov_b32 m0, s29
	s_nop 0
	global_load_lds_dwordx4 v136, s[22:23]
	s_mov_b32 m0, s33
	s_nop 0
	global_load_lds_dwordx4 v134, s[22:23]
	s_waitcnt vmcnt(8)
	s_waitcnt lgkmcnt(0)
	s_barrier
	s_setprio 1
	v_mfma_f32_16x16x32_bf16 v[64:67], v[138:141], v[176:179], 0
	v_mfma_f32_16x16x32_bf16 v[60:63], v[146:149], v[176:179], 0
	v_mfma_f32_16x16x32_bf16 v[48:51], v[138:141], v[184:187], 0
	v_mfma_f32_16x16x32_bf16 v[44:47], v[146:149], v[184:187], 0
	v_mfma_f32_16x16x32_bf16 v[30:33], v[138:141], v[196:199], 0
	v_mfma_f32_16x16x32_bf16 v[26:29], v[146:149], v[196:199], 0
	v_mfma_f32_16x16x32_bf16 v[14:17], v[138:141], v[200:203], 0
	v_mfma_f32_16x16x32_bf16 v[10:13], v[146:149], v[200:203], 0
	v_mfma_f32_16x16x32_bf16 v[64:67], v[142:145], v[188:191], v[64:67]
	v_mfma_f32_16x16x32_bf16 v[60:63], v[150:153], v[188:191], v[60:63]
	v_mfma_f32_16x16x32_bf16 v[48:51], v[142:145], v[192:195], v[48:51]
	v_mfma_f32_16x16x32_bf16 v[44:47], v[150:153], v[192:195], v[44:47]
	v_mfma_f32_16x16x32_bf16 v[30:33], v[142:145], v[204:207], v[30:33]
	v_mfma_f32_16x16x32_bf16 v[26:29], v[150:153], v[204:207], v[26:29]
	v_mfma_f32_16x16x32_bf16 v[14:17], v[142:145], v[208:211], v[14:17]
	v_mfma_f32_16x16x32_bf16 v[10:13], v[150:153], v[208:211], v[10:13]
	s_setprio 0
	s_setprio 1
	v_mfma_f32_16x16x32_bf16 v[56:59], v[154:157], v[176:179], 0
	v_mfma_f32_16x16x32_bf16 v[52:55], v[168:171], v[176:179], 0
	v_mfma_f32_16x16x32_bf16 v[40:43], v[154:157], v[184:187], 0
	v_mfma_f32_16x16x32_bf16 v[36:39], v[168:171], v[184:187], 0
	v_mfma_f32_16x16x32_bf16 v[22:25], v[154:157], v[196:199], 0
	v_mfma_f32_16x16x32_bf16 v[18:21], v[168:171], v[196:199], 0
	v_mfma_f32_16x16x32_bf16 v[6:9], v[154:157], v[200:203], 0
	v_mfma_f32_16x16x32_bf16 v[2:5], v[168:171], v[200:203], 0
	v_mfma_f32_16x16x32_bf16 v[56:59], v[164:167], v[188:191], v[56:59]
	v_mfma_f32_16x16x32_bf16 v[52:55], v[172:175], v[188:191], v[52:55]
	v_mfma_f32_16x16x32_bf16 v[40:43], v[164:167], v[192:195], v[40:43]
	v_mfma_f32_16x16x32_bf16 v[36:39], v[172:175], v[192:195], v[36:39]
	v_mfma_f32_16x16x32_bf16 v[22:25], v[164:167], v[204:207], v[22:25]
	v_mfma_f32_16x16x32_bf16 v[18:21], v[172:175], v[204:207], v[18:21]
	v_mfma_f32_16x16x32_bf16 v[6:9], v[164:167], v[208:211], v[6:9]
	v_mfma_f32_16x16x32_bf16 v[2:5], v[172:175], v[208:211], v[2:5]
	s_setprio 0
	s_barrier
	s_add_i32 s25, 0, 0x18000
	s_add_i32 s30, 0, 0x1c000
	ds_read_b128 v[138:141], v1 offset:32768
	ds_read_b128 v[142:145], v160 offset:32768
	ds_read_b128 v[146:149], v1 offset:34816
	ds_read_b128 v[150:153], v160 offset:34816
	ds_read_b128 v[154:157], v1 offset:49152
	ds_read_b128 v[164:167], v160 offset:49152
	ds_read_b128 v[168:171], v1 offset:51200
	ds_read_b128 v[172:175], v160 offset:51200
	s_mov_b64 s[100:101], s[22:23]
	s_add_u32 s22, s22, 0x160000
	s_addc_u32 s23, s23, 0
	s_mov_b32 m0, s48
	ds_read_b128 v[176:179], v161 offset:32768
	ds_read_b128 v[184:187], v161 offset:34816
	ds_read_b128 v[188:191], v162 offset:32768
	ds_read_b128 v[192:195], v162 offset:34816
	ds_read_b128 v[196:199], v161 offset:36864
	ds_read_b128 v[200:203], v161 offset:38912
	ds_read_b128 v[204:207], v162 offset:36864
	ds_read_b128 v[208:211], v162 offset:38912
	global_load_lds_dwordx4 v136, s[22:23]
	s_mov_b32 m0, s49
	s_nop 0
	global_load_lds_dwordx4 v134, s[22:23]
	s_waitcnt vmcnt(8)
	s_waitcnt lgkmcnt(0)
	s_barrier
	s_setprio 1
	v_mfma_f32_16x16x32_bf16 v[128:131], v[138:141], v[176:179], v[128:131]
	v_mfma_f32_16x16x32_bf16 v[124:127], v[146:149], v[176:179], v[124:127]
	v_mfma_f32_16x16x32_bf16 v[112:115], v[138:141], v[184:187], v[112:115]
	v_mfma_f32_16x16x32_bf16 v[108:111], v[146:149], v[184:187], v[108:111]
	v_mfma_f32_16x16x32_bf16 v[96:99], v[138:141], v[196:199], v[96:99]
	v_mfma_f32_16x16x32_bf16 v[92:95], v[146:149], v[196:199], v[92:95]
	v_mfma_f32_16x16x32_bf16 v[80:83], v[138:141], v[200:203], v[80:83]
	v_mfma_f32_16x16x32_bf16 v[76:79], v[146:149], v[200:203], v[76:79]
	v_mfma_f32_16x16x32_bf16 v[128:131], v[142:145], v[188:191], v[128:131]
	v_mfma_f32_16x16x32_bf16 v[124:127], v[150:153], v[188:191], v[124:127]
	v_mfma_f32_16x16x32_bf16 v[112:115], v[142:145], v[192:195], v[112:115]
	v_mfma_f32_16x16x32_bf16 v[108:111], v[150:153], v[192:195], v[108:111]
	v_mfma_f32_16x16x32_bf16 v[96:99], v[142:145], v[204:207], v[96:99]
	v_mfma_f32_16x16x32_bf16 v[92:95], v[150:153], v[204:207], v[92:95]
	v_mfma_f32_16x16x32_bf16 v[80:83], v[142:145], v[208:211], v[80:83]
	v_mfma_f32_16x16x32_bf16 v[76:79], v[150:153], v[208:211], v[76:79]
	s_setprio 0
	s_setprio 1
	v_mfma_f32_16x16x32_bf16 v[120:123], v[154:157], v[176:179], v[120:123]
	v_mfma_f32_16x16x32_bf16 v[116:119], v[168:171], v[176:179], v[116:119]
	v_mfma_f32_16x16x32_bf16 v[104:107], v[154:157], v[184:187], v[104:107]
	v_mfma_f32_16x16x32_bf16 v[100:103], v[168:171], v[184:187], v[100:103]
	v_mfma_f32_16x16x32_bf16 v[88:91], v[154:157], v[196:199], v[88:91]
	v_mfma_f32_16x16x32_bf16 v[84:87], v[168:171], v[196:199], v[84:87]
	v_mfma_f32_16x16x32_bf16 v[72:75], v[154:157], v[200:203], v[72:75]
	v_mfma_f32_16x16x32_bf16 v[68:71], v[168:171], v[200:203], v[68:71]
	v_mfma_f32_16x16x32_bf16 v[120:123], v[164:167], v[188:191], v[120:123]
	v_mfma_f32_16x16x32_bf16 v[116:119], v[172:175], v[188:191], v[116:119]
	v_mfma_f32_16x16x32_bf16 v[104:107], v[164:167], v[192:195], v[104:107]
	v_mfma_f32_16x16x32_bf16 v[100:103], v[172:175], v[192:195], v[100:103]
	v_mfma_f32_16x16x32_bf16 v[88:91], v[164:167], v[204:207], v[88:91]
	v_mfma_f32_16x16x32_bf16 v[84:87], v[172:175], v[204:207], v[84:87]
	v_mfma_f32_16x16x32_bf16 v[72:75], v[164:167], v[208:211], v[72:75]
	v_mfma_f32_16x16x32_bf16 v[68:71], v[172:175], v[208:211], v[68:71]
	s_setprio 0
	s_barrier
	s_add_i32 s22, s25, s28
	s_add_i32 m0, s22, 0xffffff80
	ds_read_b128 v[176:179], v161 offset:49152
	ds_read_b128 v[184:187], v161 offset:51200
	ds_read_b128 v[188:191], v162 offset:49152
	ds_read_b128 v[192:195], v162 offset:51200
	ds_read_b128 v[196:199], v161 offset:53248
	ds_read_b128 v[200:203], v161 offset:55296
	ds_read_b128 v[204:207], v162 offset:53248
	ds_read_b128 v[208:211], v162 offset:55296
	global_load_lds_dwordx4 v34, s[18:19] offset:128
	s_add_i32 m0, s22, 0x1f80
	s_mov_b64 s[98:99], s[18:19]
	s_add_u32 s18, s18, 0x160080
	s_addc_u32 s19, s19, 0
	s_add_i32 s22, s30, s28
	global_load_lds_dwordx4 v132, s[98:99] offset:128
	s_mov_b32 m0, s22
	s_nop 0
	global_load_lds_dwordx4 v34, s[18:19]
	s_add_i32 m0, s22, 0x2000
	s_nop 0
	global_load_lds_dwordx4 v132, s[18:19]
	s_add_i32 m0, s53, 0xffffff80
	s_nop 0
	global_load_lds_dwordx4 v136, s[100:101] offset:128
	s_add_i32 m0, s54, 0xffffff80
	s_nop 0
	global_load_lds_dwordx4 v134, s[100:101] offset:128
	s_waitcnt vmcnt(8)
	s_waitcnt lgkmcnt(0)
	s_barrier
	s_setprio 1
	v_mfma_f32_16x16x32_bf16 v[64:67], v[138:141], v[176:179], v[64:67]
	v_mfma_f32_16x16x32_bf16 v[60:63], v[146:149], v[176:179], v[60:63]
	v_mfma_f32_16x16x32_bf16 v[48:51], v[138:141], v[184:187], v[48:51]
	v_mfma_f32_16x16x32_bf16 v[44:47], v[146:149], v[184:187], v[44:47]
	v_mfma_f32_16x16x32_bf16 v[30:33], v[138:141], v[196:199], v[30:33]
	v_mfma_f32_16x16x32_bf16 v[26:29], v[146:149], v[196:199], v[26:29]
	v_mfma_f32_16x16x32_bf16 v[14:17], v[138:141], v[200:203], v[14:17]
	v_mfma_f32_16x16x32_bf16 v[10:13], v[146:149], v[200:203], v[10:13]
	v_mfma_f32_16x16x32_bf16 v[64:67], v[142:145], v[188:191], v[64:67]
	v_mfma_f32_16x16x32_bf16 v[60:63], v[150:153], v[188:191], v[60:63]
	v_mfma_f32_16x16x32_bf16 v[48:51], v[142:145], v[192:195], v[48:51]
	v_mfma_f32_16x16x32_bf16 v[44:47], v[150:153], v[192:195], v[44:47]
	v_mfma_f32_16x16x32_bf16 v[30:33], v[142:145], v[204:207], v[30:33]
	v_mfma_f32_16x16x32_bf16 v[26:29], v[150:153], v[204:207], v[26:29]
	v_mfma_f32_16x16x32_bf16 v[14:17], v[142:145], v[208:211], v[14:17]
	v_mfma_f32_16x16x32_bf16 v[10:13], v[150:153], v[208:211], v[10:13]
	s_setprio 0
	s_setprio 1
	v_mfma_f32_16x16x32_bf16 v[56:59], v[154:157], v[176:179], v[56:59]
	v_mfma_f32_16x16x32_bf16 v[52:55], v[168:171], v[176:179], v[52:55]
	v_mfma_f32_16x16x32_bf16 v[40:43], v[154:157], v[184:187], v[40:43]
	v_mfma_f32_16x16x32_bf16 v[36:39], v[168:171], v[184:187], v[36:39]
	v_mfma_f32_16x16x32_bf16 v[22:25], v[154:157], v[196:199], v[22:25]
	v_mfma_f32_16x16x32_bf16 v[18:21], v[168:171], v[196:199], v[18:21]
	v_mfma_f32_16x16x32_bf16 v[6:9], v[154:157], v[200:203], v[6:9]
	v_mfma_f32_16x16x32_bf16 v[2:5], v[168:171], v[200:203], v[2:5]
	v_mfma_f32_16x16x32_bf16 v[56:59], v[164:167], v[188:191], v[56:59]
	v_mfma_f32_16x16x32_bf16 v[52:55], v[172:175], v[188:191], v[52:55]
	v_mfma_f32_16x16x32_bf16 v[40:43], v[164:167], v[192:195], v[40:43]
	v_mfma_f32_16x16x32_bf16 v[36:39], v[172:175], v[192:195], v[36:39]
	v_mfma_f32_16x16x32_bf16 v[22:25], v[164:167], v[204:207], v[22:25]
	v_mfma_f32_16x16x32_bf16 v[18:21], v[172:175], v[204:207], v[18:21]
	v_mfma_f32_16x16x32_bf16 v[6:9], v[164:167], v[208:211], v[6:9]
	v_mfma_f32_16x16x32_bf16 v[2:5], v[172:175], v[208:211], v[2:5]
	s_setprio 0
	s_barrier
	s_add_i32 s24, s24, 2
	s_add_u32 s8, s8, 0x100
	s_addc_u32 s9, s9, 0
	s_add_u32 s20, s20, 0x100
	s_addc_u32 s21, s21, 0
	s_cmpk_gt_u32 s24, 0x55
	s_cbranch_scc1 .Lpeel_done_P7
.LBB0_1195:
	s_add_u32 s18, s8, 0xffea0080
	s_addc_u32 s19, s9, -1
	s_add_i32 s25, 0, 0x10000
	s_cmpk_eq_i32 s24, 0x54
	s_cselect_b32 s23, s45, s19
	s_cselect_b32 s22, s44, s18
	s_cselect_b32 s19, s47, s21
	s_cselect_b32 s18, s46, s20
	s_add_i32 s34, 0, 0x14000
	ds_read_b128 v[138:141], v1
	ds_read_b128 v[142:145], v160
	ds_read_b128 v[146:149], v1 offset:2048
	ds_read_b128 v[150:153], v160 offset:2048
	ds_read_b128 v[154:157], v1 offset:16384
	ds_read_b128 v[164:167], v160 offset:16384
	ds_read_b128 v[168:171], v1 offset:18432
	ds_read_b128 v[172:175], v160 offset:18432
	s_add_i32 m0, s29, 0xc000
	ds_read_b128 v[176:179], v161
	ds_read_b128 v[184:187], v161 offset:2048
	ds_read_b128 v[188:191], v162
	ds_read_b128 v[192:195], v162 offset:2048
	ds_read_b128 v[196:199], v161 offset:4096
	ds_read_b128 v[200:203], v161 offset:6144
	ds_read_b128 v[204:207], v162 offset:4096
	ds_read_b128 v[208:211], v162 offset:6144
	global_load_lds_dwordx4 v136, s[8:9]
	s_add_i32 m0, s29, 0xe000
	s_nop 0
	global_load_lds_dwordx4 v134, s[8:9]
	s_waitcnt vmcnt(8)
	s_waitcnt lgkmcnt(0)
	s_barrier
	s_setprio 1
	v_mfma_f32_16x16x32_bf16 v[128:131], v[138:141], v[176:179], v[128:131]
	v_mfma_f32_16x16x32_bf16 v[124:127], v[146:149], v[176:179], v[124:127]
	v_mfma_f32_16x16x32_bf16 v[112:115], v[138:141], v[184:187], v[112:115]
	v_mfma_f32_16x16x32_bf16 v[108:111], v[146:149], v[184:187], v[108:111]
	v_mfma_f32_16x16x32_bf16 v[96:99], v[138:141], v[196:199], v[96:99]
	v_mfma_f32_16x16x32_bf16 v[92:95], v[146:149], v[196:199], v[92:95]
	v_mfma_f32_16x16x32_bf16 v[80:83], v[138:141], v[200:203], v[80:83]
	v_mfma_f32_16x16x32_bf16 v[76:79], v[146:149], v[200:203], v[76:79]
	v_mfma_f32_16x16x32_bf16 v[128:131], v[142:145], v[188:191], v[128:131]
	v_mfma_f32_16x16x32_bf16 v[124:127], v[150:153], v[188:191], v[124:127]
	v_mfma_f32_16x16x32_bf16 v[112:115], v[142:145], v[192:195], v[112:115]
	v_mfma_f32_16x16x32_bf16 v[108:111], v[150:153], v[192:195], v[108:111]
	v_mfma_f32_16x16x32_bf16 v[96:99], v[142:145], v[204:207], v[96:99]
	v_mfma_f32_16x16x32_bf16 v[92:95], v[150:153], v[204:207], v[92:95]
	v_mfma_f32_16x16x32_bf16 v[80:83], v[142:145], v[208:211], v[80:83]
	v_mfma_f32_16x16x32_bf16 v[76:79], v[150:153], v[208:211], v[76:79]
	s_setprio 0
	s_setprio 1
	v_mfma_f32_16x16x32_bf16 v[120:123], v[154:157], v[176:179], v[120:123]
	v_mfma_f32_16x16x32_bf16 v[116:119], v[168:171], v[176:179], v[116:119]
	v_mfma_f32_16x16x32_bf16 v[104:107], v[154:157], v[184:187], v[104:107]
	v_mfma_f32_16x16x32_bf16 v[100:103], v[168:171], v[184:187], v[100:103]
	v_mfma_f32_16x16x32_bf16 v[88:91], v[154:157], v[196:199], v[88:91]
	v_mfma_f32_16x16x32_bf16 v[84:87], v[168:171], v[196:199], v[84:87]
	v_mfma_f32_16x16x32_bf16 v[72:75], v[154:157], v[200:203], v[72:75]
	v_mfma_f32_16x16x32_bf16 v[68:71], v[168:171], v[200:203], v[68:71]
	v_mfma_f32_16x16x32_bf16 v[120:123], v[164:167], v[188:191], v[120:123]
	v_mfma_f32_16x16x32_bf16 v[116:119], v[172:175], v[188:191], v[116:119]
	v_mfma_f32_16x16x32_bf16 v[104:107], v[164:167], v[192:195], v[104:107]
	v_mfma_f32_16x16x32_bf16 v[100:103], v[172:175], v[192:195], v[100:103]
	v_mfma_f32_16x16x32_bf16 v[88:91], v[164:167], v[204:207], v[88:91]
	v_mfma_f32_16x16x32_bf16 v[84:87], v[172:175], v[204:207], v[84:87]
	v_mfma_f32_16x16x32_bf16 v[72:75], v[164:167], v[208:211], v[72:75]
	v_mfma_f32_16x16x32_bf16 v[68:71], v[172:175], v[208:211], v[68:71]
	s_setprio 0
	s_barrier
	s_add_i32 s25, s25, s28
	s_mov_b32 m0, s25
	ds_read_b128 v[176:179], v161 offset:16384
	ds_read_b128 v[184:187], v161 offset:18432
	ds_read_b128 v[188:191], v162 offset:16384
	ds_read_b128 v[192:195], v162 offset:18432
	ds_read_b128 v[196:199], v161 offset:20480
	ds_read_b128 v[200:203], v161 offset:22528
	ds_read_b128 v[204:207], v162 offset:20480
	ds_read_b128 v[208:211], v162 offset:22528
	global_load_lds_dwordx4 v34, s[18:19]
	s_add_i32 m0, s25, 0x2000
	s_add_u32 s30, s18, 0x160000
	s_addc_u32 s31, s19, 0
	s_add_i32 s25, s34, s28
	global_load_lds_dwordx4 v132, s[18:19]
	s_mov_b32 m0, s25
	s_nop 0
	global_load_lds_dwordx4 v34, s[30:31]
	s_add_i32 m0, s25, 0x2000
	s_nop 0
	global_load_lds_dwordx4 v132, s[30:31]
	s_mov_b32 m0, s29
	s_nop 0
	global_load_lds_dwordx4 v136, s[22:23]
	s_mov_b32 m0, s33
	s_nop 0
	global_load_lds_dwordx4 v134, s[22:23]
	s_waitcnt vmcnt(8)
	s_waitcnt lgkmcnt(0)
	s_barrier
	s_setprio 1
	v_mfma_f32_16x16x32_bf16 v[64:67], v[138:141], v[176:179], v[64:67]
	v_mfma_f32_16x16x32_bf16 v[60:63], v[146:149], v[176:179], v[60:63]
	v_mfma_f32_16x16x32_bf16 v[48:51], v[138:141], v[184:187], v[48:51]
	v_mfma_f32_16x16x32_bf16 v[44:47], v[146:149], v[184:187], v[44:47]
	v_mfma_f32_16x16x32_bf16 v[30:33], v[138:141], v[196:199], v[30:33]
	v_mfma_f32_16x16x32_bf16 v[26:29], v[146:149], v[196:199], v[26:29]
	v_mfma_f32_16x16x32_bf16 v[14:17], v[138:141], v[200:203], v[14:17]
	v_mfma_f32_16x16x32_bf16 v[10:13], v[146:149], v[200:203], v[10:13]
	v_mfma_f32_16x16x32_bf16 v[64:67], v[142:145], v[188:191], v[64:67]
	v_mfma_f32_16x16x32_bf16 v[60:63], v[150:153], v[188:191], v[60:63]
	v_mfma_f32_16x16x32_bf16 v[48:51], v[142:145], v[192:195], v[48:51]
	v_mfma_f32_16x16x32_bf16 v[44:47], v[150:153], v[192:195], v[44:47]
	v_mfma_f32_16x16x32_bf16 v[30:33], v[142:145], v[204:207], v[30:33]
	v_mfma_f32_16x16x32_bf16 v[26:29], v[150:153], v[204:207], v[26:29]
	v_mfma_f32_16x16x32_bf16 v[14:17], v[142:145], v[208:211], v[14:17]
	v_mfma_f32_16x16x32_bf16 v[10:13], v[150:153], v[208:211], v[10:13]
	s_setprio 0
	s_setprio 1
	v_mfma_f32_16x16x32_bf16 v[56:59], v[154:157], v[176:179], v[56:59]
	v_mfma_f32_16x16x32_bf16 v[52:55], v[168:171], v[176:179], v[52:55]
	v_mfma_f32_16x16x32_bf16 v[40:43], v[154:157], v[184:187], v[40:43]
	v_mfma_f32_16x16x32_bf16 v[36:39], v[168:171], v[184:187], v[36:39]
	v_mfma_f32_16x16x32_bf16 v[22:25], v[154:157], v[196:199], v[22:25]
	v_mfma_f32_16x16x32_bf16 v[18:21], v[168:171], v[196:199], v[18:21]
	v_mfma_f32_16x16x32_bf16 v[6:9], v[154:157], v[200:203], v[6:9]
	v_mfma_f32_16x16x32_bf16 v[2:5], v[168:171], v[200:203], v[2:5]
	v_mfma_f32_16x16x32_bf16 v[56:59], v[164:167], v[188:191], v[56:59]
	v_mfma_f32_16x16x32_bf16 v[52:55], v[172:175], v[188:191], v[52:55]
	v_mfma_f32_16x16x32_bf16 v[40:43], v[164:167], v[192:195], v[40:43]
	v_mfma_f32_16x16x32_bf16 v[36:39], v[172:175], v[192:195], v[36:39]
	v_mfma_f32_16x16x32_bf16 v[22:25], v[164:167], v[204:207], v[22:25]
	v_mfma_f32_16x16x32_bf16 v[18:21], v[172:175], v[204:207], v[18:21]
	v_mfma_f32_16x16x32_bf16 v[6:9], v[164:167], v[208:211], v[6:9]
	v_mfma_f32_16x16x32_bf16 v[2:5], v[172:175], v[208:211], v[2:5]
	s_setprio 0
	s_barrier
	s_add_i32 s25, 0, 0x18000
	s_add_i32 s30, 0, 0x1c000
	ds_read_b128 v[138:141], v1 offset:32768
	ds_read_b128 v[142:145], v160 offset:32768
	ds_read_b128 v[146:149], v1 offset:34816
	ds_read_b128 v[150:153], v160 offset:34816
	ds_read_b128 v[154:157], v1 offset:49152
	ds_read_b128 v[164:167], v160 offset:49152
	ds_read_b128 v[168:171], v1 offset:51200
	ds_read_b128 v[172:175], v160 offset:51200
	s_mov_b64 s[100:101], s[22:23]
	s_add_u32 s22, s22, 0x160000
	s_addc_u32 s23, s23, 0
	s_mov_b32 m0, s48
	ds_read_b128 v[176:179], v161 offset:32768
	ds_read_b128 v[184:187], v161 offset:34816
	ds_read_b128 v[188:191], v162 offset:32768
	ds_read_b128 v[192:195], v162 offset:34816
	ds_read_b128 v[196:199], v161 offset:36864
	ds_read_b128 v[200:203], v161 offset:38912
	ds_read_b128 v[204:207], v162 offset:36864
	ds_read_b128 v[208:211], v162 offset:38912
	global_load_lds_dwordx4 v136, s[22:23]
	s_mov_b32 m0, s49
	s_nop 0
	global_load_lds_dwordx4 v134, s[22:23]
	s_waitcnt vmcnt(8)
	s_waitcnt lgkmcnt(0)
	s_barrier
	s_setprio 1
	v_mfma_f32_16x16x32_bf16 v[128:131], v[138:141], v[176:179], v[128:131]
	v_mfma_f32_16x16x32_bf16 v[124:127], v[146:149], v[176:179], v[124:127]
	v_mfma_f32_16x16x32_bf16 v[112:115], v[138:141], v[184:187], v[112:115]
	v_mfma_f32_16x16x32_bf16 v[108:111], v[146:149], v[184:187], v[108:111]
	v_mfma_f32_16x16x32_bf16 v[96:99], v[138:141], v[196:199], v[96:99]
	v_mfma_f32_16x16x32_bf16 v[92:95], v[146:149], v[196:199], v[92:95]
	v_mfma_f32_16x16x32_bf16 v[80:83], v[138:141], v[200:203], v[80:83]
	v_mfma_f32_16x16x32_bf16 v[76:79], v[146:149], v[200:203], v[76:79]
	v_mfma_f32_16x16x32_bf16 v[128:131], v[142:145], v[188:191], v[128:131]
	v_mfma_f32_16x16x32_bf16 v[124:127], v[150:153], v[188:191], v[124:127]
	v_mfma_f32_16x16x32_bf16 v[112:115], v[142:145], v[192:195], v[112:115]
	v_mfma_f32_16x16x32_bf16 v[108:111], v[150:153], v[192:195], v[108:111]
	v_mfma_f32_16x16x32_bf16 v[96:99], v[142:145], v[204:207], v[96:99]
	v_mfma_f32_16x16x32_bf16 v[92:95], v[150:153], v[204:207], v[92:95]
	v_mfma_f32_16x16x32_bf16 v[80:83], v[142:145], v[208:211], v[80:83]
	v_mfma_f32_16x16x32_bf16 v[76:79], v[150:153], v[208:211], v[76:79]
	s_setprio 0
	s_setprio 1
	v_mfma_f32_16x16x32_bf16 v[120:123], v[154:157], v[176:179], v[120:123]
	v_mfma_f32_16x16x32_bf16 v[116:119], v[168:171], v[176:179], v[116:119]
	v_mfma_f32_16x16x32_bf16 v[104:107], v[154:157], v[184:187], v[104:107]
	v_mfma_f32_16x16x32_bf16 v[100:103], v[168:171], v[184:187], v[100:103]
	v_mfma_f32_16x16x32_bf16 v[88:91], v[154:157], v[196:199], v[88:91]
	v_mfma_f32_16x16x32_bf16 v[84:87], v[168:171], v[196:199], v[84:87]
	v_mfma_f32_16x16x32_bf16 v[72:75], v[154:157], v[200:203], v[72:75]
	v_mfma_f32_16x16x32_bf16 v[68:71], v[168:171], v[200:203], v[68:71]
	v_mfma_f32_16x16x32_bf16 v[120:123], v[164:167], v[188:191], v[120:123]
	v_mfma_f32_16x16x32_bf16 v[116:119], v[172:175], v[188:191], v[116:119]
	v_mfma_f32_16x16x32_bf16 v[104:107], v[164:167], v[192:195], v[104:107]
	v_mfma_f32_16x16x32_bf16 v[100:103], v[172:175], v[192:195], v[100:103]
	v_mfma_f32_16x16x32_bf16 v[88:91], v[164:167], v[204:207], v[88:91]
	v_mfma_f32_16x16x32_bf16 v[84:87], v[172:175], v[204:207], v[84:87]
	v_mfma_f32_16x16x32_bf16 v[72:75], v[164:167], v[208:211], v[72:75]
	v_mfma_f32_16x16x32_bf16 v[68:71], v[172:175], v[208:211], v[68:71]
	s_setprio 0
	s_barrier
	s_add_i32 s22, s25, s28
	s_add_i32 m0, s22, 0xffffff80
	ds_read_b128 v[176:179], v161 offset:49152
	ds_read_b128 v[184:187], v161 offset:51200
	ds_read_b128 v[188:191], v162 offset:49152
	ds_read_b128 v[192:195], v162 offset:51200
	ds_read_b128 v[196:199], v161 offset:53248
	ds_read_b128 v[200:203], v161 offset:55296
	ds_read_b128 v[204:207], v162 offset:53248
	ds_read_b128 v[208:211], v162 offset:55296
	global_load_lds_dwordx4 v34, s[18:19] offset:128
	s_add_i32 m0, s22, 0x1f80
	s_mov_b64 s[98:99], s[18:19]
	s_add_u32 s18, s18, 0x160080
	s_addc_u32 s19, s19, 0
	s_add_i32 s22, s30, s28
	global_load_lds_dwordx4 v132, s[98:99] offset:128
	s_mov_b32 m0, s22
	s_nop 0
	global_load_lds_dwordx4 v34, s[18:19]
	s_add_i32 m0, s22, 0x2000
	s_nop 0
	global_load_lds_dwordx4 v132, s[18:19]
	s_add_i32 m0, s53, 0xffffff80
	s_nop 0
	global_load_lds_dwordx4 v136, s[100:101] offset:128
	s_add_i32 m0, s54, 0xffffff80
	s_nop 0
	global_load_lds_dwordx4 v134, s[100:101] offset:128
	s_waitcnt vmcnt(8)
	s_waitcnt lgkmcnt(0)
	s_barrier
	s_setprio 1
	v_mfma_f32_16x16x32_bf16 v[64:67], v[138:141], v[176:179], v[64:67]
	v_mfma_f32_16x16x32_bf16 v[60:63], v[146:149], v[176:179], v[60:63]
	v_mfma_f32_16x16x32_bf16 v[48:51], v[138:141], v[184:187], v[48:51]
	v_mfma_f32_16x16x32_bf16 v[44:47], v[146:149], v[184:187], v[44:47]
	v_mfma_f32_16x16x32_bf16 v[30:33], v[138:141], v[196:199], v[30:33]
	v_mfma_f32_16x16x32_bf16 v[26:29], v[146:149], v[196:199], v[26:29]
	v_mfma_f32_16x16x32_bf16 v[14:17], v[138:141], v[200:203], v[14:17]
	v_mfma_f32_16x16x32_bf16 v[10:13], v[146:149], v[200:203], v[10:13]
	v_mfma_f32_16x16x32_bf16 v[64:67], v[142:145], v[188:191], v[64:67]
	v_mfma_f32_16x16x32_bf16 v[60:63], v[150:153], v[188:191], v[60:63]
	v_mfma_f32_16x16x32_bf16 v[48:51], v[142:145], v[192:195], v[48:51]
	v_mfma_f32_16x16x32_bf16 v[44:47], v[150:153], v[192:195], v[44:47]
	v_mfma_f32_16x16x32_bf16 v[30:33], v[142:145], v[204:207], v[30:33]
	v_mfma_f32_16x16x32_bf16 v[26:29], v[150:153], v[204:207], v[26:29]
	v_mfma_f32_16x16x32_bf16 v[14:17], v[142:145], v[208:211], v[14:17]
	v_mfma_f32_16x16x32_bf16 v[10:13], v[150:153], v[208:211], v[10:13]
	s_setprio 0
	s_setprio 1
	v_mfma_f32_16x16x32_bf16 v[56:59], v[154:157], v[176:179], v[56:59]
	v_mfma_f32_16x16x32_bf16 v[52:55], v[168:171], v[176:179], v[52:55]
	v_mfma_f32_16x16x32_bf16 v[40:43], v[154:157], v[184:187], v[40:43]
	v_mfma_f32_16x16x32_bf16 v[36:39], v[168:171], v[184:187], v[36:39]
	v_mfma_f32_16x16x32_bf16 v[22:25], v[154:157], v[196:199], v[22:25]
	v_mfma_f32_16x16x32_bf16 v[18:21], v[168:171], v[196:199], v[18:21]
	v_mfma_f32_16x16x32_bf16 v[6:9], v[154:157], v[200:203], v[6:9]
	v_mfma_f32_16x16x32_bf16 v[2:5], v[168:171], v[200:203], v[2:5]
	v_mfma_f32_16x16x32_bf16 v[56:59], v[164:167], v[188:191], v[56:59]
	v_mfma_f32_16x16x32_bf16 v[52:55], v[172:175], v[188:191], v[52:55]
	v_mfma_f32_16x16x32_bf16 v[40:43], v[164:167], v[192:195], v[40:43]
	v_mfma_f32_16x16x32_bf16 v[36:39], v[172:175], v[192:195], v[36:39]
	v_mfma_f32_16x16x32_bf16 v[22:25], v[164:167], v[204:207], v[22:25]
	v_mfma_f32_16x16x32_bf16 v[18:21], v[172:175], v[204:207], v[18:21]
	v_mfma_f32_16x16x32_bf16 v[6:9], v[164:167], v[208:211], v[6:9]
	v_mfma_f32_16x16x32_bf16 v[2:5], v[172:175], v[208:211], v[2:5]
	s_setprio 0
	s_barrier
	s_add_i32 s24, s24, 2
	s_add_u32 s8, s8, 0x100
	s_addc_u32 s9, s9, 0
	s_add_u32 s20, s20, 0x100
	s_addc_u32 s21, s21, 0
	s_cmpk_gt_u32 s24, 0x55
	s_cbranch_scc0 .LBB0_1195
